# ALIGN barrier of the leading half moved down into the epilogues (after first LDS/stores or residual loads) so its store stream starts under the trailing half's last MFMA block
# baseline (speedup 1.0000x reference)
; #define PG8_STAGE(bufoff, gbase, voff) do { _Pragma("unroll") for (int _i = 0; _i < 2; ++_i) \
;         __builtin_amdgcn_global_load_lds((const unsigned*)((const char*)(gbase) + (voff)[_i]), (PG8_LAS unsigned*)(lds + (bufoff) + ldsw + _i * 8192), 16, 0, 0); } while (0)
; #define PG8_LDA(dst, b, h) do { _Pragma("unroll") for (int m = 0; m < 4; ++m) _Pragma("unroll") for (int k = 0; k < 2; ++k) dst[m][k] = *(const PG8_LAS bf16x8*)(lds + PG8_SA(b, h) + aoff + m * 2048 + k * 1024); } while (0)
; #define PG8_LDB(dst, b, h) do { _Pragma("unroll") for (int n = 0; n < 2; ++n) _Pragma("unroll") for (int k = 0; k < 2; ++k) dst[n][k] = *(const PG8_LAS bf16x8*)(lds + PG8_SB(b, h) + boff + n * 2048 + k * 1024); } while (0)
; #define PG8_MMA(ai, bj, At, Bt) do { __builtin_amdgcn_s_setprio(1); _Pragma("unroll") for (int m = 0; m < 4; ++m) _Pragma("unroll") for (int n = 0; n < 2; ++n) _Pragma("unroll") for (int k = 0; k < 2; ++k) \
;         acc[ai][bj][m][n] = __builtin_amdgcn_mfma_f32_16x16x32_bf16(Bt[n][k], At[m][k], acc[ai][bj][m][n], 0, 0, 0); __builtin_amdgcn_s_setprio(0); } while (0)
; #define PG8_WAIT_V(n) asm volatile("s_waitcnt vmcnt(" #n ")" ::: "memory")
; #define PG8_WAIT_L(n) asm volatile("s_waitcnt lgkmcnt(" #n ")" ::: "memory")
; #define PG8_BAR __builtin_amdgcn_s_barrier()
; #define PG8_SCHED __builtin_amdgcn_sched_barrier(0)
; template <class Epi, class Sched, bool ALIGN_EPI = false, bool SP2 = false>
; __device__ __forceinline__ void gemm_phase(PG8_LAS unsigned char* lds, const Gemm g, const Sched& S, const Epi& E, const int wave_s) {
;     ...
;             if constexpr (SP2) {
;             PG8_LDB(B0, 0, 0); PG8_LDB(B1, 0, 1); PG8_SCHED; PG8_LDA(At, 0, 0); PG8_STAGE(PG8_SA(1, 1), a1 + hstep, voffA);
;             PG8_WAIT_V(8); PG8_WAIT_L(0); PG8_BAR; PG8_MMA(0, 0, At, B0); PG8_MMA(0, 1, At, B1); PG8_BAR; PG8_SCHED;
;             PG8_LDA(At, 0, 1); PG8_STAGE(PG8_SB(0, 0), b2, voffB); PG8_STAGE(PG8_SB(0, 1), b2 + bhstep, voffB); PG8_STAGE(PG8_SA(0, 0), a2, voffA);
;             PG8_WAIT_V(8); PG8_WAIT_L(0); PG8_BAR; PG8_MMA(1, 0, At, B0); PG8_MMA(1, 1, At, B1); PG8_BAR; PG8_SCHED;
.LBB0_136:
	s_add_u32 s42, s20, 0xfffc0080
	s_addc_u32 s43, s21, -1
	s_add_i32 s71, 0, 0x10000
	s_cmp_eq_u32 s70, 12
	s_cselect_b32 s45, s65, s43
	s_cselect_b32 s44, s66, s42
	v_add_u32_e32 v0, s71, v171
	s_cselect_b32 s43, s53, s69
	s_cselect_b32 s42, s67, s68
	s_add_i32 s74, 0, 0x14000
	ds_read_b128 v[146:149], v0
	ds_read_b128 v[150:153], v0 offset:1024
	ds_read_b128 v[154:157], v0 offset:2048
	ds_read_b128 v[158:161], v0 offset:3072
	v_add_u32_e32 v0, s74, v171
	ds_read_b128 v[162:165], v0
	ds_read_b128 v[166:169], v0 offset:1024
	s_nop 0
	ds_read_b128 v[182:185], v0 offset:2048
	ds_read_b128 v[186:189], v0 offset:3072
	v_lshl_add_u64 v[224:225], s[20:21], 0, v[142:143]
	s_add_i32 m0, s7, 0xc000
	ds_read_b128 v[190:193], v177
	ds_read_b128 v[194:197], v177 offset:1024
	ds_read_b128 v[198:201], v177 offset:2048
	ds_read_b128 v[204:207], v177 offset:3072
	ds_read_b128 v[208:211], v177 offset:4096
	ds_read_b128 v[212:215], v177 offset:5120
	ds_read_b128 v[216:219], v177 offset:6144
	ds_read_b128 v[220:223], v177 offset:7168
	global_load_lds_dwordx4 v[224:225], off
	v_lshl_add_u64 v[224:225], s[20:21], 0, v[144:145]
	s_add_i32 m0, s7, 0xe000
	s_nop 0
	global_load_lds_dwordx4 v[224:225], off
	s_waitcnt vmcnt(8)
	s_waitcnt lgkmcnt(0)
	s_barrier
	s_setprio 1
	s_waitcnt lgkmcnt(0)
	v_mfma_f32_16x16x32_bf16 v[126:129], v[146:149], v[190:193], v[126:129]
	v_mfma_f32_16x16x32_bf16 v[126:129], v[150:153], v[194:197], v[126:129]
	v_mfma_f32_16x16x32_bf16 v[122:125], v[154:157], v[190:193], v[122:125]
	v_mfma_f32_16x16x32_bf16 v[122:125], v[158:161], v[194:197], v[122:125]
	v_mfma_f32_16x16x32_bf16 v[110:113], v[146:149], v[198:201], v[110:113]
	v_mfma_f32_16x16x32_bf16 v[110:113], v[150:153], v[204:207], v[110:113]
	v_mfma_f32_16x16x32_bf16 v[106:109], v[154:157], v[198:201], v[106:109]
	v_mfma_f32_16x16x32_bf16 v[106:109], v[158:161], v[204:207], v[106:109]
	v_mfma_f32_16x16x32_bf16 v[94:97], v[146:149], v[208:211], v[94:97]
	v_mfma_f32_16x16x32_bf16 v[94:97], v[150:153], v[212:215], v[94:97]
	v_mfma_f32_16x16x32_bf16 v[90:93], v[154:157], v[208:211], v[90:93]
	v_mfma_f32_16x16x32_bf16 v[90:93], v[158:161], v[212:215], v[90:93]
	v_mfma_f32_16x16x32_bf16 v[78:81], v[146:149], v[216:219], v[78:81]
	v_mfma_f32_16x16x32_bf16 v[78:81], v[150:153], v[220:223], v[78:81]
	v_mfma_f32_16x16x32_bf16 v[74:77], v[154:157], v[216:219], v[74:77]
	v_mfma_f32_16x16x32_bf16 v[74:77], v[158:161], v[220:223], v[74:77]
	s_setprio 0
	s_setprio 1
	v_mfma_f32_16x16x32_bf16 v[118:121], v[162:165], v[190:193], v[118:121]
	v_mfma_f32_16x16x32_bf16 v[118:121], v[166:169], v[194:197], v[118:121]
	v_mfma_f32_16x16x32_bf16 v[114:117], v[182:185], v[190:193], v[114:117]
	v_mfma_f32_16x16x32_bf16 v[114:117], v[186:189], v[194:197], v[114:117]
	v_mfma_f32_16x16x32_bf16 v[102:105], v[162:165], v[198:201], v[102:105]
	v_mfma_f32_16x16x32_bf16 v[102:105], v[166:169], v[204:207], v[102:105]
	v_mfma_f32_16x16x32_bf16 v[98:101], v[182:185], v[198:201], v[98:101]
	v_mfma_f32_16x16x32_bf16 v[98:101], v[186:189], v[204:207], v[98:101]
	v_mfma_f32_16x16x32_bf16 v[86:89], v[162:165], v[208:211], v[86:89]
	v_mfma_f32_16x16x32_bf16 v[86:89], v[166:169], v[212:215], v[86:89]
	v_mfma_f32_16x16x32_bf16 v[82:85], v[182:185], v[208:211], v[82:85]
	v_mfma_f32_16x16x32_bf16 v[82:85], v[186:189], v[212:215], v[82:85]
	v_mfma_f32_16x16x32_bf16 v[70:73], v[162:165], v[216:219], v[70:73]
	v_mfma_f32_16x16x32_bf16 v[70:73], v[166:169], v[220:223], v[70:73]
	v_mfma_f32_16x16x32_bf16 v[66:69], v[182:185], v[216:219], v[66:69]
	v_mfma_f32_16x16x32_bf16 v[66:69], v[186:189], v[220:223], v[66:69]
	s_setprio 0
	s_barrier
	s_add_i32 s71, s71, s6
	v_lshl_add_u64 v[224:225], s[42:43], 0, v[134:135]
	s_mov_b32 m0, s71
	ds_read_b128 v[190:193], v177 offset:16384
	ds_read_b128 v[194:197], v177 offset:17408
	ds_read_b128 v[198:201], v177 offset:18432
	ds_read_b128 v[204:207], v177 offset:19456
	ds_read_b128 v[208:211], v177 offset:20480
	ds_read_b128 v[212:215], v177 offset:21504
	ds_read_b128 v[216:219], v177 offset:22528
	ds_read_b128 v[220:223], v177 offset:23552
	global_load_lds_dwordx4 v[224:225], off
	s_add_i32 m0, s71, 0x2000
	s_add_u32 s84, s42, 0x10000
	v_lshl_add_u64 v[226:227], s[42:43], 0, v[138:139]
	s_addc_u32 s85, s43, 0
	s_add_i32 s71, s74, s6
	global_load_lds_dwordx4 v[226:227], off
	v_lshl_add_u64 v[228:229], s[84:85], 0, v[134:135]
	s_mov_b32 m0, s71
	v_lshl_add_u64 v[230:231], s[44:45], 0, v[136:137]
	global_load_lds_dwordx4 v[228:229], off
	v_lshl_add_u64 v[228:229], s[84:85], 0, v[138:139]
	s_add_i32 m0, s71, 0x2000
	s_nop 0
	global_load_lds_dwordx4 v[228:229], off
	v_lshl_add_u64 v[228:229], s[44:45], 0, v[132:133]
	s_mov_b32 m0, s7
	s_nop 0
	global_load_lds_dwordx4 v[228:229], off
	s_mov_b32 m0, s57
	s_nop 0
	global_load_lds_dwordx4 v[230:231], off
	s_waitcnt vmcnt(8)
	s_waitcnt lgkmcnt(0)
	s_barrier
; #define PG8_STAGE(bufoff, gbase, voff) do { _Pragma("unroll") for (int _i = 0; _i < 2; ++_i) \
;         __builtin_amdgcn_global_load_lds((const unsigned*)((const char*)(gbase) + (voff)[_i]), (PG8_LAS unsigned*)(lds + (bufoff) + ldsw + _i * 8192), 16, 0, 0); } while (0)
; #define PG8_LDA(dst, b, h) do { _Pragma("unroll") for (int m = 0; m < 4; ++m) _Pragma("unroll") for (int k = 0; k < 2; ++k) dst[m][k] = *(const PG8_LAS bf16x8*)(lds + PG8_SA(b, h) + aoff + m * 2048 + k * 1024); } while (0)
; #define PG8_LDB(dst, b, h) do { _Pragma("unroll") for (int n = 0; n < 2; ++n) _Pragma("unroll") for (int k = 0; k < 2; ++k) dst[n][k] = *(const PG8_LAS bf16x8*)(lds + PG8_SB(b, h) + boff + n * 2048 + k * 1024); } while (0)
; #define PG8_MMA(ai, bj, At, Bt) do { __builtin_amdgcn_s_setprio(1); _Pragma("unroll") for (int m = 0; m < 4; ++m) _Pragma("unroll") for (int n = 0; n < 2; ++n) _Pragma("unroll") for (int k = 0; k < 2; ++k) \
;         acc[ai][bj][m][n] = __builtin_amdgcn_mfma_f32_16x16x32_bf16(Bt[n][k], At[m][k], acc[ai][bj][m][n], 0, 0, 0); __builtin_amdgcn_s_setprio(0); } while (0)
; #define PG8_WAIT_V(n) asm volatile("s_waitcnt vmcnt(" #n ")" ::: "memory")
; #define PG8_WAIT_L(n) asm volatile("s_waitcnt lgkmcnt(" #n ")" ::: "memory")
; #define PG8_BAR __builtin_amdgcn_s_barrier()
; #define PG8_SCHED __builtin_amdgcn_sched_barrier(0)
; template <class Epi, class Sched, bool ALIGN_EPI = false, bool SP2 = false>
; __device__ __forceinline__ void gemm_phase(PG8_LAS unsigned char* lds, const Gemm g, const Sched& S, const Epi& E, const int wave_s) {
;     ...
;             PG8_WAIT_V(8); PG8_WAIT_L(0); PG8_BAR; PG8_MMA(1, 0, At, B0); PG8_MMA(1, 1, At, B1); PG8_BAR; PG8_SCHED;
;             PG8_LDB(B0, 1, 0); PG8_LDB(B1, 1, 1); PG8_SCHED; PG8_LDA(At, 1, 0); PG8_STAGE(PG8_SA(0, 1), a2 + hstep, voffA);
;             PG8_WAIT_V(8); PG8_WAIT_L(0); PG8_BAR; PG8_MMA(0, 0, At, B0); PG8_MMA(0, 1, At, B1); PG8_BAR; PG8_SCHED;
	s_setprio 1
	s_waitcnt lgkmcnt(0)
	v_mfma_f32_16x16x32_bf16 v[62:65], v[146:149], v[190:193], v[62:65]
	v_mfma_f32_16x16x32_bf16 v[62:65], v[150:153], v[194:197], v[62:65]
	v_mfma_f32_16x16x32_bf16 v[58:61], v[154:157], v[190:193], v[58:61]
	v_mfma_f32_16x16x32_bf16 v[58:61], v[158:161], v[194:197], v[58:61]
	v_mfma_f32_16x16x32_bf16 v[46:49], v[146:149], v[198:201], v[46:49]
	v_mfma_f32_16x16x32_bf16 v[46:49], v[150:153], v[204:207], v[46:49]
	v_mfma_f32_16x16x32_bf16 v[42:45], v[154:157], v[198:201], v[42:45]
	v_mfma_f32_16x16x32_bf16 v[42:45], v[158:161], v[204:207], v[42:45]
	v_mfma_f32_16x16x32_bf16 v[30:33], v[146:149], v[208:211], v[30:33]
	v_mfma_f32_16x16x32_bf16 v[30:33], v[150:153], v[212:215], v[30:33]
	v_mfma_f32_16x16x32_bf16 v[26:29], v[154:157], v[208:211], v[26:29]
	v_mfma_f32_16x16x32_bf16 v[26:29], v[158:161], v[212:215], v[26:29]
	v_mfma_f32_16x16x32_bf16 v[14:17], v[146:149], v[216:219], v[14:17]
	v_mfma_f32_16x16x32_bf16 v[14:17], v[150:153], v[220:223], v[14:17]
	v_mfma_f32_16x16x32_bf16 v[10:13], v[154:157], v[216:219], v[10:13]
	v_mfma_f32_16x16x32_bf16 v[10:13], v[158:161], v[220:223], v[10:13]
	s_setprio 0
	s_setprio 1
	v_mfma_f32_16x16x32_bf16 v[54:57], v[162:165], v[190:193], v[54:57]
	v_mfma_f32_16x16x32_bf16 v[54:57], v[166:169], v[194:197], v[54:57]
	v_mfma_f32_16x16x32_bf16 v[50:53], v[182:185], v[190:193], v[50:53]
	v_mfma_f32_16x16x32_bf16 v[50:53], v[186:189], v[194:197], v[50:53]
	v_mfma_f32_16x16x32_bf16 v[38:41], v[162:165], v[198:201], v[38:41]
	v_mfma_f32_16x16x32_bf16 v[38:41], v[166:169], v[204:207], v[38:41]
	v_mfma_f32_16x16x32_bf16 v[34:37], v[182:185], v[198:201], v[34:37]
	v_mfma_f32_16x16x32_bf16 v[34:37], v[186:189], v[204:207], v[34:37]
	v_mfma_f32_16x16x32_bf16 v[22:25], v[162:165], v[208:211], v[22:25]
	v_mfma_f32_16x16x32_bf16 v[22:25], v[166:169], v[212:215], v[22:25]
	v_mfma_f32_16x16x32_bf16 v[18:21], v[182:185], v[208:211], v[18:21]
	v_mfma_f32_16x16x32_bf16 v[18:21], v[186:189], v[212:215], v[18:21]
	v_mfma_f32_16x16x32_bf16 v[6:9], v[162:165], v[216:219], v[6:9]
	v_mfma_f32_16x16x32_bf16 v[6:9], v[166:169], v[220:223], v[6:9]
	v_mfma_f32_16x16x32_bf16 v[2:5], v[182:185], v[216:219], v[2:5]
	v_mfma_f32_16x16x32_bf16 v[2:5], v[186:189], v[220:223], v[2:5]
	s_setprio 0
	s_barrier
	s_add_i32 s71, 0, 0x18000
	v_add_u32_e32 v0, s71, v171
	s_add_i32 s74, 0, 0x1c000
	ds_read_b128 v[146:149], v0
	ds_read_b128 v[150:153], v0 offset:1024
	ds_read_b128 v[154:157], v0 offset:2048
	ds_read_b128 v[158:161], v0 offset:3072
	v_add_u32_e32 v0, s74, v171
	ds_read_b128 v[162:165], v0
	ds_read_b128 v[166:169], v0 offset:1024
	ds_read_b128 v[182:185], v0 offset:2048
	ds_read_b128 v[186:189], v0 offset:3072
	s_add_u32 s44, s44, 0x40000
	s_addc_u32 s45, s45, 0
	s_mov_b32 m0, s8
	v_lshl_add_u64 v[232:233], s[44:45], 0, v[132:133]
	ds_read_b128 v[190:193], v177 offset:32768
	ds_read_b128 v[194:197], v177 offset:33792
	ds_read_b128 v[198:201], v177 offset:34816
	ds_read_b128 v[204:207], v177 offset:35840
	ds_read_b128 v[208:211], v177 offset:36864
	ds_read_b128 v[212:215], v177 offset:37888
	ds_read_b128 v[216:219], v177 offset:38912
	ds_read_b128 v[220:223], v177 offset:39936
	global_load_lds_dwordx4 v[232:233], off
	v_lshl_add_u64 v[232:233], s[44:45], 0, v[136:137]
	s_mov_b32 m0, s9
	s_nop 0
	global_load_lds_dwordx4 v[232:233], off
	s_waitcnt vmcnt(8)
	s_waitcnt lgkmcnt(0)
	s_barrier
	s_setprio 1
	s_waitcnt lgkmcnt(0)
	v_mfma_f32_16x16x32_bf16 v[126:129], v[146:149], v[190:193], v[126:129]
	v_mfma_f32_16x16x32_bf16 v[126:129], v[150:153], v[194:197], v[126:129]
	v_mfma_f32_16x16x32_bf16 v[122:125], v[154:157], v[190:193], v[122:125]
	v_mfma_f32_16x16x32_bf16 v[122:125], v[158:161], v[194:197], v[122:125]
	v_mfma_f32_16x16x32_bf16 v[110:113], v[146:149], v[198:201], v[110:113]
	v_mfma_f32_16x16x32_bf16 v[110:113], v[150:153], v[204:207], v[110:113]
	v_mfma_f32_16x16x32_bf16 v[106:109], v[154:157], v[198:201], v[106:109]
	v_mfma_f32_16x16x32_bf16 v[106:109], v[158:161], v[204:207], v[106:109]
	v_mfma_f32_16x16x32_bf16 v[94:97], v[146:149], v[208:211], v[94:97]
	v_mfma_f32_16x16x32_bf16 v[94:97], v[150:153], v[212:215], v[94:97]
	v_mfma_f32_16x16x32_bf16 v[90:93], v[154:157], v[208:211], v[90:93]
	v_mfma_f32_16x16x32_bf16 v[90:93], v[158:161], v[212:215], v[90:93]
	v_mfma_f32_16x16x32_bf16 v[78:81], v[146:149], v[216:219], v[78:81]
	v_mfma_f32_16x16x32_bf16 v[78:81], v[150:153], v[220:223], v[78:81]
	v_mfma_f32_16x16x32_bf16 v[74:77], v[154:157], v[216:219], v[74:77]
	v_mfma_f32_16x16x32_bf16 v[74:77], v[158:161], v[220:223], v[74:77]
	s_setprio 0
	s_setprio 1
	v_mfma_f32_16x16x32_bf16 v[118:121], v[162:165], v[190:193], v[118:121]
	v_mfma_f32_16x16x32_bf16 v[118:121], v[166:169], v[194:197], v[118:121]
	v_mfma_f32_16x16x32_bf16 v[114:117], v[182:185], v[190:193], v[114:117]
	v_mfma_f32_16x16x32_bf16 v[114:117], v[186:189], v[194:197], v[114:117]
	v_mfma_f32_16x16x32_bf16 v[102:105], v[162:165], v[198:201], v[102:105]
	v_mfma_f32_16x16x32_bf16 v[102:105], v[166:169], v[204:207], v[102:105]
	v_mfma_f32_16x16x32_bf16 v[98:101], v[182:185], v[198:201], v[98:101]
	v_mfma_f32_16x16x32_bf16 v[98:101], v[186:189], v[204:207], v[98:101]
	v_mfma_f32_16x16x32_bf16 v[86:89], v[162:165], v[208:211], v[86:89]
	v_mfma_f32_16x16x32_bf16 v[86:89], v[166:169], v[212:215], v[86:89]
	v_mfma_f32_16x16x32_bf16 v[82:85], v[182:185], v[208:211], v[82:85]
	v_mfma_f32_16x16x32_bf16 v[82:85], v[186:189], v[212:215], v[82:85]
	v_mfma_f32_16x16x32_bf16 v[70:73], v[162:165], v[216:219], v[70:73]
	v_mfma_f32_16x16x32_bf16 v[70:73], v[166:169], v[220:223], v[70:73]
	v_mfma_f32_16x16x32_bf16 v[66:69], v[182:185], v[216:219], v[66:69]
	v_mfma_f32_16x16x32_bf16 v[66:69], v[186:189], v[220:223], v[66:69]
	s_setprio 0
	s_barrier
; #define PG8_STAGE(bufoff, gbase, voff) do { _Pragma("unroll") for (int _i = 0; _i < 2; ++_i) \
;         __builtin_amdgcn_global_load_lds((const unsigned*)((const char*)(gbase) + (voff)[_i]), (PG8_LAS unsigned*)(lds + (bufoff) + ldsw + _i * 8192), 16, 0, 0); } while (0)
; #define PG8_LDA(dst, b, h) do { _Pragma("unroll") for (int m = 0; m < 4; ++m) _Pragma("unroll") for (int k = 0; k < 2; ++k) dst[m][k] = *(const PG8_LAS bf16x8*)(lds + PG8_SA(b, h) + aoff + m * 2048 + k * 1024); } while (0)
; #define PG8_BAR __builtin_amdgcn_s_barrier()
; template <class Epi, class Sched, bool ALIGN_EPI = false, bool SP2 = false>
; __device__ __forceinline__ void gemm_phase(PG8_LAS unsigned char* lds, const Gemm g, const Sched& S, const Epi& E, const int wave_s) {
;     ...
;             PG8_LDA(At, 1, 1); PG8_STAGE(PG8_SB(1, 0), b3, voffB); PG8_STAGE(PG8_SB(1, 1), b3 + bhstep, voffB); PG8_STAGE(PG8_SA(1, 0), a3, voffA);
;             PG8_WAIT_V(8); PG8_WAIT_L(0); PG8_BAR; PG8_MMA(1, 0, At, B0); PG8_MMA(1, 1, At, B1); PG8_BAR; PG8_SCHED;
;             } else {
;             PG8_LDB(B0, 0, 0); PG8_SCHED; PG8_LDA(At, 0, 0); PG8_STAGE(PG8_SA(1, 1), a1 + hstep, voffA);
;             PG8_WAIT_L(8); PG8_BAR; PG8_WAIT_L(0); PG8_MMA(0, 0, At, B0); PG8_BAR; PG8_SCHED;
;             PG8_LDB(B1, 0, 1); PG8_STAGE(PG8_SB(0, 0), b2, voffB);
;             PG8_BAR; PG8_WAIT_L(0); PG8_MMA(0, 1, At, B1); PG8_BAR;
;             PG8_LDA(At, 0, 1); PG8_STAGE(PG8_SA(0, 0), a2, voffA);
;             PG8_BAR; PG8_WAIT_L(0); PG8_MMA(1, 0, At, B0); PG8_BAR; PG8_SCHED;
;             PG8_STAGE(PG8_SB(0, 1), b2 + bhstep, voffB);
;             PG8_WAIT_V(6); PG8_BAR; PG8_MMA(1, 1, At, B1); PG8_BAR;
;             PG8_LDB(B0, 1, 0); PG8_SCHED; PG8_LDA(At, 1, 0); PG8_STAGE(PG8_SA(0, 1), a2 + hstep, voffA);
;             PG8_WAIT_L(8); PG8_BAR; PG8_WAIT_L(0); PG8_MMA(0, 0, At, B0); PG8_BAR; PG8_SCHED;
;             PG8_LDB(B1, 1, 1); PG8_STAGE(PG8_SB(1, 0), b3, voffB);
;             PG8_BAR; PG8_WAIT_L(0); PG8_MMA(0, 1, At, B1); PG8_BAR;
;             PG8_LDA(At, 1, 1); PG8_STAGE(PG8_SA(1, 0), a3, voffA);
;             PG8_BAR; PG8_WAIT_L(0); PG8_MMA(1, 0, At, B0); PG8_BAR; PG8_SCHED;
;             PG8_STAGE(PG8_SB(1, 1), b3 + bhstep, voffB);
;             PG8_WAIT_V(6); PG8_BAR; PG8_MMA(1, 1, At, B1); PG8_BAR;
;             }
;         }
;         if constexpr (ALIGN_EPI) { if (wr == 0) PG8_BAR; }
	s_add_i32 s44, s71, s6
	v_lshl_add_u64 v[224:225], v[224:225], 0, s[24:25]
	s_mov_b32 m0, s44
	ds_read_b128 v[190:193], v177 offset:49152
	ds_read_b128 v[194:197], v177 offset:50176
	ds_read_b128 v[198:201], v177 offset:51200
	ds_read_b128 v[204:207], v177 offset:52224
	ds_read_b128 v[208:211], v177 offset:53248
	ds_read_b128 v[212:215], v177 offset:54272
	ds_read_b128 v[216:219], v177 offset:55296
	ds_read_b128 v[220:223], v177 offset:56320
	global_load_lds_dwordx4 v[224:225], off
	s_add_i32 m0, s44, 0x2000
	s_add_u32 s42, s42, 0x10080
	v_lshl_add_u64 v[224:225], v[226:227], 0, s[24:25]
	s_addc_u32 s43, s43, 0
	s_add_i32 s44, s74, s6
	global_load_lds_dwordx4 v[224:225], off
	v_lshl_add_u64 v[224:225], s[42:43], 0, v[134:135]
	s_mov_b32 m0, s44
	s_nop 0
	global_load_lds_dwordx4 v[224:225], off
	v_lshl_add_u64 v[224:225], s[42:43], 0, v[138:139]
	s_add_i32 m0, s44, 0x2000
	s_nop 0
	global_load_lds_dwordx4 v[224:225], off
	v_lshl_add_u64 v[224:225], v[228:229], 0, s[24:25]
	s_mov_b32 m0, s11
	s_nop 0
	global_load_lds_dwordx4 v[224:225], off
	v_lshl_add_u64 v[224:225], v[230:231], 0, s[24:25]
	s_mov_b32 m0, s12
	s_nop 0
	global_load_lds_dwordx4 v[224:225], off
	s_waitcnt vmcnt(8)
	s_waitcnt lgkmcnt(0)
	s_barrier
	s_setprio 1
	s_waitcnt lgkmcnt(0)
	v_mfma_f32_16x16x32_bf16 v[62:65], v[146:149], v[190:193], v[62:65]
	v_mfma_f32_16x16x32_bf16 v[62:65], v[150:153], v[194:197], v[62:65]
	v_mfma_f32_16x16x32_bf16 v[58:61], v[154:157], v[190:193], v[58:61]
	v_mfma_f32_16x16x32_bf16 v[58:61], v[158:161], v[194:197], v[58:61]
	v_mfma_f32_16x16x32_bf16 v[46:49], v[146:149], v[198:201], v[46:49]
	v_mfma_f32_16x16x32_bf16 v[46:49], v[150:153], v[204:207], v[46:49]
	v_mfma_f32_16x16x32_bf16 v[42:45], v[154:157], v[198:201], v[42:45]
	v_mfma_f32_16x16x32_bf16 v[42:45], v[158:161], v[204:207], v[42:45]
	v_mfma_f32_16x16x32_bf16 v[30:33], v[146:149], v[208:211], v[30:33]
	v_mfma_f32_16x16x32_bf16 v[30:33], v[150:153], v[212:215], v[30:33]
	v_mfma_f32_16x16x32_bf16 v[26:29], v[154:157], v[208:211], v[26:29]
	v_mfma_f32_16x16x32_bf16 v[26:29], v[158:161], v[212:215], v[26:29]
	v_mfma_f32_16x16x32_bf16 v[14:17], v[146:149], v[216:219], v[14:17]
	v_mfma_f32_16x16x32_bf16 v[14:17], v[150:153], v[220:223], v[14:17]
	v_mfma_f32_16x16x32_bf16 v[10:13], v[154:157], v[216:219], v[10:13]
	v_mfma_f32_16x16x32_bf16 v[10:13], v[158:161], v[220:223], v[10:13]
	s_setprio 0
	s_setprio 1
	v_mfma_f32_16x16x32_bf16 v[54:57], v[162:165], v[190:193], v[54:57]
	v_mfma_f32_16x16x32_bf16 v[54:57], v[166:169], v[194:197], v[54:57]
	v_mfma_f32_16x16x32_bf16 v[50:53], v[182:185], v[190:193], v[50:53]
	v_mfma_f32_16x16x32_bf16 v[50:53], v[186:189], v[194:197], v[50:53]
	v_mfma_f32_16x16x32_bf16 v[38:41], v[162:165], v[198:201], v[38:41]
	v_mfma_f32_16x16x32_bf16 v[38:41], v[166:169], v[204:207], v[38:41]
	v_mfma_f32_16x16x32_bf16 v[34:37], v[182:185], v[198:201], v[34:37]
	v_mfma_f32_16x16x32_bf16 v[34:37], v[186:189], v[204:207], v[34:37]
	v_mfma_f32_16x16x32_bf16 v[22:25], v[162:165], v[208:211], v[22:25]
	v_mfma_f32_16x16x32_bf16 v[22:25], v[166:169], v[212:215], v[22:25]
	v_mfma_f32_16x16x32_bf16 v[18:21], v[182:185], v[208:211], v[18:21]
	v_mfma_f32_16x16x32_bf16 v[18:21], v[186:189], v[212:215], v[18:21]
	v_mfma_f32_16x16x32_bf16 v[6:9], v[162:165], v[216:219], v[6:9]
	v_mfma_f32_16x16x32_bf16 v[6:9], v[166:169], v[220:223], v[6:9]
	v_mfma_f32_16x16x32_bf16 v[2:5], v[182:185], v[216:219], v[2:5]
	v_mfma_f32_16x16x32_bf16 v[2:5], v[186:189], v[220:223], v[2:5]
	s_setprio 0
	s_barrier
	s_add_i32 s70, s70, 2
	s_add_u32 s20, s20, 0x100
	s_addc_u32 s21, s21, 0
	s_add_u32 s68, s68, 0x100
	s_addc_u32 s69, s69, 0
	s_cmp_gt_u32 s70, 13
	s_cbranch_scc0 .LBB0_136

; #define PG8_LAS __attribute__((address_space(3)))
; __device__ __forceinline__ unsigned cvt_pk_bf16(float lo, float hi) { unsigned r; asm volatile("v_cvt_pk_bf16_f32 %0, %1, %2" : "=v"(r) : "v"(lo), "v"(hi)); return r; }
; __device__ __forceinline__ float peer_x16(float v, int fq) { auto r = __builtin_amdgcn_permlane16_swap(__float_as_uint(v), __float_as_uint(v), false, false); return __uint_as_float((fq & 1) ? r[0] : r[1]); }
;     __device__ __forceinline__ void operator()(const f32x4 (&acc)[2][2][4][2], const Unit& u, int wr, int wc, int fr, int fq, PG8_LAS float* stash, int par, PG8_LAS unsigned char* stg, const Unit& un) const {
;     ...
;                 const int row = u.pm * BM + ai * HALF + wr * 64 + m * 16 + fr, pos = row & 4095, b = row >> 12;
;                 const float rs = rsa[ai][m];
; #pragma unroll
;                 for (int bj = 0; bj < 2; ++bj) {
;                     int kind;
;                     if (odd) kind = (u.pn < 6) ? 0 : (u.pn == 6 ? 1 : 2);
;                     else     kind = (u.pn < 2) ? 0 : (u.pn == 2 ? (wc < 2 ? 1 : 2) : 3);
;                     float v[8];
; #pragma unroll
;                     for (int i = 0; i < 4; ++i) { v[i] = acc[ai][bj][m][0][i] * rs; v[4 + i] = acc[ai][bj][m][1][i] * rs; }
;                     if (kind <= 1 && bj == 0) {
;                         const f32x4 c0 = *(const f32x4*)(cs + pos * 16), c1 = *(const f32x4*)(cs + pos * 16 + 4), s0 = *(const f32x4*)(cs + pos * 16 + 8), s1 = *(const f32x4*)(cs + pos * 16 + 12);
; #pragma unroll
;                         for (int i = 0; i < 8; ++i) {
;                             const float c = i < 4 ? c0[i & 3] : c1[i & 3], s = i < 4 ? s0[i & 3] : s1[i & 3];
;                             const float pr = peer_x16(v[i], fq);
;                             const float r = (fq == 0) ? (v[i] * c - pr * s) : (v[i] * c + pr * s);
;                             v[i] = (fq < 2) ? r : v[i];
;                         }
;                     }
;                     if (kind == 0) {
; #pragma unroll
;                         for (int i = 0; i < 8; ++i) v[i] *= C2Q;
;                     }
;                     { u32x4 w; w.x = cvt_pk_bf16(v[0], v[1]); w.y = cvt_pk_bf16(v[2], v[3]); w.z = cvt_pk_bf16(v[4], v[5]); w.w = cvt_pk_bf16(v[6], v[7]);
;                       *(PG8_LAS u32x4*)(stg + fr * 144 + fq * 16 + bj * 64) = w; }
;                 }
.Lipe_Q:
	s_add_i32 s44, s19, 0
	s_and_b32 s44, s44, 0xfff
	v_or_b32_e32 v0, s44, v141
	v_lshlrev_b32_e32 v0, 6, v0
	s_mov_b64 s[44:45], exec
	s_and_b64 exec, exec, s[38:39]
	global_load_dwordx4 v[154:157], v0, s[62:63]
	global_load_dwordx4 v[158:161], v0, s[62:63] offset:16
	global_load_dwordx4 v[162:165], v0, s[62:63] offset:32
	global_load_dwordx4 v[166:169], v0, s[62:63] offset:48
	s_mov_b64 exec, s[44:45]
	s_add_i32 s44, s19, 16
	s_and_b32 s44, s44, 0xfff
	v_or_b32_e32 v0, s44, v141
	v_lshlrev_b32_e32 v0, 6, v0
	s_mov_b64 s[44:45], exec
	s_and_b64 exec, exec, s[38:39]
	global_load_dwordx4 v[218:221], v0, s[62:63]
	global_load_dwordx4 v[222:225], v0, s[62:63] offset:16
	global_load_dwordx4 v[226:229], v0, s[62:63] offset:32
	global_load_dwordx4 v[230:233], v0, s[62:63] offset:48
	s_mov_b64 exec, s[44:45]
	v_pk_mul_f32 v[118:119], v[118:119], v[152:153] op_sel_hi:[1,0]
	v_pk_mul_f32 v[120:121], v[120:121], v[152:153] op_sel_hi:[1,0]
	v_pk_mul_f32 v[114:115], v[114:115], v[152:153] op_sel_hi:[1,0]
	v_pk_mul_f32 v[116:117], v[116:117], v[152:153] op_sel_hi:[1,0]
	v_pk_mul_f32 v[118:119], v[118:119], s[30:31] op_sel_hi:[1,0]
	v_pk_mul_f32 v[120:121], v[120:121], s[30:31] op_sel_hi:[1,0]
	v_pk_mul_f32 v[114:115], v[114:115], s[30:31] op_sel_hi:[1,0]
	v_pk_mul_f32 v[116:117], v[116:117], s[30:31] op_sel_hi:[1,0]
	v_cvt_pk_bf16_f32 v118, v118, v119
	v_cvt_pk_bf16_f32 v119, v120, v121
	v_cvt_pk_bf16_f32 v120, v114, v115
	v_cvt_pk_bf16_f32 v121, v116, v117
	v_pk_mul_f32 v[126:127], v[126:127], v[152:153] op_sel_hi:[1,0]
	v_pk_mul_f32 v[128:129], v[128:129], v[152:153] op_sel_hi:[1,0]
	v_pk_mul_f32 v[122:123], v[122:123], v[152:153] op_sel_hi:[1,0]
	v_pk_mul_f32 v[124:125], v[124:125], v[152:153] op_sel_hi:[1,0]
	ds_swizzle_b32 v114, v126 offset:0x401f
	ds_swizzle_b32 v115, v127 offset:0x401f
	ds_swizzle_b32 v116, v128 offset:0x401f
	ds_swizzle_b32 v117, v129 offset:0x401f
	s_waitcnt vmcnt(4)
	v_xor_b32_e32 v162, v201, v162
	v_xor_b32_e32 v163, v201, v163
	v_xor_b32_e32 v164, v201, v164
	v_xor_b32_e32 v165, v201, v165
	v_xor_b32_e32 v166, v201, v166
	v_xor_b32_e32 v167, v201, v167
	v_xor_b32_e32 v168, v201, v168
	v_xor_b32_e32 v169, v201, v169
	s_waitcnt lgkmcnt(0)
	v_mul_f32_e32 v114, v162, v114
	v_fmac_f32_e32 v114, v126, v154
	v_cndmask_b32_e64 v126, v126, v114, s[38:39]
	v_mul_f32_e32 v115, v163, v115
	v_fmac_f32_e32 v115, v127, v155
	v_cndmask_b32_e64 v127, v127, v115, s[38:39]
	v_mul_f32_e32 v116, v164, v116
	v_fmac_f32_e32 v116, v128, v156
	v_cndmask_b32_e64 v128, v128, v116, s[38:39]
	v_mul_f32_e32 v117, v165, v117
	v_fmac_f32_e32 v117, v129, v157
	v_cndmask_b32_e64 v129, v129, v117, s[38:39]
	ds_swizzle_b32 v114, v122 offset:0x401f
	ds_swizzle_b32 v115, v123 offset:0x401f
	ds_swizzle_b32 v116, v124 offset:0x401f
	ds_swizzle_b32 v117, v125 offset:0x401f
	s_waitcnt lgkmcnt(0)
	v_mul_f32_e32 v114, v166, v114
	v_fmac_f32_e32 v114, v122, v158
	v_cndmask_b32_e64 v122, v122, v114, s[38:39]
	v_mul_f32_e32 v115, v167, v115
	v_fmac_f32_e32 v115, v123, v159
	v_cndmask_b32_e64 v123, v123, v115, s[38:39]
	v_mul_f32_e32 v116, v168, v116
	v_fmac_f32_e32 v116, v124, v160
	v_cndmask_b32_e64 v124, v124, v116, s[38:39]
	v_mul_f32_e32 v117, v169, v117
	v_fmac_f32_e32 v117, v125, v161
	v_cndmask_b32_e64 v125, v125, v117, s[38:39]
	v_pk_mul_f32 v[126:127], v[126:127], s[30:31] op_sel_hi:[1,0]
	v_pk_mul_f32 v[128:129], v[128:129], s[30:31] op_sel_hi:[1,0]
	v_pk_mul_f32 v[122:123], v[122:123], s[30:31] op_sel_hi:[1,0]
	v_pk_mul_f32 v[124:125], v[124:125], s[30:31] op_sel_hi:[1,0]
	v_cvt_pk_bf16_f32 v126, v126, v127
	v_cvt_pk_bf16_f32 v127, v128, v129
	v_cvt_pk_bf16_f32 v128, v122, v123
	v_cvt_pk_bf16_f32 v129, v124, v125
	ds_write_b128 v178, v[126:129]
	ds_write_b128 v178, v[118:121] offset:64
	ds_read_b128 v[122:125], v180
	ds_read_b128 v[114:117], v180 offset:1152
	s_and_b64 vcc, exec, s[60:61]
	s_cbranch_vccz .Lalign_ipeQ
	s_barrier
.Lalign_ipeQ:
	s_add_i32 s44, s19, 32
	s_and_b32 s44, s44, 0xfff
	v_or_b32_e32 v0, s44, v141
	v_lshlrev_b32_e32 v0, 6, v0
	s_mov_b64 s[44:45], exec
	s_and_b64 exec, exec, s[38:39]
	global_load_dwordx4 v[154:157], v0, s[62:63]
	global_load_dwordx4 v[158:161], v0, s[62:63] offset:16
	global_load_dwordx4 v[162:165], v0, s[62:63] offset:32
	global_load_dwordx4 v[166:169], v0, s[62:63] offset:48
	s_mov_b64 exec, s[44:45]
	v_pk_mul_f32 v[102:103], v[102:103], v[152:153] op_sel:[0,1]
	v_pk_mul_f32 v[104:105], v[104:105], v[152:153] op_sel:[0,1]
	v_pk_mul_f32 v[98:99], v[98:99], v[152:153] op_sel:[0,1]
	v_pk_mul_f32 v[100:101], v[100:101], v[152:153] op_sel:[0,1]
	v_pk_mul_f32 v[102:103], v[102:103], s[30:31] op_sel_hi:[1,0]
	v_pk_mul_f32 v[104:105], v[104:105], s[30:31] op_sel_hi:[1,0]
	v_pk_mul_f32 v[98:99], v[98:99], s[30:31] op_sel_hi:[1,0]
	v_pk_mul_f32 v[100:101], v[100:101], s[30:31] op_sel_hi:[1,0]
	v_cvt_pk_bf16_f32 v102, v102, v103
	v_cvt_pk_bf16_f32 v103, v104, v105
	v_cvt_pk_bf16_f32 v104, v98, v99
	v_cvt_pk_bf16_f32 v105, v100, v101
	v_pk_mul_f32 v[110:111], v[110:111], v[152:153] op_sel:[0,1]
	v_pk_mul_f32 v[112:113], v[112:113], v[152:153] op_sel:[0,1]
	v_pk_mul_f32 v[106:107], v[106:107], v[152:153] op_sel:[0,1]
	v_pk_mul_f32 v[108:109], v[108:109], v[152:153] op_sel:[0,1]
	ds_swizzle_b32 v98, v110 offset:0x401f
	ds_swizzle_b32 v99, v111 offset:0x401f
	ds_swizzle_b32 v100, v112 offset:0x401f
	ds_swizzle_b32 v101, v113 offset:0x401f
	s_waitcnt vmcnt(4)
	v_xor_b32_e32 v226, v201, v226
	v_xor_b32_e32 v227, v201, v227
	v_xor_b32_e32 v228, v201, v228
	v_xor_b32_e32 v229, v201, v229
	v_xor_b32_e32 v230, v201, v230
	v_xor_b32_e32 v231, v201, v231
	v_xor_b32_e32 v232, v201, v232
	v_xor_b32_e32 v233, v201, v233
	s_waitcnt lgkmcnt(0)
;     __device__ __forceinline__ void operator()(const f32x4 (&acc)[2][2][4][2], const Unit& u, int wr, int wc, int fr, int fq, PG8_LAS float* stash, int par, PG8_LAS unsigned char* stg, const Unit& un) const {
;     ...
;                 const int row = u.pm * BM + ai * HALF + wr * 64 + m * 16 + fr, pos = row & 4095, b = row >> 12;
;                 const float rs = rsa[ai][m];
; #pragma unroll
;                 for (int bj = 0; bj < 2; ++bj) {
;                     int kind;
;                     if (odd) kind = (u.pn < 6) ? 0 : (u.pn == 6 ? 1 : 2);
;                     else     kind = (u.pn < 2) ? 0 : (u.pn == 2 ? (wc < 2 ? 1 : 2) : 3);
;                     float v[8];
; #pragma unroll
;                     for (int i = 0; i < 4; ++i) { v[i] = acc[ai][bj][m][0][i] * rs; v[4 + i] = acc[ai][bj][m][1][i] * rs; }
;                     if (kind <= 1 && bj == 0) {
;                         const f32x4 c0 = *(const f32x4*)(cs + pos * 16), c1 = *(const f32x4*)(cs + pos * 16 + 4), s0 = *(const f32x4*)(cs + pos * 16 + 8), s1 = *(const f32x4*)(cs + pos * 16 + 12);
; #pragma unroll
;                         for (int i = 0; i < 8; ++i) {
;                             const float c = i < 4 ? c0[i & 3] : c1[i & 3], s = i < 4 ? s0[i & 3] : s1[i & 3];
;                             const float pr = peer_x16(v[i], fq);
;                             const float r = (fq == 0) ? (v[i] * c - pr * s) : (v[i] * c + pr * s);
;                             v[i] = (fq < 2) ? r : v[i];
;                         }
;                     }
;                     if (kind == 0) {
; #pragma unroll
;                         for (int i = 0; i < 8; ++i) v[i] *= C2Q;
;                     }
;                     { u32x4 w; w.x = cvt_pk_bf16(v[0], v[1]); w.y = cvt_pk_bf16(v[2], v[3]); w.z = cvt_pk_bf16(v[4], v[5]); w.w = cvt_pk_bf16(v[6], v[7]);
;                       *(PG8_LAS u32x4*)(stg + fr * 144 + fq * 16 + bj * 64) = w; }
;                 }
;                 {
;                     int kind;
;                     if (odd) kind = (u.pn < 6) ? 0 : (u.pn == 6 ? 1 : 2);
;                     else     kind = (u.pn < 2) ? 0 : (u.pn == 2 ? (wc < 2 ? 1 : 2) : 3);
; #pragma unroll
;                     for (int i = 0; i < 2; ++i) { const int c = fq * 16 + fr + 64 * i, rr = c >> 3, pc = c & 7;
;                         const u32x4 w = *(const PG8_LAS u32x4*)(stg + rr * 144 + pc * 16);
	v_mul_f32_e32 v98, v226, v98
	v_fmac_f32_e32 v98, v110, v218
	v_cndmask_b32_e64 v110, v110, v98, s[38:39]
	v_mul_f32_e32 v99, v227, v99
	v_fmac_f32_e32 v99, v111, v219
	v_cndmask_b32_e64 v111, v111, v99, s[38:39]
	v_mul_f32_e32 v100, v228, v100
	v_fmac_f32_e32 v100, v112, v220
	v_cndmask_b32_e64 v112, v112, v100, s[38:39]
	v_mul_f32_e32 v101, v229, v101
	v_fmac_f32_e32 v101, v113, v221
	v_cndmask_b32_e64 v113, v113, v101, s[38:39]
	ds_swizzle_b32 v98, v106 offset:0x401f
	ds_swizzle_b32 v99, v107 offset:0x401f
	ds_swizzle_b32 v100, v108 offset:0x401f
	ds_swizzle_b32 v101, v109 offset:0x401f
	s_waitcnt lgkmcnt(0)
	v_mul_f32_e32 v98, v230, v98
	v_fmac_f32_e32 v98, v106, v222
	v_cndmask_b32_e64 v106, v106, v98, s[38:39]
	v_mul_f32_e32 v99, v231, v99
	v_fmac_f32_e32 v99, v107, v223
	v_cndmask_b32_e64 v107, v107, v99, s[38:39]
	v_mul_f32_e32 v100, v232, v100
	v_fmac_f32_e32 v100, v108, v224
	v_cndmask_b32_e64 v108, v108, v100, s[38:39]
	v_mul_f32_e32 v101, v233, v101
	v_fmac_f32_e32 v101, v109, v225
	v_cndmask_b32_e64 v109, v109, v101, s[38:39]
	v_pk_mul_f32 v[110:111], v[110:111], s[30:31] op_sel_hi:[1,0]
	v_pk_mul_f32 v[112:113], v[112:113], s[30:31] op_sel_hi:[1,0]
	v_pk_mul_f32 v[106:107], v[106:107], s[30:31] op_sel_hi:[1,0]
	v_pk_mul_f32 v[108:109], v[108:109], s[30:31] op_sel_hi:[1,0]
	v_cvt_pk_bf16_f32 v110, v110, v111
	v_cvt_pk_bf16_f32 v111, v112, v113
	v_cvt_pk_bf16_f32 v112, v106, v107
	v_cvt_pk_bf16_f32 v113, v108, v109
	s_mov_b32 s100, s98
	s_mov_b32 s101, s99
	global_store_dwordx4 v200, v[122:125], s[100:101] nt
	s_add_u32 s100, s100, s67
	s_addc_u32 s101, s101, 0
	global_store_dwordx4 v200, v[114:117], s[100:101] nt
	ds_write_b128 v178, v[110:113]
	ds_write_b128 v178, v[102:105] offset:64
	ds_read_b128 v[106:109], v180
	ds_read_b128 v[98:101], v180 offset:1152
	s_add_i32 s44, s19, 48
	s_and_b32 s44, s44, 0xfff
	v_or_b32_e32 v0, s44, v141
	v_lshlrev_b32_e32 v0, 6, v0
	s_mov_b64 s[44:45], exec
	s_and_b64 exec, exec, s[38:39]
	global_load_dwordx4 v[218:221], v0, s[62:63]
	global_load_dwordx4 v[222:225], v0, s[62:63] offset:16
	global_load_dwordx4 v[226:229], v0, s[62:63] offset:32
	global_load_dwordx4 v[230:233], v0, s[62:63] offset:48
	s_mov_b64 exec, s[44:45]
	v_pk_mul_f32 v[86:87], v[86:87], v[150:151] op_sel_hi:[1,0]
	v_pk_mul_f32 v[88:89], v[88:89], v[150:151] op_sel_hi:[1,0]
	v_pk_mul_f32 v[82:83], v[82:83], v[150:151] op_sel_hi:[1,0]
	v_pk_mul_f32 v[84:85], v[84:85], v[150:151] op_sel_hi:[1,0]
	v_pk_mul_f32 v[86:87], v[86:87], s[30:31] op_sel_hi:[1,0]
	v_pk_mul_f32 v[88:89], v[88:89], s[30:31] op_sel_hi:[1,0]
	v_pk_mul_f32 v[82:83], v[82:83], s[30:31] op_sel_hi:[1,0]
	v_pk_mul_f32 v[84:85], v[84:85], s[30:31] op_sel_hi:[1,0]
	v_cvt_pk_bf16_f32 v86, v86, v87
	v_cvt_pk_bf16_f32 v87, v88, v89
	v_cvt_pk_bf16_f32 v88, v82, v83
	v_cvt_pk_bf16_f32 v89, v84, v85
	v_pk_mul_f32 v[94:95], v[94:95], v[150:151] op_sel_hi:[1,0]
	v_pk_mul_f32 v[96:97], v[96:97], v[150:151] op_sel_hi:[1,0]
	v_pk_mul_f32 v[90:91], v[90:91], v[150:151] op_sel_hi:[1,0]
	v_pk_mul_f32 v[92:93], v[92:93], v[150:151] op_sel_hi:[1,0]
	ds_swizzle_b32 v82, v94 offset:0x401f
	ds_swizzle_b32 v83, v95 offset:0x401f
	ds_swizzle_b32 v84, v96 offset:0x401f
	ds_swizzle_b32 v85, v97 offset:0x401f
	s_waitcnt vmcnt(6)
	v_xor_b32_e32 v162, v201, v162
	v_xor_b32_e32 v163, v201, v163
	v_xor_b32_e32 v164, v201, v164
	v_xor_b32_e32 v165, v201, v165
	v_xor_b32_e32 v166, v201, v166
	v_xor_b32_e32 v167, v201, v167
	v_xor_b32_e32 v168, v201, v168
	v_xor_b32_e32 v169, v201, v169
	s_waitcnt lgkmcnt(0)
	v_mul_f32_e32 v82, v162, v82
	v_fmac_f32_e32 v82, v94, v154
	v_cndmask_b32_e64 v94, v94, v82, s[38:39]
	v_mul_f32_e32 v83, v163, v83
	v_fmac_f32_e32 v83, v95, v155
	v_cndmask_b32_e64 v95, v95, v83, s[38:39]
	v_mul_f32_e32 v84, v164, v84
	v_fmac_f32_e32 v84, v96, v156
	v_cndmask_b32_e64 v96, v96, v84, s[38:39]
	v_mul_f32_e32 v85, v165, v85
	v_fmac_f32_e32 v85, v97, v157
	v_cndmask_b32_e64 v97, v97, v85, s[38:39]
	ds_swizzle_b32 v82, v90 offset:0x401f
	ds_swizzle_b32 v83, v91 offset:0x401f
	ds_swizzle_b32 v84, v92 offset:0x401f
	ds_swizzle_b32 v85, v93 offset:0x401f
	s_waitcnt lgkmcnt(0)
	v_mul_f32_e32 v82, v166, v82
	v_fmac_f32_e32 v82, v90, v158
	v_cndmask_b32_e64 v90, v90, v82, s[38:39]
	v_mul_f32_e32 v83, v167, v83
	v_fmac_f32_e32 v83, v91, v159
	v_cndmask_b32_e64 v91, v91, v83, s[38:39]
	v_mul_f32_e32 v84, v168, v84
	v_fmac_f32_e32 v84, v92, v160
	v_cndmask_b32_e64 v92, v92, v84, s[38:39]
	v_mul_f32_e32 v85, v169, v85
	v_fmac_f32_e32 v85, v93, v161
	v_cndmask_b32_e64 v93, v93, v85, s[38:39]
	v_pk_mul_f32 v[94:95], v[94:95], s[30:31] op_sel_hi:[1,0]
	v_pk_mul_f32 v[96:97], v[96:97], s[30:31] op_sel_hi:[1,0]
	v_pk_mul_f32 v[90:91], v[90:91], s[30:31] op_sel_hi:[1,0]
	v_pk_mul_f32 v[92:93], v[92:93], s[30:31] op_sel_hi:[1,0]
	v_cvt_pk_bf16_f32 v94, v94, v95
	v_cvt_pk_bf16_f32 v95, v96, v97
	v_cvt_pk_bf16_f32 v96, v90, v91
	v_cvt_pk_bf16_f32 v97, v92, v93
	s_mul_i32 s44, s66, 16
	s_add_u32 s100, s98, s44
	s_addc_u32 s101, s99, 0
	global_store_dwordx4 v200, v[106:109], s[100:101] nt
	s_add_u32 s100, s100, s67
	s_addc_u32 s101, s101, 0
	global_store_dwordx4 v200, v[98:101], s[100:101] nt
	ds_write_b128 v178, v[94:97]
	ds_write_b128 v178, v[86:89] offset:64
	ds_read_b128 v[90:93], v180
	ds_read_b128 v[82:85], v180 offset:1152
	s_add_i32 s44, s19, 128
	s_and_b32 s44, s44, 0xfff
	v_or_b32_e32 v0, s44, v141
	v_lshlrev_b32_e32 v0, 6, v0
	s_mov_b64 s[44:45], exec
	s_and_b64 exec, exec, s[38:39]
	global_load_dwordx4 v[154:157], v0, s[62:63]
	global_load_dwordx4 v[158:161], v0, s[62:63] offset:16
	global_load_dwordx4 v[162:165], v0, s[62:63] offset:32
	global_load_dwordx4 v[166:169], v0, s[62:63] offset:48
	s_mov_b64 exec, s[44:45]
	v_pk_mul_f32 v[70:71], v[70:71], v[150:151] op_sel:[0,1]
	v_pk_mul_f32 v[72:73], v[72:73], v[150:151] op_sel:[0,1]
	v_pk_mul_f32 v[66:67], v[66:67], v[150:151] op_sel:[0,1]
	v_pk_mul_f32 v[68:69], v[68:69], v[150:151] op_sel:[0,1]
	v_pk_mul_f32 v[70:71], v[70:71], s[30:31] op_sel_hi:[1,0]
	v_pk_mul_f32 v[72:73], v[72:73], s[30:31] op_sel_hi:[1,0]
	v_pk_mul_f32 v[66:67], v[66:67], s[30:31] op_sel_hi:[1,0]
	v_pk_mul_f32 v[68:69], v[68:69], s[30:31] op_sel_hi:[1,0]
	v_cvt_pk_bf16_f32 v70, v70, v71
	v_cvt_pk_bf16_f32 v71, v72, v73
	v_cvt_pk_bf16_f32 v72, v66, v67
	v_cvt_pk_bf16_f32 v73, v68, v69
	v_pk_mul_f32 v[78:79], v[78:79], v[150:151] op_sel:[0,1]
	v_pk_mul_f32 v[80:81], v[80:81], v[150:151] op_sel:[0,1]
	v_pk_mul_f32 v[74:75], v[74:75], v[150:151] op_sel:[0,1]
	v_pk_mul_f32 v[76:77], v[76:77], v[150:151] op_sel:[0,1]
	ds_swizzle_b32 v66, v78 offset:0x401f
	ds_swizzle_b32 v67, v79 offset:0x401f
	ds_swizzle_b32 v68, v80 offset:0x401f
	ds_swizzle_b32 v69, v81 offset:0x401f
	s_waitcnt vmcnt(6)
;     __device__ __forceinline__ void operator()(const f32x4 (&acc)[2][2][4][2], const Unit& u, int wr, int wc, int fr, int fq, PG8_LAS float* stash, int par, PG8_LAS unsigned char* stg, const Unit& un) const {
;     ...
;                 const int row = u.pm * BM + ai * HALF + wr * 64 + m * 16 + fr, pos = row & 4095, b = row >> 12;
;                 const float rs = rsa[ai][m];
; #pragma unroll
;                 for (int bj = 0; bj < 2; ++bj) {
;                     int kind;
;                     if (odd) kind = (u.pn < 6) ? 0 : (u.pn == 6 ? 1 : 2);
;                     else     kind = (u.pn < 2) ? 0 : (u.pn == 2 ? (wc < 2 ? 1 : 2) : 3);
;                     float v[8];
; #pragma unroll
;                     for (int i = 0; i < 4; ++i) { v[i] = acc[ai][bj][m][0][i] * rs; v[4 + i] = acc[ai][bj][m][1][i] * rs; }
;                     if (kind <= 1 && bj == 0) {
;                         const f32x4 c0 = *(const f32x4*)(cs + pos * 16), c1 = *(const f32x4*)(cs + pos * 16 + 4), s0 = *(const f32x4*)(cs + pos * 16 + 8), s1 = *(const f32x4*)(cs + pos * 16 + 12);
; #pragma unroll
;                         for (int i = 0; i < 8; ++i) {
;                             const float c = i < 4 ? c0[i & 3] : c1[i & 3], s = i < 4 ? s0[i & 3] : s1[i & 3];
;                             const float pr = peer_x16(v[i], fq);
;                             const float r = (fq == 0) ? (v[i] * c - pr * s) : (v[i] * c + pr * s);
;                             v[i] = (fq < 2) ? r : v[i];
;                         }
;                     }
;                     if (kind == 0) {
; #pragma unroll
;                         for (int i = 0; i < 8; ++i) v[i] *= C2Q;
;                     }
;                     { u32x4 w; w.x = cvt_pk_bf16(v[0], v[1]); w.y = cvt_pk_bf16(v[2], v[3]); w.z = cvt_pk_bf16(v[4], v[5]); w.w = cvt_pk_bf16(v[6], v[7]);
;                       *(PG8_LAS u32x4*)(stg + fr * 144 + fq * 16 + bj * 64) = w; }
;                 }
;                 {
;                     int kind;
;                     if (odd) kind = (u.pn < 6) ? 0 : (u.pn == 6 ? 1 : 2);
;                     else     kind = (u.pn < 2) ? 0 : (u.pn == 2 ? (wc < 2 ? 1 : 2) : 3);
; #pragma unroll
;                     for (int i = 0; i < 2; ++i) { const int c = fq * 16 + fr + 64 * i, rr = c >> 3, pc = c & 7;
;                         const u32x4 w = *(const PG8_LAS u32x4*)(stg + rr * 144 + pc * 16);
	v_xor_b32_e32 v226, v201, v226
	v_xor_b32_e32 v227, v201, v227
	v_xor_b32_e32 v228, v201, v228
	v_xor_b32_e32 v229, v201, v229
	v_xor_b32_e32 v230, v201, v230
	v_xor_b32_e32 v231, v201, v231
	v_xor_b32_e32 v232, v201, v232
	v_xor_b32_e32 v233, v201, v233
	s_waitcnt lgkmcnt(0)
	v_mul_f32_e32 v66, v226, v66
	v_fmac_f32_e32 v66, v78, v218
	v_cndmask_b32_e64 v78, v78, v66, s[38:39]
	v_mul_f32_e32 v67, v227, v67
	v_fmac_f32_e32 v67, v79, v219
	v_cndmask_b32_e64 v79, v79, v67, s[38:39]
	v_mul_f32_e32 v68, v228, v68
	v_fmac_f32_e32 v68, v80, v220
	v_cndmask_b32_e64 v80, v80, v68, s[38:39]
	v_mul_f32_e32 v69, v229, v69
	v_fmac_f32_e32 v69, v81, v221
	v_cndmask_b32_e64 v81, v81, v69, s[38:39]
	ds_swizzle_b32 v66, v74 offset:0x401f
	ds_swizzle_b32 v67, v75 offset:0x401f
	ds_swizzle_b32 v68, v76 offset:0x401f
	ds_swizzle_b32 v69, v77 offset:0x401f
	s_waitcnt lgkmcnt(0)
	v_mul_f32_e32 v66, v230, v66
	v_fmac_f32_e32 v66, v74, v222
	v_cndmask_b32_e64 v74, v74, v66, s[38:39]
	v_mul_f32_e32 v67, v231, v67
	v_fmac_f32_e32 v67, v75, v223
	v_cndmask_b32_e64 v75, v75, v67, s[38:39]
	v_mul_f32_e32 v68, v232, v68
	v_fmac_f32_e32 v68, v76, v224
	v_cndmask_b32_e64 v76, v76, v68, s[38:39]
	v_mul_f32_e32 v69, v233, v69
	v_fmac_f32_e32 v69, v77, v225
	v_cndmask_b32_e64 v77, v77, v69, s[38:39]
	v_pk_mul_f32 v[78:79], v[78:79], s[30:31] op_sel_hi:[1,0]
	v_pk_mul_f32 v[80:81], v[80:81], s[30:31] op_sel_hi:[1,0]
	v_pk_mul_f32 v[74:75], v[74:75], s[30:31] op_sel_hi:[1,0]
	v_pk_mul_f32 v[76:77], v[76:77], s[30:31] op_sel_hi:[1,0]
	v_cvt_pk_bf16_f32 v78, v78, v79
	v_cvt_pk_bf16_f32 v79, v80, v81
	v_cvt_pk_bf16_f32 v80, v74, v75
	v_cvt_pk_bf16_f32 v81, v76, v77
	s_mul_i32 s44, s66, 32
	s_add_u32 s100, s98, s44
	s_addc_u32 s101, s99, 0
	global_store_dwordx4 v200, v[90:93], s[100:101] nt
	s_add_u32 s100, s100, s67
	s_addc_u32 s101, s101, 0
	global_store_dwordx4 v200, v[82:85], s[100:101] nt
	ds_write_b128 v178, v[78:81]
	ds_write_b128 v178, v[70:73] offset:64
	ds_read_b128 v[74:77], v180
	ds_read_b128 v[66:69], v180 offset:1152
	s_add_i32 s44, s19, 144
	s_and_b32 s44, s44, 0xfff
	v_or_b32_e32 v0, s44, v141
	v_lshlrev_b32_e32 v0, 6, v0
	s_mov_b64 s[44:45], exec
	s_and_b64 exec, exec, s[38:39]
	global_load_dwordx4 v[218:221], v0, s[62:63]
	global_load_dwordx4 v[222:225], v0, s[62:63] offset:16
	global_load_dwordx4 v[226:229], v0, s[62:63] offset:32
	global_load_dwordx4 v[230:233], v0, s[62:63] offset:48
	s_mov_b64 exec, s[44:45]
	v_pk_mul_f32 v[54:55], v[54:55], v[148:149] op_sel_hi:[1,0]
	v_pk_mul_f32 v[56:57], v[56:57], v[148:149] op_sel_hi:[1,0]
	v_pk_mul_f32 v[50:51], v[50:51], v[148:149] op_sel_hi:[1,0]
	v_pk_mul_f32 v[52:53], v[52:53], v[148:149] op_sel_hi:[1,0]
	v_pk_mul_f32 v[54:55], v[54:55], s[30:31] op_sel_hi:[1,0]
	v_pk_mul_f32 v[56:57], v[56:57], s[30:31] op_sel_hi:[1,0]
	v_pk_mul_f32 v[50:51], v[50:51], s[30:31] op_sel_hi:[1,0]
	v_pk_mul_f32 v[52:53], v[52:53], s[30:31] op_sel_hi:[1,0]
	v_cvt_pk_bf16_f32 v54, v54, v55
	v_cvt_pk_bf16_f32 v55, v56, v57
	v_cvt_pk_bf16_f32 v56, v50, v51
	v_cvt_pk_bf16_f32 v57, v52, v53
	v_pk_mul_f32 v[62:63], v[62:63], v[148:149] op_sel_hi:[1,0]
	v_pk_mul_f32 v[64:65], v[64:65], v[148:149] op_sel_hi:[1,0]
	v_pk_mul_f32 v[58:59], v[58:59], v[148:149] op_sel_hi:[1,0]
	v_pk_mul_f32 v[60:61], v[60:61], v[148:149] op_sel_hi:[1,0]
	ds_swizzle_b32 v50, v62 offset:0x401f
	ds_swizzle_b32 v51, v63 offset:0x401f
	ds_swizzle_b32 v52, v64 offset:0x401f
	ds_swizzle_b32 v53, v65 offset:0x401f
	s_waitcnt vmcnt(6)
	v_xor_b32_e32 v162, v201, v162
	v_xor_b32_e32 v163, v201, v163
	v_xor_b32_e32 v164, v201, v164
	v_xor_b32_e32 v165, v201, v165
	v_xor_b32_e32 v166, v201, v166
	v_xor_b32_e32 v167, v201, v167
	v_xor_b32_e32 v168, v201, v168
	v_xor_b32_e32 v169, v201, v169
	s_waitcnt lgkmcnt(0)
	v_mul_f32_e32 v50, v162, v50
	v_fmac_f32_e32 v50, v62, v154
	v_cndmask_b32_e64 v62, v62, v50, s[38:39]
	v_mul_f32_e32 v51, v163, v51
	v_fmac_f32_e32 v51, v63, v155
	v_cndmask_b32_e64 v63, v63, v51, s[38:39]
	v_mul_f32_e32 v52, v164, v52
	v_fmac_f32_e32 v52, v64, v156
	v_cndmask_b32_e64 v64, v64, v52, s[38:39]
	v_mul_f32_e32 v53, v165, v53
	v_fmac_f32_e32 v53, v65, v157
	v_cndmask_b32_e64 v65, v65, v53, s[38:39]
	ds_swizzle_b32 v50, v58 offset:0x401f
	ds_swizzle_b32 v51, v59 offset:0x401f
	ds_swizzle_b32 v52, v60 offset:0x401f
	ds_swizzle_b32 v53, v61 offset:0x401f
	s_waitcnt lgkmcnt(0)
	v_mul_f32_e32 v50, v166, v50
	v_fmac_f32_e32 v50, v58, v158
	v_cndmask_b32_e64 v58, v58, v50, s[38:39]
	v_mul_f32_e32 v51, v167, v51
	v_fmac_f32_e32 v51, v59, v159
	v_cndmask_b32_e64 v59, v59, v51, s[38:39]
	v_mul_f32_e32 v52, v168, v52
	v_fmac_f32_e32 v52, v60, v160
	v_cndmask_b32_e64 v60, v60, v52, s[38:39]
	v_mul_f32_e32 v53, v169, v53
	v_fmac_f32_e32 v53, v61, v161
	v_cndmask_b32_e64 v61, v61, v53, s[38:39]
	v_pk_mul_f32 v[62:63], v[62:63], s[30:31] op_sel_hi:[1,0]
	v_pk_mul_f32 v[64:65], v[64:65], s[30:31] op_sel_hi:[1,0]
	v_pk_mul_f32 v[58:59], v[58:59], s[30:31] op_sel_hi:[1,0]
	v_pk_mul_f32 v[60:61], v[60:61], s[30:31] op_sel_hi:[1,0]
	v_cvt_pk_bf16_f32 v62, v62, v63
	v_cvt_pk_bf16_f32 v63, v64, v65
	v_cvt_pk_bf16_f32 v64, v58, v59
	v_cvt_pk_bf16_f32 v65, v60, v61
	s_mul_i32 s44, s66, 48
	s_add_u32 s100, s98, s44
	s_addc_u32 s101, s99, 0
	global_store_dwordx4 v200, v[74:77], s[100:101] nt
	s_add_u32 s100, s100, s67
	s_addc_u32 s101, s101, 0
	global_store_dwordx4 v200, v[66:69], s[100:101] nt
	ds_write_b128 v178, v[62:65]
	ds_write_b128 v178, v[54:57] offset:64
	ds_read_b128 v[58:61], v180
	ds_read_b128 v[50:53], v180 offset:1152
	s_add_i32 s44, s19, 160
	s_and_b32 s44, s44, 0xfff
	v_or_b32_e32 v0, s44, v141
	v_lshlrev_b32_e32 v0, 6, v0
	s_mov_b64 s[44:45], exec
	s_and_b64 exec, exec, s[38:39]
	global_load_dwordx4 v[154:157], v0, s[62:63]
	global_load_dwordx4 v[158:161], v0, s[62:63] offset:16
	global_load_dwordx4 v[162:165], v0, s[62:63] offset:32
	global_load_dwordx4 v[166:169], v0, s[62:63] offset:48
	s_mov_b64 exec, s[44:45]
	v_pk_mul_f32 v[38:39], v[38:39], v[148:149] op_sel:[0,1]
	v_pk_mul_f32 v[40:41], v[40:41], v[148:149] op_sel:[0,1]
	v_pk_mul_f32 v[34:35], v[34:35], v[148:149] op_sel:[0,1]
	v_pk_mul_f32 v[36:37], v[36:37], v[148:149] op_sel:[0,1]
	v_pk_mul_f32 v[38:39], v[38:39], s[30:31] op_sel_hi:[1,0]
	v_pk_mul_f32 v[40:41], v[40:41], s[30:31] op_sel_hi:[1,0]
	v_pk_mul_f32 v[34:35], v[34:35], s[30:31] op_sel_hi:[1,0]
	v_pk_mul_f32 v[36:37], v[36:37], s[30:31] op_sel_hi:[1,0]
	v_cvt_pk_bf16_f32 v38, v38, v39
	v_cvt_pk_bf16_f32 v39, v40, v41
	v_cvt_pk_bf16_f32 v40, v34, v35
	v_cvt_pk_bf16_f32 v41, v36, v37
	v_pk_mul_f32 v[46:47], v[46:47], v[148:149] op_sel:[0,1]
	v_pk_mul_f32 v[48:49], v[48:49], v[148:149] op_sel:[0,1]
	v_pk_mul_f32 v[42:43], v[42:43], v[148:149] op_sel:[0,1]
	v_pk_mul_f32 v[44:45], v[44:45], v[148:149] op_sel:[0,1]
	ds_swizzle_b32 v34, v46 offset:0x401f
	ds_swizzle_b32 v35, v47 offset:0x401f
	ds_swizzle_b32 v36, v48 offset:0x401f
	ds_swizzle_b32 v37, v49 offset:0x401f
	s_waitcnt vmcnt(6)
;     __device__ __forceinline__ void operator()(const f32x4 (&acc)[2][2][4][2], const Unit& u, int wr, int wc, int fr, int fq, PG8_LAS float* stash, int par, PG8_LAS unsigned char* stg, const Unit& un) const {
;     ...
;                 const int row = u.pm * BM + ai * HALF + wr * 64 + m * 16 + fr, pos = row & 4095, b = row >> 12;
;                 const float rs = rsa[ai][m];
; #pragma unroll
;                 for (int bj = 0; bj < 2; ++bj) {
;                     int kind;
;                     if (odd) kind = (u.pn < 6) ? 0 : (u.pn == 6 ? 1 : 2);
;                     else     kind = (u.pn < 2) ? 0 : (u.pn == 2 ? (wc < 2 ? 1 : 2) : 3);
;                     float v[8];
; #pragma unroll
;                     for (int i = 0; i < 4; ++i) { v[i] = acc[ai][bj][m][0][i] * rs; v[4 + i] = acc[ai][bj][m][1][i] * rs; }
;                     if (kind <= 1 && bj == 0) {
;                         const f32x4 c0 = *(const f32x4*)(cs + pos * 16), c1 = *(const f32x4*)(cs + pos * 16 + 4), s0 = *(const f32x4*)(cs + pos * 16 + 8), s1 = *(const f32x4*)(cs + pos * 16 + 12);
; #pragma unroll
;                         for (int i = 0; i < 8; ++i) {
;                             const float c = i < 4 ? c0[i & 3] : c1[i & 3], s = i < 4 ? s0[i & 3] : s1[i & 3];
;                             const float pr = peer_x16(v[i], fq);
;                             const float r = (fq == 0) ? (v[i] * c - pr * s) : (v[i] * c + pr * s);
;                             v[i] = (fq < 2) ? r : v[i];
;                         }
;                     }
;                     if (kind == 0) {
; #pragma unroll
;                         for (int i = 0; i < 8; ++i) v[i] *= C2Q;
;                     }
;                     { u32x4 w; w.x = cvt_pk_bf16(v[0], v[1]); w.y = cvt_pk_bf16(v[2], v[3]); w.z = cvt_pk_bf16(v[4], v[5]); w.w = cvt_pk_bf16(v[6], v[7]);
;                       *(PG8_LAS u32x4*)(stg + fr * 144 + fq * 16 + bj * 64) = w; }
;                 }
;                 {
;                     int kind;
;                     if (odd) kind = (u.pn < 6) ? 0 : (u.pn == 6 ? 1 : 2);
;                     else     kind = (u.pn < 2) ? 0 : (u.pn == 2 ? (wc < 2 ? 1 : 2) : 3);
; #pragma unroll
;                     for (int i = 0; i < 2; ++i) { const int c = fq * 16 + fr + 64 * i, rr = c >> 3, pc = c & 7;
;                         const u32x4 w = *(const PG8_LAS u32x4*)(stg + rr * 144 + pc * 16);
	v_xor_b32_e32 v226, v201, v226
	v_xor_b32_e32 v227, v201, v227
	v_xor_b32_e32 v228, v201, v228
	v_xor_b32_e32 v229, v201, v229
	v_xor_b32_e32 v230, v201, v230
	v_xor_b32_e32 v231, v201, v231
	v_xor_b32_e32 v232, v201, v232
	v_xor_b32_e32 v233, v201, v233
	s_waitcnt lgkmcnt(0)
	v_mul_f32_e32 v34, v226, v34
	v_fmac_f32_e32 v34, v46, v218
	v_cndmask_b32_e64 v46, v46, v34, s[38:39]
	v_mul_f32_e32 v35, v227, v35
	v_fmac_f32_e32 v35, v47, v219
	v_cndmask_b32_e64 v47, v47, v35, s[38:39]
	v_mul_f32_e32 v36, v228, v36
	v_fmac_f32_e32 v36, v48, v220
	v_cndmask_b32_e64 v48, v48, v36, s[38:39]
	v_mul_f32_e32 v37, v229, v37
	v_fmac_f32_e32 v37, v49, v221
	v_cndmask_b32_e64 v49, v49, v37, s[38:39]
	ds_swizzle_b32 v34, v42 offset:0x401f
	ds_swizzle_b32 v35, v43 offset:0x401f
	ds_swizzle_b32 v36, v44 offset:0x401f
	ds_swizzle_b32 v37, v45 offset:0x401f
	s_waitcnt lgkmcnt(0)
	v_mul_f32_e32 v34, v230, v34
	v_fmac_f32_e32 v34, v42, v222
	v_cndmask_b32_e64 v42, v42, v34, s[38:39]
	v_mul_f32_e32 v35, v231, v35
	v_fmac_f32_e32 v35, v43, v223
	v_cndmask_b32_e64 v43, v43, v35, s[38:39]
	v_mul_f32_e32 v36, v232, v36
	v_fmac_f32_e32 v36, v44, v224
	v_cndmask_b32_e64 v44, v44, v36, s[38:39]
	v_mul_f32_e32 v37, v233, v37
	v_fmac_f32_e32 v37, v45, v225
	v_cndmask_b32_e64 v45, v45, v37, s[38:39]
	v_pk_mul_f32 v[46:47], v[46:47], s[30:31] op_sel_hi:[1,0]
	v_pk_mul_f32 v[48:49], v[48:49], s[30:31] op_sel_hi:[1,0]
	v_pk_mul_f32 v[42:43], v[42:43], s[30:31] op_sel_hi:[1,0]
	v_pk_mul_f32 v[44:45], v[44:45], s[30:31] op_sel_hi:[1,0]
	v_cvt_pk_bf16_f32 v46, v46, v47
	v_cvt_pk_bf16_f32 v47, v48, v49
	v_cvt_pk_bf16_f32 v48, v42, v43
	v_cvt_pk_bf16_f32 v49, v44, v45
	s_mul_i32 s44, s66, 128
	s_add_u32 s100, s98, s44
	s_addc_u32 s101, s99, 0
	global_store_dwordx4 v200, v[58:61], s[100:101] nt
	s_add_u32 s100, s100, s67
	s_addc_u32 s101, s101, 0
	global_store_dwordx4 v200, v[50:53], s[100:101] nt
	ds_write_b128 v178, v[46:49]
	ds_write_b128 v178, v[38:41] offset:64
	ds_read_b128 v[42:45], v180
	ds_read_b128 v[34:37], v180 offset:1152
	s_add_i32 s44, s19, 176
	s_and_b32 s44, s44, 0xfff
	v_or_b32_e32 v0, s44, v141
	v_lshlrev_b32_e32 v0, 6, v0
	s_mov_b64 s[44:45], exec
	s_and_b64 exec, exec, s[38:39]
	global_load_dwordx4 v[218:221], v0, s[62:63]
	global_load_dwordx4 v[222:225], v0, s[62:63] offset:16
	global_load_dwordx4 v[226:229], v0, s[62:63] offset:32
	global_load_dwordx4 v[230:233], v0, s[62:63] offset:48
	s_mov_b64 exec, s[44:45]
	v_pk_mul_f32 v[22:23], v[22:23], v[146:147] op_sel_hi:[1,0]
	v_pk_mul_f32 v[24:25], v[24:25], v[146:147] op_sel_hi:[1,0]
	v_pk_mul_f32 v[18:19], v[18:19], v[146:147] op_sel_hi:[1,0]
	v_pk_mul_f32 v[20:21], v[20:21], v[146:147] op_sel_hi:[1,0]
	v_pk_mul_f32 v[22:23], v[22:23], s[30:31] op_sel_hi:[1,0]
	v_pk_mul_f32 v[24:25], v[24:25], s[30:31] op_sel_hi:[1,0]
	v_pk_mul_f32 v[18:19], v[18:19], s[30:31] op_sel_hi:[1,0]
	v_pk_mul_f32 v[20:21], v[20:21], s[30:31] op_sel_hi:[1,0]
	v_cvt_pk_bf16_f32 v22, v22, v23
	v_cvt_pk_bf16_f32 v23, v24, v25
	v_cvt_pk_bf16_f32 v24, v18, v19
	v_cvt_pk_bf16_f32 v25, v20, v21
	v_pk_mul_f32 v[30:31], v[30:31], v[146:147] op_sel_hi:[1,0]
	v_pk_mul_f32 v[32:33], v[32:33], v[146:147] op_sel_hi:[1,0]
	v_pk_mul_f32 v[26:27], v[26:27], v[146:147] op_sel_hi:[1,0]
	v_pk_mul_f32 v[28:29], v[28:29], v[146:147] op_sel_hi:[1,0]
	ds_swizzle_b32 v18, v30 offset:0x401f
	ds_swizzle_b32 v19, v31 offset:0x401f
	ds_swizzle_b32 v20, v32 offset:0x401f
	ds_swizzle_b32 v21, v33 offset:0x401f
	s_waitcnt vmcnt(6)
	v_xor_b32_e32 v162, v201, v162
	v_xor_b32_e32 v163, v201, v163
	v_xor_b32_e32 v164, v201, v164
	v_xor_b32_e32 v165, v201, v165
	v_xor_b32_e32 v166, v201, v166
	v_xor_b32_e32 v167, v201, v167
	v_xor_b32_e32 v168, v201, v168
	v_xor_b32_e32 v169, v201, v169
	s_waitcnt lgkmcnt(0)
	v_mul_f32_e32 v18, v162, v18
	v_fmac_f32_e32 v18, v30, v154
	v_cndmask_b32_e64 v30, v30, v18, s[38:39]
	v_mul_f32_e32 v19, v163, v19
	v_fmac_f32_e32 v19, v31, v155
	v_cndmask_b32_e64 v31, v31, v19, s[38:39]
	v_mul_f32_e32 v20, v164, v20
	v_fmac_f32_e32 v20, v32, v156
	v_cndmask_b32_e64 v32, v32, v20, s[38:39]
	v_mul_f32_e32 v21, v165, v21
	v_fmac_f32_e32 v21, v33, v157
	v_cndmask_b32_e64 v33, v33, v21, s[38:39]
	ds_swizzle_b32 v18, v26 offset:0x401f
	ds_swizzle_b32 v19, v27 offset:0x401f
	ds_swizzle_b32 v20, v28 offset:0x401f
	ds_swizzle_b32 v21, v29 offset:0x401f
	s_waitcnt lgkmcnt(0)
	v_mul_f32_e32 v18, v166, v18
	v_fmac_f32_e32 v18, v26, v158
	v_cndmask_b32_e64 v26, v26, v18, s[38:39]
	v_mul_f32_e32 v19, v167, v19
	v_fmac_f32_e32 v19, v27, v159
	v_cndmask_b32_e64 v27, v27, v19, s[38:39]
	v_mul_f32_e32 v20, v168, v20
	v_fmac_f32_e32 v20, v28, v160
	v_cndmask_b32_e64 v28, v28, v20, s[38:39]
	v_mul_f32_e32 v21, v169, v21
	v_fmac_f32_e32 v21, v29, v161
	v_cndmask_b32_e64 v29, v29, v21, s[38:39]
	v_pk_mul_f32 v[30:31], v[30:31], s[30:31] op_sel_hi:[1,0]
	v_pk_mul_f32 v[32:33], v[32:33], s[30:31] op_sel_hi:[1,0]
	v_pk_mul_f32 v[26:27], v[26:27], s[30:31] op_sel_hi:[1,0]
	v_pk_mul_f32 v[28:29], v[28:29], s[30:31] op_sel_hi:[1,0]
	v_cvt_pk_bf16_f32 v30, v30, v31
	v_cvt_pk_bf16_f32 v31, v32, v33
	v_cvt_pk_bf16_f32 v32, v26, v27
	v_cvt_pk_bf16_f32 v33, v28, v29
	s_mul_i32 s44, s66, 144
	s_add_u32 s100, s98, s44
	s_addc_u32 s101, s99, 0
	global_store_dwordx4 v200, v[42:45], s[100:101] nt
	s_add_u32 s100, s100, s67
	s_addc_u32 s101, s101, 0
	global_store_dwordx4 v200, v[34:37], s[100:101] nt
	ds_write_b128 v178, v[30:33]
	ds_write_b128 v178, v[22:25] offset:64
	ds_read_b128 v[26:29], v180
	ds_read_b128 v[18:21], v180 offset:1152
	v_pk_mul_f32 v[6:7], v[6:7], v[146:147] op_sel:[0,1]
	v_pk_mul_f32 v[8:9], v[8:9], v[146:147] op_sel:[0,1]
	v_pk_mul_f32 v[2:3], v[2:3], v[146:147] op_sel:[0,1]
	v_pk_mul_f32 v[4:5], v[4:5], v[146:147] op_sel:[0,1]
	v_pk_mul_f32 v[6:7], v[6:7], s[30:31] op_sel_hi:[1,0]
	v_pk_mul_f32 v[8:9], v[8:9], s[30:31] op_sel_hi:[1,0]
	v_pk_mul_f32 v[2:3], v[2:3], s[30:31] op_sel_hi:[1,0]
	v_pk_mul_f32 v[4:5], v[4:5], s[30:31] op_sel_hi:[1,0]
	v_cvt_pk_bf16_f32 v6, v6, v7
	v_cvt_pk_bf16_f32 v7, v8, v9
	v_cvt_pk_bf16_f32 v8, v2, v3
	v_cvt_pk_bf16_f32 v9, v4, v5
	v_pk_mul_f32 v[14:15], v[14:15], v[146:147] op_sel:[0,1]
	v_pk_mul_f32 v[16:17], v[16:17], v[146:147] op_sel:[0,1]
	v_pk_mul_f32 v[10:11], v[10:11], v[146:147] op_sel:[0,1]
	v_pk_mul_f32 v[12:13], v[12:13], v[146:147] op_sel:[0,1]
	ds_swizzle_b32 v2, v14 offset:0x401f
	ds_swizzle_b32 v3, v15 offset:0x401f
	ds_swizzle_b32 v4, v16 offset:0x401f
	ds_swizzle_b32 v5, v17 offset:0x401f
	s_waitcnt vmcnt(2)
;     __device__ __forceinline__ void operator()(const f32x4 (&acc)[2][2][4][2], const Unit& u, int wr, int wc, int fr, int fq, PG8_LAS float* stash, int par, PG8_LAS unsigned char* stg, const Unit& un) const {
;     ...
;                 const int row = u.pm * BM + ai * HALF + wr * 64 + m * 16 + fr, pos = row & 4095, b = row >> 12;
;                 const float rs = rsa[ai][m];
; #pragma unroll
;                 for (int bj = 0; bj < 2; ++bj) {
;                     int kind;
;                     if (odd) kind = (u.pn < 6) ? 0 : (u.pn == 6 ? 1 : 2);
;                     else     kind = (u.pn < 2) ? 0 : (u.pn == 2 ? (wc < 2 ? 1 : 2) : 3);
;                     float v[8];
; #pragma unroll
;                     for (int i = 0; i < 4; ++i) { v[i] = acc[ai][bj][m][0][i] * rs; v[4 + i] = acc[ai][bj][m][1][i] * rs; }
;                     if (kind <= 1 && bj == 0) {
;                         const f32x4 c0 = *(const f32x4*)(cs + pos * 16), c1 = *(const f32x4*)(cs + pos * 16 + 4), s0 = *(const f32x4*)(cs + pos * 16 + 8), s1 = *(const f32x4*)(cs + pos * 16 + 12);
; #pragma unroll
;                         for (int i = 0; i < 8; ++i) {
;                             const float c = i < 4 ? c0[i & 3] : c1[i & 3], s = i < 4 ? s0[i & 3] : s1[i & 3];
;                             const float pr = peer_x16(v[i], fq);
;                             const float r = (fq == 0) ? (v[i] * c - pr * s) : (v[i] * c + pr * s);
;                             v[i] = (fq < 2) ? r : v[i];
;                         }
;                     }
;                     if (kind == 0) {
; #pragma unroll
;                         for (int i = 0; i < 8; ++i) v[i] *= C2Q;
;                     }
;                     { u32x4 w; w.x = cvt_pk_bf16(v[0], v[1]); w.y = cvt_pk_bf16(v[2], v[3]); w.z = cvt_pk_bf16(v[4], v[5]); w.w = cvt_pk_bf16(v[6], v[7]);
;                       *(PG8_LAS u32x4*)(stg + fr * 144 + fq * 16 + bj * 64) = w; }
;                 }
;                 {
;                     int kind;
;                     if (odd) kind = (u.pn < 6) ? 0 : (u.pn == 6 ? 1 : 2);
;                     else     kind = (u.pn < 2) ? 0 : (u.pn == 2 ? (wc < 2 ? 1 : 2) : 3);
; #pragma unroll
;                     for (int i = 0; i < 2; ++i) { const int c = fq * 16 + fr + 64 * i, rr = c >> 3, pc = c & 7;
;                         const u32x4 w = *(const PG8_LAS u32x4*)(stg + rr * 144 + pc * 16);
	v_xor_b32_e32 v226, v201, v226
	v_xor_b32_e32 v227, v201, v227
	v_xor_b32_e32 v228, v201, v228
	v_xor_b32_e32 v229, v201, v229
	v_xor_b32_e32 v230, v201, v230
	v_xor_b32_e32 v231, v201, v231
	v_xor_b32_e32 v232, v201, v232
	v_xor_b32_e32 v233, v201, v233
	s_waitcnt lgkmcnt(0)
	v_mul_f32_e32 v2, v226, v2
	v_fmac_f32_e32 v2, v14, v218
	v_cndmask_b32_e64 v14, v14, v2, s[38:39]
	v_mul_f32_e32 v3, v227, v3
	v_fmac_f32_e32 v3, v15, v219
	v_cndmask_b32_e64 v15, v15, v3, s[38:39]
	v_mul_f32_e32 v4, v228, v4
	v_fmac_f32_e32 v4, v16, v220
	v_cndmask_b32_e64 v16, v16, v4, s[38:39]
	v_mul_f32_e32 v5, v229, v5
	v_fmac_f32_e32 v5, v17, v221
	v_cndmask_b32_e64 v17, v17, v5, s[38:39]
	ds_swizzle_b32 v2, v10 offset:0x401f
	ds_swizzle_b32 v3, v11 offset:0x401f
	ds_swizzle_b32 v4, v12 offset:0x401f
	ds_swizzle_b32 v5, v13 offset:0x401f
	s_waitcnt lgkmcnt(0)
	v_mul_f32_e32 v2, v230, v2
	v_fmac_f32_e32 v2, v10, v222
	v_cndmask_b32_e64 v10, v10, v2, s[38:39]
	v_mul_f32_e32 v3, v231, v3
	v_fmac_f32_e32 v3, v11, v223
	v_cndmask_b32_e64 v11, v11, v3, s[38:39]
	v_mul_f32_e32 v4, v232, v4
	v_fmac_f32_e32 v4, v12, v224
	v_cndmask_b32_e64 v12, v12, v4, s[38:39]
	v_mul_f32_e32 v5, v233, v5
	v_fmac_f32_e32 v5, v13, v225
	v_cndmask_b32_e64 v13, v13, v5, s[38:39]
	v_pk_mul_f32 v[14:15], v[14:15], s[30:31] op_sel_hi:[1,0]
	v_pk_mul_f32 v[16:17], v[16:17], s[30:31] op_sel_hi:[1,0]
	v_pk_mul_f32 v[10:11], v[10:11], s[30:31] op_sel_hi:[1,0]
	v_pk_mul_f32 v[12:13], v[12:13], s[30:31] op_sel_hi:[1,0]
	v_cvt_pk_bf16_f32 v14, v14, v15
	v_cvt_pk_bf16_f32 v15, v16, v17
	v_cvt_pk_bf16_f32 v16, v10, v11
	v_cvt_pk_bf16_f32 v17, v12, v13
	s_mul_i32 s44, s66, 160
	s_add_u32 s100, s98, s44
	s_addc_u32 s101, s99, 0
	global_store_dwordx4 v200, v[26:29], s[100:101] nt
	s_add_u32 s100, s100, s67
	s_addc_u32 s101, s101, 0
	global_store_dwordx4 v200, v[18:21], s[100:101] nt
	ds_write_b128 v178, v[14:17]
	ds_write_b128 v178, v[6:9] offset:64
	ds_read_b128 v[10:13], v180
	ds_read_b128 v[2:5], v180 offset:1152
	s_waitcnt lgkmcnt(0)
	s_mul_i32 s44, s66, 176
	s_add_u32 s100, s98, s44
	s_addc_u32 s101, s99, 0
	global_store_dwordx4 v200, v[10:13], s[100:101] nt
	s_add_u32 s100, s100, s67
	s_addc_u32 s101, s101, 0
	global_store_dwordx4 v200, v[2:5], s[100:101] nt
	s_branch .Lipe_done
.Lipe_K:
	s_add_i32 s44, s19, 0
	s_and_b32 s44, s44, 0xfff
	v_or_b32_e32 v0, s44, v141
	v_lshlrev_b32_e32 v0, 6, v0
	s_mov_b64 s[44:45], exec
	s_and_b64 exec, exec, s[38:39]
	global_load_dwordx4 v[154:157], v0, s[62:63]
	global_load_dwordx4 v[158:161], v0, s[62:63] offset:16
	global_load_dwordx4 v[162:165], v0, s[62:63] offset:32
	global_load_dwordx4 v[166:169], v0, s[62:63] offset:48
	s_mov_b64 exec, s[44:45]
	s_add_i32 s44, s19, 16
	s_and_b32 s44, s44, 0xfff
	v_or_b32_e32 v0, s44, v141
	v_lshlrev_b32_e32 v0, 6, v0
	s_mov_b64 s[44:45], exec
	s_and_b64 exec, exec, s[38:39]
	global_load_dwordx4 v[218:221], v0, s[62:63]
	global_load_dwordx4 v[222:225], v0, s[62:63] offset:16
	global_load_dwordx4 v[226:229], v0, s[62:63] offset:32
	global_load_dwordx4 v[230:233], v0, s[62:63] offset:48
	s_mov_b64 exec, s[44:45]
	v_pk_mul_f32 v[118:119], v[118:119], v[152:153] op_sel_hi:[1,0]
	v_pk_mul_f32 v[120:121], v[120:121], v[152:153] op_sel_hi:[1,0]
	v_pk_mul_f32 v[114:115], v[114:115], v[152:153] op_sel_hi:[1,0]
	v_pk_mul_f32 v[116:117], v[116:117], v[152:153] op_sel_hi:[1,0]
	v_cvt_pk_bf16_f32 v118, v118, v119
	v_cvt_pk_bf16_f32 v119, v120, v121
	v_cvt_pk_bf16_f32 v120, v114, v115
	v_cvt_pk_bf16_f32 v121, v116, v117
	v_pk_mul_f32 v[126:127], v[126:127], v[152:153] op_sel_hi:[1,0]
	v_pk_mul_f32 v[128:129], v[128:129], v[152:153] op_sel_hi:[1,0]
	v_pk_mul_f32 v[122:123], v[122:123], v[152:153] op_sel_hi:[1,0]
	v_pk_mul_f32 v[124:125], v[124:125], v[152:153] op_sel_hi:[1,0]
	ds_swizzle_b32 v114, v126 offset:0x401f
	ds_swizzle_b32 v115, v127 offset:0x401f
	ds_swizzle_b32 v116, v128 offset:0x401f
	ds_swizzle_b32 v117, v129 offset:0x401f
	s_waitcnt vmcnt(4)
	v_xor_b32_e32 v162, v201, v162
	v_xor_b32_e32 v163, v201, v163
	v_xor_b32_e32 v164, v201, v164
	v_xor_b32_e32 v165, v201, v165
	v_xor_b32_e32 v166, v201, v166
	v_xor_b32_e32 v167, v201, v167
	v_xor_b32_e32 v168, v201, v168
	v_xor_b32_e32 v169, v201, v169
	s_waitcnt lgkmcnt(0)
	v_mul_f32_e32 v114, v162, v114
	v_fmac_f32_e32 v114, v126, v154
	v_cndmask_b32_e64 v126, v126, v114, s[38:39]
	v_mul_f32_e32 v115, v163, v115
	v_fmac_f32_e32 v115, v127, v155
	v_cndmask_b32_e64 v127, v127, v115, s[38:39]
	v_mul_f32_e32 v116, v164, v116
	v_fmac_f32_e32 v116, v128, v156
	v_cndmask_b32_e64 v128, v128, v116, s[38:39]
	v_mul_f32_e32 v117, v165, v117
	v_fmac_f32_e32 v117, v129, v157
	v_cndmask_b32_e64 v129, v129, v117, s[38:39]
	ds_swizzle_b32 v114, v122 offset:0x401f
	ds_swizzle_b32 v115, v123 offset:0x401f
	ds_swizzle_b32 v116, v124 offset:0x401f
	ds_swizzle_b32 v117, v125 offset:0x401f
	s_waitcnt lgkmcnt(0)
	v_mul_f32_e32 v114, v166, v114
	v_fmac_f32_e32 v114, v122, v158
	v_cndmask_b32_e64 v122, v122, v114, s[38:39]
	v_mul_f32_e32 v115, v167, v115
	v_fmac_f32_e32 v115, v123, v159
	v_cndmask_b32_e64 v123, v123, v115, s[38:39]
	v_mul_f32_e32 v116, v168, v116
	v_fmac_f32_e32 v116, v124, v160
	v_cndmask_b32_e64 v124, v124, v116, s[38:39]
	v_mul_f32_e32 v117, v169, v117
	v_fmac_f32_e32 v117, v125, v161
	v_cndmask_b32_e64 v125, v125, v117, s[38:39]
	v_cvt_pk_bf16_f32 v126, v126, v127
	v_cvt_pk_bf16_f32 v127, v128, v129
	v_cvt_pk_bf16_f32 v128, v122, v123
	v_cvt_pk_bf16_f32 v129, v124, v125
	ds_write_b128 v178, v[126:129]
	ds_write_b128 v178, v[118:121] offset:64
	ds_read_b128 v[122:125], v180
	ds_read_b128 v[114:117], v180 offset:1152
	s_and_b64 vcc, exec, s[60:61]
	s_cbranch_vccz .Lalign_ipeK
	s_barrier
;     __device__ __forceinline__ void operator()(const f32x4 (&acc)[2][2][4][2], const Unit& u, int wr, int wc, int fr, int fq, PG8_LAS float* stash, int par, PG8_LAS unsigned char* stg, const Unit& un) const {
;     ...
;                 const int row = u.pm * BM + ai * HALF + wr * 64 + m * 16 + fr, pos = row & 4095, b = row >> 12;
;                 const float rs = rsa[ai][m];
; #pragma unroll
;                 for (int bj = 0; bj < 2; ++bj) {
;                     int kind;
;                     if (odd) kind = (u.pn < 6) ? 0 : (u.pn == 6 ? 1 : 2);
;                     else     kind = (u.pn < 2) ? 0 : (u.pn == 2 ? (wc < 2 ? 1 : 2) : 3);
;                     float v[8];
; #pragma unroll
;                     for (int i = 0; i < 4; ++i) { v[i] = acc[ai][bj][m][0][i] * rs; v[4 + i] = acc[ai][bj][m][1][i] * rs; }
;                     if (kind <= 1 && bj == 0) {
;                         const f32x4 c0 = *(const f32x4*)(cs + pos * 16), c1 = *(const f32x4*)(cs + pos * 16 + 4), s0 = *(const f32x4*)(cs + pos * 16 + 8), s1 = *(const f32x4*)(cs + pos * 16 + 12);
; #pragma unroll
;                         for (int i = 0; i < 8; ++i) {
;                             const float c = i < 4 ? c0[i & 3] : c1[i & 3], s = i < 4 ? s0[i & 3] : s1[i & 3];
;                             const float pr = peer_x16(v[i], fq);
;                             const float r = (fq == 0) ? (v[i] * c - pr * s) : (v[i] * c + pr * s);
;                             v[i] = (fq < 2) ? r : v[i];
;                         }
;                     }
;                     if (kind == 0) {
; #pragma unroll
;                         for (int i = 0; i < 8; ++i) v[i] *= C2Q;
;                     }
;                     { u32x4 w; w.x = cvt_pk_bf16(v[0], v[1]); w.y = cvt_pk_bf16(v[2], v[3]); w.z = cvt_pk_bf16(v[4], v[5]); w.w = cvt_pk_bf16(v[6], v[7]);
;                       *(PG8_LAS u32x4*)(stg + fr * 144 + fq * 16 + bj * 64) = w; }
;                 }
;                 {
;                     int kind;
;                     if (odd) kind = (u.pn < 6) ? 0 : (u.pn == 6 ? 1 : 2);
;                     else     kind = (u.pn < 2) ? 0 : (u.pn == 2 ? (wc < 2 ? 1 : 2) : 3);
; #pragma unroll
;                     for (int i = 0; i < 2; ++i) { const int c = fq * 16 + fr + 64 * i, rr = c >> 3, pc = c & 7;
;                         const u32x4 w = *(const PG8_LAS u32x4*)(stg + rr * 144 + pc * 16);
.Lalign_ipeK:
	s_add_i32 s44, s19, 32
	s_and_b32 s44, s44, 0xfff
	v_or_b32_e32 v0, s44, v141
	v_lshlrev_b32_e32 v0, 6, v0
	s_mov_b64 s[44:45], exec
	s_and_b64 exec, exec, s[38:39]
	global_load_dwordx4 v[154:157], v0, s[62:63]
	global_load_dwordx4 v[158:161], v0, s[62:63] offset:16
	global_load_dwordx4 v[162:165], v0, s[62:63] offset:32
	global_load_dwordx4 v[166:169], v0, s[62:63] offset:48
	s_mov_b64 exec, s[44:45]
	v_pk_mul_f32 v[102:103], v[102:103], v[152:153] op_sel:[0,1]
	v_pk_mul_f32 v[104:105], v[104:105], v[152:153] op_sel:[0,1]
	v_pk_mul_f32 v[98:99], v[98:99], v[152:153] op_sel:[0,1]
	v_pk_mul_f32 v[100:101], v[100:101], v[152:153] op_sel:[0,1]
	v_cvt_pk_bf16_f32 v102, v102, v103
	v_cvt_pk_bf16_f32 v103, v104, v105
	v_cvt_pk_bf16_f32 v104, v98, v99
	v_cvt_pk_bf16_f32 v105, v100, v101
	v_pk_mul_f32 v[110:111], v[110:111], v[152:153] op_sel:[0,1]
	v_pk_mul_f32 v[112:113], v[112:113], v[152:153] op_sel:[0,1]
	v_pk_mul_f32 v[106:107], v[106:107], v[152:153] op_sel:[0,1]
	v_pk_mul_f32 v[108:109], v[108:109], v[152:153] op_sel:[0,1]
	ds_swizzle_b32 v98, v110 offset:0x401f
	ds_swizzle_b32 v99, v111 offset:0x401f
	ds_swizzle_b32 v100, v112 offset:0x401f
	ds_swizzle_b32 v101, v113 offset:0x401f
	s_waitcnt vmcnt(4)
	v_xor_b32_e32 v226, v201, v226
	v_xor_b32_e32 v227, v201, v227
	v_xor_b32_e32 v228, v201, v228
	v_xor_b32_e32 v229, v201, v229
	v_xor_b32_e32 v230, v201, v230
	v_xor_b32_e32 v231, v201, v231
	v_xor_b32_e32 v232, v201, v232
	v_xor_b32_e32 v233, v201, v233
	s_waitcnt lgkmcnt(0)
	v_mul_f32_e32 v98, v226, v98
	v_fmac_f32_e32 v98, v110, v218
	v_cndmask_b32_e64 v110, v110, v98, s[38:39]
	v_mul_f32_e32 v99, v227, v99
	v_fmac_f32_e32 v99, v111, v219
	v_cndmask_b32_e64 v111, v111, v99, s[38:39]
	v_mul_f32_e32 v100, v228, v100
	v_fmac_f32_e32 v100, v112, v220
	v_cndmask_b32_e64 v112, v112, v100, s[38:39]
	v_mul_f32_e32 v101, v229, v101
	v_fmac_f32_e32 v101, v113, v221
	v_cndmask_b32_e64 v113, v113, v101, s[38:39]
	ds_swizzle_b32 v98, v106 offset:0x401f
	ds_swizzle_b32 v99, v107 offset:0x401f
	ds_swizzle_b32 v100, v108 offset:0x401f
	ds_swizzle_b32 v101, v109 offset:0x401f
	s_waitcnt lgkmcnt(0)
	v_mul_f32_e32 v98, v230, v98
	v_fmac_f32_e32 v98, v106, v222
	v_cndmask_b32_e64 v106, v106, v98, s[38:39]
	v_mul_f32_e32 v99, v231, v99
	v_fmac_f32_e32 v99, v107, v223
	v_cndmask_b32_e64 v107, v107, v99, s[38:39]
	v_mul_f32_e32 v100, v232, v100
	v_fmac_f32_e32 v100, v108, v224
	v_cndmask_b32_e64 v108, v108, v100, s[38:39]
	v_mul_f32_e32 v101, v233, v101
	v_fmac_f32_e32 v101, v109, v225
	v_cndmask_b32_e64 v109, v109, v101, s[38:39]
	v_cvt_pk_bf16_f32 v110, v110, v111
	v_cvt_pk_bf16_f32 v111, v112, v113
	v_cvt_pk_bf16_f32 v112, v106, v107
	v_cvt_pk_bf16_f32 v113, v108, v109
	s_mov_b32 s100, s98
	s_mov_b32 s101, s99
	global_store_dwordx4 v200, v[122:125], s[100:101] nt
	s_add_u32 s100, s100, s67
	s_addc_u32 s101, s101, 0
	global_store_dwordx4 v200, v[114:117], s[100:101] nt
	ds_write_b128 v178, v[110:113]
	ds_write_b128 v178, v[102:105] offset:64
	ds_read_b128 v[106:109], v180
	ds_read_b128 v[98:101], v180 offset:1152
	s_add_i32 s44, s19, 48
	s_and_b32 s44, s44, 0xfff
	v_or_b32_e32 v0, s44, v141
	v_lshlrev_b32_e32 v0, 6, v0
	s_mov_b64 s[44:45], exec
	s_and_b64 exec, exec, s[38:39]
	global_load_dwordx4 v[218:221], v0, s[62:63]
	global_load_dwordx4 v[222:225], v0, s[62:63] offset:16
	global_load_dwordx4 v[226:229], v0, s[62:63] offset:32
	global_load_dwordx4 v[230:233], v0, s[62:63] offset:48
	s_mov_b64 exec, s[44:45]
	v_pk_mul_f32 v[86:87], v[86:87], v[150:151] op_sel_hi:[1,0]
	v_pk_mul_f32 v[88:89], v[88:89], v[150:151] op_sel_hi:[1,0]
	v_pk_mul_f32 v[82:83], v[82:83], v[150:151] op_sel_hi:[1,0]
	v_pk_mul_f32 v[84:85], v[84:85], v[150:151] op_sel_hi:[1,0]
	v_cvt_pk_bf16_f32 v86, v86, v87
	v_cvt_pk_bf16_f32 v87, v88, v89
	v_cvt_pk_bf16_f32 v88, v82, v83
	v_cvt_pk_bf16_f32 v89, v84, v85
	v_pk_mul_f32 v[94:95], v[94:95], v[150:151] op_sel_hi:[1,0]
	v_pk_mul_f32 v[96:97], v[96:97], v[150:151] op_sel_hi:[1,0]
	v_pk_mul_f32 v[90:91], v[90:91], v[150:151] op_sel_hi:[1,0]
	v_pk_mul_f32 v[92:93], v[92:93], v[150:151] op_sel_hi:[1,0]
	ds_swizzle_b32 v82, v94 offset:0x401f
	ds_swizzle_b32 v83, v95 offset:0x401f
	ds_swizzle_b32 v84, v96 offset:0x401f
	ds_swizzle_b32 v85, v97 offset:0x401f
	s_waitcnt vmcnt(6)
	v_xor_b32_e32 v162, v201, v162
	v_xor_b32_e32 v163, v201, v163
	v_xor_b32_e32 v164, v201, v164
	v_xor_b32_e32 v165, v201, v165
	v_xor_b32_e32 v166, v201, v166
	v_xor_b32_e32 v167, v201, v167
	v_xor_b32_e32 v168, v201, v168
	v_xor_b32_e32 v169, v201, v169
	s_waitcnt lgkmcnt(0)
	v_mul_f32_e32 v82, v162, v82
	v_fmac_f32_e32 v82, v94, v154
	v_cndmask_b32_e64 v94, v94, v82, s[38:39]
	v_mul_f32_e32 v83, v163, v83
	v_fmac_f32_e32 v83, v95, v155
	v_cndmask_b32_e64 v95, v95, v83, s[38:39]
	v_mul_f32_e32 v84, v164, v84
	v_fmac_f32_e32 v84, v96, v156
	v_cndmask_b32_e64 v96, v96, v84, s[38:39]
	v_mul_f32_e32 v85, v165, v85
	v_fmac_f32_e32 v85, v97, v157
	v_cndmask_b32_e64 v97, v97, v85, s[38:39]
	ds_swizzle_b32 v82, v90 offset:0x401f
	ds_swizzle_b32 v83, v91 offset:0x401f
	ds_swizzle_b32 v84, v92 offset:0x401f
	ds_swizzle_b32 v85, v93 offset:0x401f
	s_waitcnt lgkmcnt(0)
;     __device__ __forceinline__ void operator()(const f32x4 (&acc)[2][2][4][2], const Unit& u, int wr, int wc, int fr, int fq, PG8_LAS float* stash, int par, PG8_LAS unsigned char* stg, const Unit& un) const {
;     ...
;                 const int row = u.pm * BM + ai * HALF + wr * 64 + m * 16 + fr, pos = row & 4095, b = row >> 12;
;                 const float rs = rsa[ai][m];
; #pragma unroll
;                 for (int bj = 0; bj < 2; ++bj) {
;                     int kind;
;                     if (odd) kind = (u.pn < 6) ? 0 : (u.pn == 6 ? 1 : 2);
;                     else     kind = (u.pn < 2) ? 0 : (u.pn == 2 ? (wc < 2 ? 1 : 2) : 3);
;                     float v[8];
; #pragma unroll
;                     for (int i = 0; i < 4; ++i) { v[i] = acc[ai][bj][m][0][i] * rs; v[4 + i] = acc[ai][bj][m][1][i] * rs; }
;                     if (kind <= 1 && bj == 0) {
;                         const f32x4 c0 = *(const f32x4*)(cs + pos * 16), c1 = *(const f32x4*)(cs + pos * 16 + 4), s0 = *(const f32x4*)(cs + pos * 16 + 8), s1 = *(const f32x4*)(cs + pos * 16 + 12);
; #pragma unroll
;                         for (int i = 0; i < 8; ++i) {
;                             const float c = i < 4 ? c0[i & 3] : c1[i & 3], s = i < 4 ? s0[i & 3] : s1[i & 3];
;                             const float pr = peer_x16(v[i], fq);
;                             const float r = (fq == 0) ? (v[i] * c - pr * s) : (v[i] * c + pr * s);
;                             v[i] = (fq < 2) ? r : v[i];
;                         }
;                     }
;                     if (kind == 0) {
; #pragma unroll
;                         for (int i = 0; i < 8; ++i) v[i] *= C2Q;
;                     }
;                     { u32x4 w; w.x = cvt_pk_bf16(v[0], v[1]); w.y = cvt_pk_bf16(v[2], v[3]); w.z = cvt_pk_bf16(v[4], v[5]); w.w = cvt_pk_bf16(v[6], v[7]);
;                       *(PG8_LAS u32x4*)(stg + fr * 144 + fq * 16 + bj * 64) = w; }
;                 }
;                 {
;                     int kind;
;                     if (odd) kind = (u.pn < 6) ? 0 : (u.pn == 6 ? 1 : 2);
;                     else     kind = (u.pn < 2) ? 0 : (u.pn == 2 ? (wc < 2 ? 1 : 2) : 3);
; #pragma unroll
;                     for (int i = 0; i < 2; ++i) { const int c = fq * 16 + fr + 64 * i, rr = c >> 3, pc = c & 7;
;                         const u32x4 w = *(const PG8_LAS u32x4*)(stg + rr * 144 + pc * 16);
	v_mul_f32_e32 v82, v166, v82
	v_fmac_f32_e32 v82, v90, v158
	v_cndmask_b32_e64 v90, v90, v82, s[38:39]
	v_mul_f32_e32 v83, v167, v83
	v_fmac_f32_e32 v83, v91, v159
	v_cndmask_b32_e64 v91, v91, v83, s[38:39]
	v_mul_f32_e32 v84, v168, v84
	v_fmac_f32_e32 v84, v92, v160
	v_cndmask_b32_e64 v92, v92, v84, s[38:39]
	v_mul_f32_e32 v85, v169, v85
	v_fmac_f32_e32 v85, v93, v161
	v_cndmask_b32_e64 v93, v93, v85, s[38:39]
	v_cvt_pk_bf16_f32 v94, v94, v95
	v_cvt_pk_bf16_f32 v95, v96, v97
	v_cvt_pk_bf16_f32 v96, v90, v91
	v_cvt_pk_bf16_f32 v97, v92, v93
	s_mul_i32 s44, s66, 16
	s_add_u32 s100, s98, s44
	s_addc_u32 s101, s99, 0
	global_store_dwordx4 v200, v[106:109], s[100:101] nt
	s_add_u32 s100, s100, s67
	s_addc_u32 s101, s101, 0
	global_store_dwordx4 v200, v[98:101], s[100:101] nt
	ds_write_b128 v178, v[94:97]
	ds_write_b128 v178, v[86:89] offset:64
	ds_read_b128 v[90:93], v180
	ds_read_b128 v[82:85], v180 offset:1152
	s_add_i32 s44, s19, 128
	s_and_b32 s44, s44, 0xfff
	v_or_b32_e32 v0, s44, v141
	v_lshlrev_b32_e32 v0, 6, v0
	s_mov_b64 s[44:45], exec
	s_and_b64 exec, exec, s[38:39]
	global_load_dwordx4 v[154:157], v0, s[62:63]
	global_load_dwordx4 v[158:161], v0, s[62:63] offset:16
	global_load_dwordx4 v[162:165], v0, s[62:63] offset:32
	global_load_dwordx4 v[166:169], v0, s[62:63] offset:48
	s_mov_b64 exec, s[44:45]
	v_pk_mul_f32 v[70:71], v[70:71], v[150:151] op_sel:[0,1]
	v_pk_mul_f32 v[72:73], v[72:73], v[150:151] op_sel:[0,1]
	v_pk_mul_f32 v[66:67], v[66:67], v[150:151] op_sel:[0,1]
	v_pk_mul_f32 v[68:69], v[68:69], v[150:151] op_sel:[0,1]
	v_cvt_pk_bf16_f32 v70, v70, v71
	v_cvt_pk_bf16_f32 v71, v72, v73
	v_cvt_pk_bf16_f32 v72, v66, v67
	v_cvt_pk_bf16_f32 v73, v68, v69
	v_pk_mul_f32 v[78:79], v[78:79], v[150:151] op_sel:[0,1]
	v_pk_mul_f32 v[80:81], v[80:81], v[150:151] op_sel:[0,1]
	v_pk_mul_f32 v[74:75], v[74:75], v[150:151] op_sel:[0,1]
	v_pk_mul_f32 v[76:77], v[76:77], v[150:151] op_sel:[0,1]
	ds_swizzle_b32 v66, v78 offset:0x401f
	ds_swizzle_b32 v67, v79 offset:0x401f
	ds_swizzle_b32 v68, v80 offset:0x401f
	ds_swizzle_b32 v69, v81 offset:0x401f
	s_waitcnt vmcnt(6)
	v_xor_b32_e32 v226, v201, v226
	v_xor_b32_e32 v227, v201, v227
	v_xor_b32_e32 v228, v201, v228
	v_xor_b32_e32 v229, v201, v229
	v_xor_b32_e32 v230, v201, v230
	v_xor_b32_e32 v231, v201, v231
	v_xor_b32_e32 v232, v201, v232
	v_xor_b32_e32 v233, v201, v233
	s_waitcnt lgkmcnt(0)
	v_mul_f32_e32 v66, v226, v66
	v_fmac_f32_e32 v66, v78, v218
	v_cndmask_b32_e64 v78, v78, v66, s[38:39]
	v_mul_f32_e32 v67, v227, v67
	v_fmac_f32_e32 v67, v79, v219
	v_cndmask_b32_e64 v79, v79, v67, s[38:39]
	v_mul_f32_e32 v68, v228, v68
	v_fmac_f32_e32 v68, v80, v220
	v_cndmask_b32_e64 v80, v80, v68, s[38:39]
	v_mul_f32_e32 v69, v229, v69
	v_fmac_f32_e32 v69, v81, v221
	v_cndmask_b32_e64 v81, v81, v69, s[38:39]
	ds_swizzle_b32 v66, v74 offset:0x401f
	ds_swizzle_b32 v67, v75 offset:0x401f
	ds_swizzle_b32 v68, v76 offset:0x401f
	ds_swizzle_b32 v69, v77 offset:0x401f
	s_waitcnt lgkmcnt(0)
	v_mul_f32_e32 v66, v230, v66
	v_fmac_f32_e32 v66, v74, v222
	v_cndmask_b32_e64 v74, v74, v66, s[38:39]
	v_mul_f32_e32 v67, v231, v67
	v_fmac_f32_e32 v67, v75, v223
	v_cndmask_b32_e64 v75, v75, v67, s[38:39]
	v_mul_f32_e32 v68, v232, v68
	v_fmac_f32_e32 v68, v76, v224
	v_cndmask_b32_e64 v76, v76, v68, s[38:39]
	v_mul_f32_e32 v69, v233, v69
	v_fmac_f32_e32 v69, v77, v225
	v_cndmask_b32_e64 v77, v77, v69, s[38:39]
	v_cvt_pk_bf16_f32 v78, v78, v79
	v_cvt_pk_bf16_f32 v79, v80, v81
	v_cvt_pk_bf16_f32 v80, v74, v75
	v_cvt_pk_bf16_f32 v81, v76, v77
	s_mul_i32 s44, s66, 32
	s_add_u32 s100, s98, s44
	s_addc_u32 s101, s99, 0
	global_store_dwordx4 v200, v[90:93], s[100:101] nt
	s_add_u32 s100, s100, s67
	s_addc_u32 s101, s101, 0
	global_store_dwordx4 v200, v[82:85], s[100:101] nt
	ds_write_b128 v178, v[78:81]
	ds_write_b128 v178, v[70:73] offset:64
	ds_read_b128 v[74:77], v180
	ds_read_b128 v[66:69], v180 offset:1152
	s_add_i32 s44, s19, 144
	s_and_b32 s44, s44, 0xfff
	v_or_b32_e32 v0, s44, v141
	v_lshlrev_b32_e32 v0, 6, v0
	s_mov_b64 s[44:45], exec
	s_and_b64 exec, exec, s[38:39]
	global_load_dwordx4 v[218:221], v0, s[62:63]
	global_load_dwordx4 v[222:225], v0, s[62:63] offset:16
	global_load_dwordx4 v[226:229], v0, s[62:63] offset:32
	global_load_dwordx4 v[230:233], v0, s[62:63] offset:48
	s_mov_b64 exec, s[44:45]
	v_pk_mul_f32 v[54:55], v[54:55], v[148:149] op_sel_hi:[1,0]
	v_pk_mul_f32 v[56:57], v[56:57], v[148:149] op_sel_hi:[1,0]
	v_pk_mul_f32 v[50:51], v[50:51], v[148:149] op_sel_hi:[1,0]
	v_pk_mul_f32 v[52:53], v[52:53], v[148:149] op_sel_hi:[1,0]
	v_cvt_pk_bf16_f32 v54, v54, v55
	v_cvt_pk_bf16_f32 v55, v56, v57
	v_cvt_pk_bf16_f32 v56, v50, v51
	v_cvt_pk_bf16_f32 v57, v52, v53
	v_pk_mul_f32 v[62:63], v[62:63], v[148:149] op_sel_hi:[1,0]
	v_pk_mul_f32 v[64:65], v[64:65], v[148:149] op_sel_hi:[1,0]
	v_pk_mul_f32 v[58:59], v[58:59], v[148:149] op_sel_hi:[1,0]
	v_pk_mul_f32 v[60:61], v[60:61], v[148:149] op_sel_hi:[1,0]
	ds_swizzle_b32 v50, v62 offset:0x401f
	ds_swizzle_b32 v51, v63 offset:0x401f
	ds_swizzle_b32 v52, v64 offset:0x401f
	ds_swizzle_b32 v53, v65 offset:0x401f
	s_waitcnt vmcnt(6)
	v_xor_b32_e32 v162, v201, v162
	v_xor_b32_e32 v163, v201, v163
	v_xor_b32_e32 v164, v201, v164
	v_xor_b32_e32 v165, v201, v165
	v_xor_b32_e32 v166, v201, v166
	v_xor_b32_e32 v167, v201, v167
	v_xor_b32_e32 v168, v201, v168
	v_xor_b32_e32 v169, v201, v169
	s_waitcnt lgkmcnt(0)
;     __device__ __forceinline__ void operator()(const f32x4 (&acc)[2][2][4][2], const Unit& u, int wr, int wc, int fr, int fq, PG8_LAS float* stash, int par, PG8_LAS unsigned char* stg, const Unit& un) const {
;     ...
;                 const int row = u.pm * BM + ai * HALF + wr * 64 + m * 16 + fr, pos = row & 4095, b = row >> 12;
;                 const float rs = rsa[ai][m];
; #pragma unroll
;                 for (int bj = 0; bj < 2; ++bj) {
;                     int kind;
;                     if (odd) kind = (u.pn < 6) ? 0 : (u.pn == 6 ? 1 : 2);
;                     else     kind = (u.pn < 2) ? 0 : (u.pn == 2 ? (wc < 2 ? 1 : 2) : 3);
;                     float v[8];
; #pragma unroll
;                     for (int i = 0; i < 4; ++i) { v[i] = acc[ai][bj][m][0][i] * rs; v[4 + i] = acc[ai][bj][m][1][i] * rs; }
;                     if (kind <= 1 && bj == 0) {
;                         const f32x4 c0 = *(const f32x4*)(cs + pos * 16), c1 = *(const f32x4*)(cs + pos * 16 + 4), s0 = *(const f32x4*)(cs + pos * 16 + 8), s1 = *(const f32x4*)(cs + pos * 16 + 12);
; #pragma unroll
;                         for (int i = 0; i < 8; ++i) {
;                             const float c = i < 4 ? c0[i & 3] : c1[i & 3], s = i < 4 ? s0[i & 3] : s1[i & 3];
;                             const float pr = peer_x16(v[i], fq);
;                             const float r = (fq == 0) ? (v[i] * c - pr * s) : (v[i] * c + pr * s);
;                             v[i] = (fq < 2) ? r : v[i];
;                         }
;                     }
;                     if (kind == 0) {
; #pragma unroll
;                         for (int i = 0; i < 8; ++i) v[i] *= C2Q;
;                     }
;                     { u32x4 w; w.x = cvt_pk_bf16(v[0], v[1]); w.y = cvt_pk_bf16(v[2], v[3]); w.z = cvt_pk_bf16(v[4], v[5]); w.w = cvt_pk_bf16(v[6], v[7]);
;                       *(PG8_LAS u32x4*)(stg + fr * 144 + fq * 16 + bj * 64) = w; }
;                 }
;                 {
;                     int kind;
;                     if (odd) kind = (u.pn < 6) ? 0 : (u.pn == 6 ? 1 : 2);
;                     else     kind = (u.pn < 2) ? 0 : (u.pn == 2 ? (wc < 2 ? 1 : 2) : 3);
; #pragma unroll
;                     for (int i = 0; i < 2; ++i) { const int c = fq * 16 + fr + 64 * i, rr = c >> 3, pc = c & 7;
;                         const u32x4 w = *(const PG8_LAS u32x4*)(stg + rr * 144 + pc * 16);
	v_mul_f32_e32 v50, v162, v50
	v_fmac_f32_e32 v50, v62, v154
	v_cndmask_b32_e64 v62, v62, v50, s[38:39]
	v_mul_f32_e32 v51, v163, v51
	v_fmac_f32_e32 v51, v63, v155
	v_cndmask_b32_e64 v63, v63, v51, s[38:39]
	v_mul_f32_e32 v52, v164, v52
	v_fmac_f32_e32 v52, v64, v156
	v_cndmask_b32_e64 v64, v64, v52, s[38:39]
	v_mul_f32_e32 v53, v165, v53
	v_fmac_f32_e32 v53, v65, v157
	v_cndmask_b32_e64 v65, v65, v53, s[38:39]
	ds_swizzle_b32 v50, v58 offset:0x401f
	ds_swizzle_b32 v51, v59 offset:0x401f
	ds_swizzle_b32 v52, v60 offset:0x401f
	ds_swizzle_b32 v53, v61 offset:0x401f
	s_waitcnt lgkmcnt(0)
	v_mul_f32_e32 v50, v166, v50
	v_fmac_f32_e32 v50, v58, v158
	v_cndmask_b32_e64 v58, v58, v50, s[38:39]
	v_mul_f32_e32 v51, v167, v51
	v_fmac_f32_e32 v51, v59, v159
	v_cndmask_b32_e64 v59, v59, v51, s[38:39]
	v_mul_f32_e32 v52, v168, v52
	v_fmac_f32_e32 v52, v60, v160
	v_cndmask_b32_e64 v60, v60, v52, s[38:39]
	v_mul_f32_e32 v53, v169, v53
	v_fmac_f32_e32 v53, v61, v161
	v_cndmask_b32_e64 v61, v61, v53, s[38:39]
	v_cvt_pk_bf16_f32 v62, v62, v63
	v_cvt_pk_bf16_f32 v63, v64, v65
	v_cvt_pk_bf16_f32 v64, v58, v59
	v_cvt_pk_bf16_f32 v65, v60, v61
	s_mul_i32 s44, s66, 48
	s_add_u32 s100, s98, s44
	s_addc_u32 s101, s99, 0
	global_store_dwordx4 v200, v[74:77], s[100:101] nt
	s_add_u32 s100, s100, s67
	s_addc_u32 s101, s101, 0
	global_store_dwordx4 v200, v[66:69], s[100:101] nt
	ds_write_b128 v178, v[62:65]
	ds_write_b128 v178, v[54:57] offset:64
	ds_read_b128 v[58:61], v180
	ds_read_b128 v[50:53], v180 offset:1152
	s_add_i32 s44, s19, 160
	s_and_b32 s44, s44, 0xfff
	v_or_b32_e32 v0, s44, v141
	v_lshlrev_b32_e32 v0, 6, v0
	s_mov_b64 s[44:45], exec
	s_and_b64 exec, exec, s[38:39]
	global_load_dwordx4 v[154:157], v0, s[62:63]
	global_load_dwordx4 v[158:161], v0, s[62:63] offset:16
	global_load_dwordx4 v[162:165], v0, s[62:63] offset:32
	global_load_dwordx4 v[166:169], v0, s[62:63] offset:48
	s_mov_b64 exec, s[44:45]
	v_pk_mul_f32 v[38:39], v[38:39], v[148:149] op_sel:[0,1]
	v_pk_mul_f32 v[40:41], v[40:41], v[148:149] op_sel:[0,1]
	v_pk_mul_f32 v[34:35], v[34:35], v[148:149] op_sel:[0,1]
	v_pk_mul_f32 v[36:37], v[36:37], v[148:149] op_sel:[0,1]
	v_cvt_pk_bf16_f32 v38, v38, v39
	v_cvt_pk_bf16_f32 v39, v40, v41
	v_cvt_pk_bf16_f32 v40, v34, v35
	v_cvt_pk_bf16_f32 v41, v36, v37
	v_pk_mul_f32 v[46:47], v[46:47], v[148:149] op_sel:[0,1]
	v_pk_mul_f32 v[48:49], v[48:49], v[148:149] op_sel:[0,1]
	v_pk_mul_f32 v[42:43], v[42:43], v[148:149] op_sel:[0,1]
	v_pk_mul_f32 v[44:45], v[44:45], v[148:149] op_sel:[0,1]
	ds_swizzle_b32 v34, v46 offset:0x401f
	ds_swizzle_b32 v35, v47 offset:0x401f
	ds_swizzle_b32 v36, v48 offset:0x401f
	ds_swizzle_b32 v37, v49 offset:0x401f
	s_waitcnt vmcnt(6)
	v_xor_b32_e32 v226, v201, v226
	v_xor_b32_e32 v227, v201, v227
	v_xor_b32_e32 v228, v201, v228
	v_xor_b32_e32 v229, v201, v229
	v_xor_b32_e32 v230, v201, v230
	v_xor_b32_e32 v231, v201, v231
	v_xor_b32_e32 v232, v201, v232
	v_xor_b32_e32 v233, v201, v233
	s_waitcnt lgkmcnt(0)
	v_mul_f32_e32 v34, v226, v34
	v_fmac_f32_e32 v34, v46, v218
	v_cndmask_b32_e64 v46, v46, v34, s[38:39]
	v_mul_f32_e32 v35, v227, v35
	v_fmac_f32_e32 v35, v47, v219
	v_cndmask_b32_e64 v47, v47, v35, s[38:39]
	v_mul_f32_e32 v36, v228, v36
	v_fmac_f32_e32 v36, v48, v220
	v_cndmask_b32_e64 v48, v48, v36, s[38:39]
	v_mul_f32_e32 v37, v229, v37
	v_fmac_f32_e32 v37, v49, v221
	v_cndmask_b32_e64 v49, v49, v37, s[38:39]
	ds_swizzle_b32 v34, v42 offset:0x401f
	ds_swizzle_b32 v35, v43 offset:0x401f
	ds_swizzle_b32 v36, v44 offset:0x401f
	ds_swizzle_b32 v37, v45 offset:0x401f
	s_waitcnt lgkmcnt(0)
	v_mul_f32_e32 v34, v230, v34
	v_fmac_f32_e32 v34, v42, v222
	v_cndmask_b32_e64 v42, v42, v34, s[38:39]
	v_mul_f32_e32 v35, v231, v35
	v_fmac_f32_e32 v35, v43, v223
	v_cndmask_b32_e64 v43, v43, v35, s[38:39]
	v_mul_f32_e32 v36, v232, v36
	v_fmac_f32_e32 v36, v44, v224
	v_cndmask_b32_e64 v44, v44, v36, s[38:39]
	v_mul_f32_e32 v37, v233, v37
	v_fmac_f32_e32 v37, v45, v225
	v_cndmask_b32_e64 v45, v45, v37, s[38:39]
	v_cvt_pk_bf16_f32 v46, v46, v47
	v_cvt_pk_bf16_f32 v47, v48, v49
	v_cvt_pk_bf16_f32 v48, v42, v43
	v_cvt_pk_bf16_f32 v49, v44, v45
	s_mul_i32 s44, s66, 128
	s_add_u32 s100, s98, s44
	s_addc_u32 s101, s99, 0
	global_store_dwordx4 v200, v[58:61], s[100:101] nt
	s_add_u32 s100, s100, s67
	s_addc_u32 s101, s101, 0
	global_store_dwordx4 v200, v[50:53], s[100:101] nt
	ds_write_b128 v178, v[46:49]
	ds_write_b128 v178, v[38:41] offset:64
	ds_read_b128 v[42:45], v180
	ds_read_b128 v[34:37], v180 offset:1152
	s_add_i32 s44, s19, 176
	s_and_b32 s44, s44, 0xfff
	v_or_b32_e32 v0, s44, v141
	v_lshlrev_b32_e32 v0, 6, v0
	s_mov_b64 s[44:45], exec
	s_and_b64 exec, exec, s[38:39]
	global_load_dwordx4 v[218:221], v0, s[62:63]
	global_load_dwordx4 v[222:225], v0, s[62:63] offset:16
	global_load_dwordx4 v[226:229], v0, s[62:63] offset:32
	global_load_dwordx4 v[230:233], v0, s[62:63] offset:48
	s_mov_b64 exec, s[44:45]
	v_pk_mul_f32 v[22:23], v[22:23], v[146:147] op_sel_hi:[1,0]
	v_pk_mul_f32 v[24:25], v[24:25], v[146:147] op_sel_hi:[1,0]
	v_pk_mul_f32 v[18:19], v[18:19], v[146:147] op_sel_hi:[1,0]
	v_pk_mul_f32 v[20:21], v[20:21], v[146:147] op_sel_hi:[1,0]
	v_cvt_pk_bf16_f32 v22, v22, v23
	v_cvt_pk_bf16_f32 v23, v24, v25
	v_cvt_pk_bf16_f32 v24, v18, v19
	v_cvt_pk_bf16_f32 v25, v20, v21
	v_pk_mul_f32 v[30:31], v[30:31], v[146:147] op_sel_hi:[1,0]
	v_pk_mul_f32 v[32:33], v[32:33], v[146:147] op_sel_hi:[1,0]
	v_pk_mul_f32 v[26:27], v[26:27], v[146:147] op_sel_hi:[1,0]
	v_pk_mul_f32 v[28:29], v[28:29], v[146:147] op_sel_hi:[1,0]
	ds_swizzle_b32 v18, v30 offset:0x401f
	ds_swizzle_b32 v19, v31 offset:0x401f
	ds_swizzle_b32 v20, v32 offset:0x401f
	ds_swizzle_b32 v21, v33 offset:0x401f
	s_waitcnt vmcnt(6)
;     __device__ __forceinline__ void operator()(const f32x4 (&acc)[2][2][4][2], const Unit& u, int wr, int wc, int fr, int fq, PG8_LAS float* stash, int par, PG8_LAS unsigned char* stg, const Unit& un) const {
;     ...
;                 const int row = u.pm * BM + ai * HALF + wr * 64 + m * 16 + fr, pos = row & 4095, b = row >> 12;
;                 const float rs = rsa[ai][m];
; #pragma unroll
;                 for (int bj = 0; bj < 2; ++bj) {
;                     int kind;
;                     if (odd) kind = (u.pn < 6) ? 0 : (u.pn == 6 ? 1 : 2);
;                     else     kind = (u.pn < 2) ? 0 : (u.pn == 2 ? (wc < 2 ? 1 : 2) : 3);
;                     float v[8];
; #pragma unroll
;                     for (int i = 0; i < 4; ++i) { v[i] = acc[ai][bj][m][0][i] * rs; v[4 + i] = acc[ai][bj][m][1][i] * rs; }
;                     if (kind <= 1 && bj == 0) {
;                         const f32x4 c0 = *(const f32x4*)(cs + pos * 16), c1 = *(const f32x4*)(cs + pos * 16 + 4), s0 = *(const f32x4*)(cs + pos * 16 + 8), s1 = *(const f32x4*)(cs + pos * 16 + 12);
; #pragma unroll
;                         for (int i = 0; i < 8; ++i) {
;                             const float c = i < 4 ? c0[i & 3] : c1[i & 3], s = i < 4 ? s0[i & 3] : s1[i & 3];
;                             const float pr = peer_x16(v[i], fq);
;                             const float r = (fq == 0) ? (v[i] * c - pr * s) : (v[i] * c + pr * s);
;                             v[i] = (fq < 2) ? r : v[i];
;                         }
;                     }
;                     if (kind == 0) {
; #pragma unroll
;                         for (int i = 0; i < 8; ++i) v[i] *= C2Q;
;                     }
;                     { u32x4 w; w.x = cvt_pk_bf16(v[0], v[1]); w.y = cvt_pk_bf16(v[2], v[3]); w.z = cvt_pk_bf16(v[4], v[5]); w.w = cvt_pk_bf16(v[6], v[7]);
;                       *(PG8_LAS u32x4*)(stg + fr * 144 + fq * 16 + bj * 64) = w; }
;                 }
;                 {
;                     int kind;
;                     if (odd) kind = (u.pn < 6) ? 0 : (u.pn == 6 ? 1 : 2);
;                     else     kind = (u.pn < 2) ? 0 : (u.pn == 2 ? (wc < 2 ? 1 : 2) : 3);
; #pragma unroll
;                     for (int i = 0; i < 2; ++i) { const int c = fq * 16 + fr + 64 * i, rr = c >> 3, pc = c & 7;
;                         const u32x4 w = *(const PG8_LAS u32x4*)(stg + rr * 144 + pc * 16);
	v_xor_b32_e32 v162, v201, v162
	v_xor_b32_e32 v163, v201, v163
	v_xor_b32_e32 v164, v201, v164
	v_xor_b32_e32 v165, v201, v165
	v_xor_b32_e32 v166, v201, v166
	v_xor_b32_e32 v167, v201, v167
	v_xor_b32_e32 v168, v201, v168
	v_xor_b32_e32 v169, v201, v169
	s_waitcnt lgkmcnt(0)
	v_mul_f32_e32 v18, v162, v18
	v_fmac_f32_e32 v18, v30, v154
	v_cndmask_b32_e64 v30, v30, v18, s[38:39]
	v_mul_f32_e32 v19, v163, v19
	v_fmac_f32_e32 v19, v31, v155
	v_cndmask_b32_e64 v31, v31, v19, s[38:39]
	v_mul_f32_e32 v20, v164, v20
	v_fmac_f32_e32 v20, v32, v156
	v_cndmask_b32_e64 v32, v32, v20, s[38:39]
	v_mul_f32_e32 v21, v165, v21
	v_fmac_f32_e32 v21, v33, v157
	v_cndmask_b32_e64 v33, v33, v21, s[38:39]
	ds_swizzle_b32 v18, v26 offset:0x401f
	ds_swizzle_b32 v19, v27 offset:0x401f
	ds_swizzle_b32 v20, v28 offset:0x401f
	ds_swizzle_b32 v21, v29 offset:0x401f
	s_waitcnt lgkmcnt(0)
	v_mul_f32_e32 v18, v166, v18
	v_fmac_f32_e32 v18, v26, v158
	v_cndmask_b32_e64 v26, v26, v18, s[38:39]
	v_mul_f32_e32 v19, v167, v19
	v_fmac_f32_e32 v19, v27, v159
	v_cndmask_b32_e64 v27, v27, v19, s[38:39]
	v_mul_f32_e32 v20, v168, v20
	v_fmac_f32_e32 v20, v28, v160
	v_cndmask_b32_e64 v28, v28, v20, s[38:39]
	v_mul_f32_e32 v21, v169, v21
	v_fmac_f32_e32 v21, v29, v161
	v_cndmask_b32_e64 v29, v29, v21, s[38:39]
	v_cvt_pk_bf16_f32 v30, v30, v31
	v_cvt_pk_bf16_f32 v31, v32, v33
	v_cvt_pk_bf16_f32 v32, v26, v27
	v_cvt_pk_bf16_f32 v33, v28, v29
	s_mul_i32 s44, s66, 144
	s_add_u32 s100, s98, s44
	s_addc_u32 s101, s99, 0
	global_store_dwordx4 v200, v[42:45], s[100:101] nt
	s_add_u32 s100, s100, s67
	s_addc_u32 s101, s101, 0
	global_store_dwordx4 v200, v[34:37], s[100:101] nt
	ds_write_b128 v178, v[30:33]
	ds_write_b128 v178, v[22:25] offset:64
	ds_read_b128 v[26:29], v180
	ds_read_b128 v[18:21], v180 offset:1152
	v_pk_mul_f32 v[6:7], v[6:7], v[146:147] op_sel:[0,1]
	v_pk_mul_f32 v[8:9], v[8:9], v[146:147] op_sel:[0,1]
	v_pk_mul_f32 v[2:3], v[2:3], v[146:147] op_sel:[0,1]
	v_pk_mul_f32 v[4:5], v[4:5], v[146:147] op_sel:[0,1]
	v_cvt_pk_bf16_f32 v6, v6, v7
	v_cvt_pk_bf16_f32 v7, v8, v9
	v_cvt_pk_bf16_f32 v8, v2, v3
	v_cvt_pk_bf16_f32 v9, v4, v5
	v_pk_mul_f32 v[14:15], v[14:15], v[146:147] op_sel:[0,1]
	v_pk_mul_f32 v[16:17], v[16:17], v[146:147] op_sel:[0,1]
	v_pk_mul_f32 v[10:11], v[10:11], v[146:147] op_sel:[0,1]
	v_pk_mul_f32 v[12:13], v[12:13], v[146:147] op_sel:[0,1]
	ds_swizzle_b32 v2, v14 offset:0x401f
	ds_swizzle_b32 v3, v15 offset:0x401f
	ds_swizzle_b32 v4, v16 offset:0x401f
	ds_swizzle_b32 v5, v17 offset:0x401f
	s_waitcnt vmcnt(2)
	v_xor_b32_e32 v226, v201, v226
	v_xor_b32_e32 v227, v201, v227
	v_xor_b32_e32 v228, v201, v228
	v_xor_b32_e32 v229, v201, v229
	v_xor_b32_e32 v230, v201, v230
	v_xor_b32_e32 v231, v201, v231
	v_xor_b32_e32 v232, v201, v232
	v_xor_b32_e32 v233, v201, v233
	s_waitcnt lgkmcnt(0)
	v_mul_f32_e32 v2, v226, v2
	v_fmac_f32_e32 v2, v14, v218
	v_cndmask_b32_e64 v14, v14, v2, s[38:39]
	v_mul_f32_e32 v3, v227, v3
	v_fmac_f32_e32 v3, v15, v219
	v_cndmask_b32_e64 v15, v15, v3, s[38:39]
	v_mul_f32_e32 v4, v228, v4
	v_fmac_f32_e32 v4, v16, v220
	v_cndmask_b32_e64 v16, v16, v4, s[38:39]
	v_mul_f32_e32 v5, v229, v5
	v_fmac_f32_e32 v5, v17, v221
	v_cndmask_b32_e64 v17, v17, v5, s[38:39]
	ds_swizzle_b32 v2, v10 offset:0x401f
	ds_swizzle_b32 v3, v11 offset:0x401f
	ds_swizzle_b32 v4, v12 offset:0x401f
	ds_swizzle_b32 v5, v13 offset:0x401f
	s_waitcnt lgkmcnt(0)
	v_mul_f32_e32 v2, v230, v2
	v_fmac_f32_e32 v2, v10, v222
	v_cndmask_b32_e64 v10, v10, v2, s[38:39]
	v_mul_f32_e32 v3, v231, v3
	v_fmac_f32_e32 v3, v11, v223
	v_cndmask_b32_e64 v11, v11, v3, s[38:39]
	v_mul_f32_e32 v4, v232, v4
	v_fmac_f32_e32 v4, v12, v224
	v_cndmask_b32_e64 v12, v12, v4, s[38:39]
	v_mul_f32_e32 v5, v233, v5
	v_fmac_f32_e32 v5, v13, v225
	v_cndmask_b32_e64 v13, v13, v5, s[38:39]
	v_cvt_pk_bf16_f32 v14, v14, v15
	v_cvt_pk_bf16_f32 v15, v16, v17
	v_cvt_pk_bf16_f32 v16, v10, v11
	v_cvt_pk_bf16_f32 v17, v12, v13
	s_mul_i32 s44, s66, 160
	s_add_u32 s100, s98, s44
	s_addc_u32 s101, s99, 0
	global_store_dwordx4 v200, v[26:29], s[100:101] nt
	s_add_u32 s100, s100, s67
	s_addc_u32 s101, s101, 0
	global_store_dwordx4 v200, v[18:21], s[100:101] nt
	ds_write_b128 v178, v[14:17]
	ds_write_b128 v178, v[6:9] offset:64
	ds_read_b128 v[10:13], v180
	ds_read_b128 v[2:5], v180 offset:1152
	s_waitcnt lgkmcnt(0)
	s_mul_i32 s44, s66, 176
	s_add_u32 s100, s98, s44
	s_addc_u32 s101, s99, 0
	global_store_dwordx4 v200, v[10:13], s[100:101] nt
	s_add_u32 s100, s100, s67
	s_addc_u32 s101, s101, 0
	global_store_dwordx4 v200, v[2:5], s[100:101] nt
	s_branch .Lipe_done
.Lipe_P:
	v_pk_mul_f32 v[118:119], v[118:119], v[152:153] op_sel_hi:[1,0]
	v_pk_mul_f32 v[120:121], v[120:121], v[152:153] op_sel_hi:[1,0]
	v_pk_mul_f32 v[114:115], v[114:115], v[152:153] op_sel_hi:[1,0]
	v_pk_mul_f32 v[116:117], v[116:117], v[152:153] op_sel_hi:[1,0]
	v_cvt_pk_bf16_f32 v118, v118, v119
	v_cvt_pk_bf16_f32 v119, v120, v121
	v_cvt_pk_bf16_f32 v120, v114, v115
	v_cvt_pk_bf16_f32 v121, v116, v117
	v_pk_mul_f32 v[126:127], v[126:127], v[152:153] op_sel_hi:[1,0]
	v_pk_mul_f32 v[128:129], v[128:129], v[152:153] op_sel_hi:[1,0]
	v_pk_mul_f32 v[122:123], v[122:123], v[152:153] op_sel_hi:[1,0]
	v_pk_mul_f32 v[124:125], v[124:125], v[152:153] op_sel_hi:[1,0]
	s_waitcnt lgkmcnt(0)
	v_cvt_pk_bf16_f32 v126, v126, v127
	v_cvt_pk_bf16_f32 v127, v128, v129
	v_cvt_pk_bf16_f32 v128, v122, v123
	v_cvt_pk_bf16_f32 v129, v124, v125
	ds_write_b128 v178, v[126:129]
	ds_write_b128 v178, v[118:121] offset:64
	ds_read_b128 v[122:125], v180
	ds_read_b128 v[114:117], v180 offset:1152
	s_and_b64 vcc, exec, s[60:61]
	s_cbranch_vccz .Lalign_ipeP
	s_barrier
;     __device__ __forceinline__ void operator()(const f32x4 (&acc)[2][2][4][2], const Unit& u, int wr, int wc, int fr, int fq, PG8_LAS float* stash, int par, PG8_LAS unsigned char* stg, const Unit& un) const {
;     ...
;                 const int row = u.pm * BM + ai * HALF + wr * 64 + m * 16 + fr, pos = row & 4095, b = row >> 12;
;                 const float rs = rsa[ai][m];
; #pragma unroll
;                 for (int bj = 0; bj < 2; ++bj) {
;                     int kind;
;                     if (odd) kind = (u.pn < 6) ? 0 : (u.pn == 6 ? 1 : 2);
;                     else     kind = (u.pn < 2) ? 0 : (u.pn == 2 ? (wc < 2 ? 1 : 2) : 3);
;                     float v[8];
; #pragma unroll
;                     for (int i = 0; i < 4; ++i) { v[i] = acc[ai][bj][m][0][i] * rs; v[4 + i] = acc[ai][bj][m][1][i] * rs; }
;                     if (kind <= 1 && bj == 0) {
;                         const f32x4 c0 = *(const f32x4*)(cs + pos * 16), c1 = *(const f32x4*)(cs + pos * 16 + 4), s0 = *(const f32x4*)(cs + pos * 16 + 8), s1 = *(const f32x4*)(cs + pos * 16 + 12);
; #pragma unroll
;                         for (int i = 0; i < 8; ++i) {
;                             const float c = i < 4 ? c0[i & 3] : c1[i & 3], s = i < 4 ? s0[i & 3] : s1[i & 3];
;                             const float pr = peer_x16(v[i], fq);
;                             const float r = (fq == 0) ? (v[i] * c - pr * s) : (v[i] * c + pr * s);
;                             v[i] = (fq < 2) ? r : v[i];
;                         }
;                     }
;                     if (kind == 0) {
; #pragma unroll
;                         for (int i = 0; i < 8; ++i) v[i] *= C2Q;
;                     }
;                     { u32x4 w; w.x = cvt_pk_bf16(v[0], v[1]); w.y = cvt_pk_bf16(v[2], v[3]); w.z = cvt_pk_bf16(v[4], v[5]); w.w = cvt_pk_bf16(v[6], v[7]);
;                       *(PG8_LAS u32x4*)(stg + fr * 144 + fq * 16 + bj * 64) = w; }
;                 }
;                 {
;                     int kind;
;                     if (odd) kind = (u.pn < 6) ? 0 : (u.pn == 6 ? 1 : 2);
;                     else     kind = (u.pn < 2) ? 0 : (u.pn == 2 ? (wc < 2 ? 1 : 2) : 3);
; #pragma unroll
;                     for (int i = 0; i < 2; ++i) { const int c = fq * 16 + fr + 64 * i, rr = c >> 3, pc = c & 7;
;                         const u32x4 w = *(const PG8_LAS u32x4*)(stg + rr * 144 + pc * 16);
.Lalign_ipeP:
	v_pk_mul_f32 v[102:103], v[102:103], v[152:153] op_sel:[0,1]
	v_pk_mul_f32 v[104:105], v[104:105], v[152:153] op_sel:[0,1]
	v_pk_mul_f32 v[98:99], v[98:99], v[152:153] op_sel:[0,1]
	v_pk_mul_f32 v[100:101], v[100:101], v[152:153] op_sel:[0,1]
	v_cvt_pk_bf16_f32 v102, v102, v103
	v_cvt_pk_bf16_f32 v103, v104, v105
	v_cvt_pk_bf16_f32 v104, v98, v99
	v_cvt_pk_bf16_f32 v105, v100, v101
	v_pk_mul_f32 v[110:111], v[110:111], v[152:153] op_sel:[0,1]
	v_pk_mul_f32 v[112:113], v[112:113], v[152:153] op_sel:[0,1]
	v_pk_mul_f32 v[106:107], v[106:107], v[152:153] op_sel:[0,1]
	v_pk_mul_f32 v[108:109], v[108:109], v[152:153] op_sel:[0,1]
	s_waitcnt lgkmcnt(0)
	v_cvt_pk_bf16_f32 v110, v110, v111
	v_cvt_pk_bf16_f32 v111, v112, v113
	v_cvt_pk_bf16_f32 v112, v106, v107
	v_cvt_pk_bf16_f32 v113, v108, v109
	s_mov_b32 s100, s98
	s_mov_b32 s101, s99
	global_store_dwordx4 v200, v[122:125], s[100:101] nt
	s_add_u32 s100, s100, s67
	s_addc_u32 s101, s101, 0
	global_store_dwordx4 v200, v[114:117], s[100:101] nt
	ds_write_b128 v178, v[110:113]
	ds_write_b128 v178, v[102:105] offset:64
	ds_read_b128 v[106:109], v180
	ds_read_b128 v[98:101], v180 offset:1152
	v_pk_mul_f32 v[86:87], v[86:87], v[150:151] op_sel_hi:[1,0]
	v_pk_mul_f32 v[88:89], v[88:89], v[150:151] op_sel_hi:[1,0]
	v_pk_mul_f32 v[82:83], v[82:83], v[150:151] op_sel_hi:[1,0]
	v_pk_mul_f32 v[84:85], v[84:85], v[150:151] op_sel_hi:[1,0]
	v_cvt_pk_bf16_f32 v86, v86, v87
	v_cvt_pk_bf16_f32 v87, v88, v89
	v_cvt_pk_bf16_f32 v88, v82, v83
	v_cvt_pk_bf16_f32 v89, v84, v85
	v_pk_mul_f32 v[94:95], v[94:95], v[150:151] op_sel_hi:[1,0]
	v_pk_mul_f32 v[96:97], v[96:97], v[150:151] op_sel_hi:[1,0]
	v_pk_mul_f32 v[90:91], v[90:91], v[150:151] op_sel_hi:[1,0]
	v_pk_mul_f32 v[92:93], v[92:93], v[150:151] op_sel_hi:[1,0]
	s_waitcnt lgkmcnt(0)
	v_cvt_pk_bf16_f32 v94, v94, v95
	v_cvt_pk_bf16_f32 v95, v96, v97
	v_cvt_pk_bf16_f32 v96, v90, v91
	v_cvt_pk_bf16_f32 v97, v92, v93
	s_mul_i32 s44, s66, 16
	s_add_u32 s100, s98, s44
	s_addc_u32 s101, s99, 0
	global_store_dwordx4 v200, v[106:109], s[100:101] nt
	s_add_u32 s100, s100, s67
	s_addc_u32 s101, s101, 0
	global_store_dwordx4 v200, v[98:101], s[100:101] nt
	ds_write_b128 v178, v[94:97]
	ds_write_b128 v178, v[86:89] offset:64
	ds_read_b128 v[90:93], v180
	ds_read_b128 v[82:85], v180 offset:1152
	v_pk_mul_f32 v[70:71], v[70:71], v[150:151] op_sel:[0,1]
	v_pk_mul_f32 v[72:73], v[72:73], v[150:151] op_sel:[0,1]
	v_pk_mul_f32 v[66:67], v[66:67], v[150:151] op_sel:[0,1]
	v_pk_mul_f32 v[68:69], v[68:69], v[150:151] op_sel:[0,1]
	v_cvt_pk_bf16_f32 v70, v70, v71
	v_cvt_pk_bf16_f32 v71, v72, v73
	v_cvt_pk_bf16_f32 v72, v66, v67
	v_cvt_pk_bf16_f32 v73, v68, v69
	v_pk_mul_f32 v[78:79], v[78:79], v[150:151] op_sel:[0,1]
	v_pk_mul_f32 v[80:81], v[80:81], v[150:151] op_sel:[0,1]
	v_pk_mul_f32 v[74:75], v[74:75], v[150:151] op_sel:[0,1]
	v_pk_mul_f32 v[76:77], v[76:77], v[150:151] op_sel:[0,1]
	s_waitcnt lgkmcnt(0)
	v_cvt_pk_bf16_f32 v78, v78, v79
	v_cvt_pk_bf16_f32 v79, v80, v81
	v_cvt_pk_bf16_f32 v80, v74, v75
	v_cvt_pk_bf16_f32 v81, v76, v77
	s_mul_i32 s44, s66, 32
	s_add_u32 s100, s98, s44
	s_addc_u32 s101, s99, 0
	global_store_dwordx4 v200, v[90:93], s[100:101] nt
	s_add_u32 s100, s100, s67
	s_addc_u32 s101, s101, 0
	global_store_dwordx4 v200, v[82:85], s[100:101] nt
	ds_write_b128 v178, v[78:81]
	ds_write_b128 v178, v[70:73] offset:64
	ds_read_b128 v[74:77], v180
	ds_read_b128 v[66:69], v180 offset:1152
	v_pk_mul_f32 v[54:55], v[54:55], v[148:149] op_sel_hi:[1,0]
	v_pk_mul_f32 v[56:57], v[56:57], v[148:149] op_sel_hi:[1,0]
	v_pk_mul_f32 v[50:51], v[50:51], v[148:149] op_sel_hi:[1,0]
	v_pk_mul_f32 v[52:53], v[52:53], v[148:149] op_sel_hi:[1,0]
	v_cvt_pk_bf16_f32 v54, v54, v55
	v_cvt_pk_bf16_f32 v55, v56, v57
	v_cvt_pk_bf16_f32 v56, v50, v51
	v_cvt_pk_bf16_f32 v57, v52, v53
	v_pk_mul_f32 v[62:63], v[62:63], v[148:149] op_sel_hi:[1,0]
	v_pk_mul_f32 v[64:65], v[64:65], v[148:149] op_sel_hi:[1,0]
	v_pk_mul_f32 v[58:59], v[58:59], v[148:149] op_sel_hi:[1,0]
	v_pk_mul_f32 v[60:61], v[60:61], v[148:149] op_sel_hi:[1,0]
	s_waitcnt lgkmcnt(0)
;     __device__ __forceinline__ void operator()(const f32x4 (&acc)[2][2][4][2], const Unit& u, int wr, int wc, int fr, int fq, PG8_LAS float* stash, int par, PG8_LAS unsigned char* stg, const Unit& un) const {
;     ...
;                 const int row = u.pm * BM + ai * HALF + wr * 64 + m * 16 + fr, pos = row & 4095, b = row >> 12;
;                 const float rs = rsa[ai][m];
; #pragma unroll
;                 for (int bj = 0; bj < 2; ++bj) {
;                     int kind;
;                     if (odd) kind = (u.pn < 6) ? 0 : (u.pn == 6 ? 1 : 2);
;                     else     kind = (u.pn < 2) ? 0 : (u.pn == 2 ? (wc < 2 ? 1 : 2) : 3);
;                     float v[8];
; #pragma unroll
;                     for (int i = 0; i < 4; ++i) { v[i] = acc[ai][bj][m][0][i] * rs; v[4 + i] = acc[ai][bj][m][1][i] * rs; }
;                     if (kind <= 1 && bj == 0) {
;                         const f32x4 c0 = *(const f32x4*)(cs + pos * 16), c1 = *(const f32x4*)(cs + pos * 16 + 4), s0 = *(const f32x4*)(cs + pos * 16 + 8), s1 = *(const f32x4*)(cs + pos * 16 + 12);
; #pragma unroll
;                         for (int i = 0; i < 8; ++i) {
;                             const float c = i < 4 ? c0[i & 3] : c1[i & 3], s = i < 4 ? s0[i & 3] : s1[i & 3];
;                             const float pr = peer_x16(v[i], fq);
;                             const float r = (fq == 0) ? (v[i] * c - pr * s) : (v[i] * c + pr * s);
;                             v[i] = (fq < 2) ? r : v[i];
;                         }
;                     }
;                     if (kind == 0) {
; #pragma unroll
;                         for (int i = 0; i < 8; ++i) v[i] *= C2Q;
;                     }
;                     { u32x4 w; w.x = cvt_pk_bf16(v[0], v[1]); w.y = cvt_pk_bf16(v[2], v[3]); w.z = cvt_pk_bf16(v[4], v[5]); w.w = cvt_pk_bf16(v[6], v[7]);
;                       *(PG8_LAS u32x4*)(stg + fr * 144 + fq * 16 + bj * 64) = w; }
;                 }
;                 {
;                     int kind;
;                     if (odd) kind = (u.pn < 6) ? 0 : (u.pn == 6 ? 1 : 2);
;                     else     kind = (u.pn < 2) ? 0 : (u.pn == 2 ? (wc < 2 ? 1 : 2) : 3);
; #pragma unroll
;                     for (int i = 0; i < 2; ++i) { const int c = fq * 16 + fr + 64 * i, rr = c >> 3, pc = c & 7;
;                         const u32x4 w = *(const PG8_LAS u32x4*)(stg + rr * 144 + pc * 16);
	v_cvt_pk_bf16_f32 v62, v62, v63
	v_cvt_pk_bf16_f32 v63, v64, v65
	v_cvt_pk_bf16_f32 v64, v58, v59
	v_cvt_pk_bf16_f32 v65, v60, v61
	s_mul_i32 s44, s66, 48
	s_add_u32 s100, s98, s44
	s_addc_u32 s101, s99, 0
	global_store_dwordx4 v200, v[74:77], s[100:101] nt
	s_add_u32 s100, s100, s67
	s_addc_u32 s101, s101, 0
	global_store_dwordx4 v200, v[66:69], s[100:101] nt
	ds_write_b128 v178, v[62:65]
	ds_write_b128 v178, v[54:57] offset:64
	ds_read_b128 v[58:61], v180
	ds_read_b128 v[50:53], v180 offset:1152
	v_pk_mul_f32 v[38:39], v[38:39], v[148:149] op_sel:[0,1]
	v_pk_mul_f32 v[40:41], v[40:41], v[148:149] op_sel:[0,1]
	v_pk_mul_f32 v[34:35], v[34:35], v[148:149] op_sel:[0,1]
	v_pk_mul_f32 v[36:37], v[36:37], v[148:149] op_sel:[0,1]
	v_cvt_pk_bf16_f32 v38, v38, v39
	v_cvt_pk_bf16_f32 v39, v40, v41
	v_cvt_pk_bf16_f32 v40, v34, v35
	v_cvt_pk_bf16_f32 v41, v36, v37
	v_pk_mul_f32 v[46:47], v[46:47], v[148:149] op_sel:[0,1]
	v_pk_mul_f32 v[48:49], v[48:49], v[148:149] op_sel:[0,1]
	v_pk_mul_f32 v[42:43], v[42:43], v[148:149] op_sel:[0,1]
	v_pk_mul_f32 v[44:45], v[44:45], v[148:149] op_sel:[0,1]
	s_waitcnt lgkmcnt(0)
	v_cvt_pk_bf16_f32 v46, v46, v47
	v_cvt_pk_bf16_f32 v47, v48, v49
	v_cvt_pk_bf16_f32 v48, v42, v43
	v_cvt_pk_bf16_f32 v49, v44, v45
	s_mul_i32 s44, s66, 128
	s_add_u32 s100, s98, s44
	s_addc_u32 s101, s99, 0
	global_store_dwordx4 v200, v[58:61], s[100:101] nt
	s_add_u32 s100, s100, s67
	s_addc_u32 s101, s101, 0
	global_store_dwordx4 v200, v[50:53], s[100:101] nt
	ds_write_b128 v178, v[46:49]
	ds_write_b128 v178, v[38:41] offset:64
	ds_read_b128 v[42:45], v180
	ds_read_b128 v[34:37], v180 offset:1152
	v_pk_mul_f32 v[22:23], v[22:23], v[146:147] op_sel_hi:[1,0]
	v_pk_mul_f32 v[24:25], v[24:25], v[146:147] op_sel_hi:[1,0]
	v_pk_mul_f32 v[18:19], v[18:19], v[146:147] op_sel_hi:[1,0]
	v_pk_mul_f32 v[20:21], v[20:21], v[146:147] op_sel_hi:[1,0]
	v_cvt_pk_bf16_f32 v22, v22, v23
	v_cvt_pk_bf16_f32 v23, v24, v25
	v_cvt_pk_bf16_f32 v24, v18, v19
	v_cvt_pk_bf16_f32 v25, v20, v21
	v_pk_mul_f32 v[30:31], v[30:31], v[146:147] op_sel_hi:[1,0]
	v_pk_mul_f32 v[32:33], v[32:33], v[146:147] op_sel_hi:[1,0]
	v_pk_mul_f32 v[26:27], v[26:27], v[146:147] op_sel_hi:[1,0]
	v_pk_mul_f32 v[28:29], v[28:29], v[146:147] op_sel_hi:[1,0]
	s_waitcnt lgkmcnt(0)
	v_cvt_pk_bf16_f32 v30, v30, v31
	v_cvt_pk_bf16_f32 v31, v32, v33
	v_cvt_pk_bf16_f32 v32, v26, v27
	v_cvt_pk_bf16_f32 v33, v28, v29
	s_mul_i32 s44, s66, 144
	s_add_u32 s100, s98, s44
	s_addc_u32 s101, s99, 0
	global_store_dwordx4 v200, v[42:45], s[100:101] nt
	s_add_u32 s100, s100, s67
	s_addc_u32 s101, s101, 0
	global_store_dwordx4 v200, v[34:37], s[100:101] nt
	ds_write_b128 v178, v[30:33]
	ds_write_b128 v178, v[22:25] offset:64
	ds_read_b128 v[26:29], v180
	ds_read_b128 v[18:21], v180 offset:1152
	v_pk_mul_f32 v[6:7], v[6:7], v[146:147] op_sel:[0,1]
	v_pk_mul_f32 v[8:9], v[8:9], v[146:147] op_sel:[0,1]
	v_pk_mul_f32 v[2:3], v[2:3], v[146:147] op_sel:[0,1]
	v_pk_mul_f32 v[4:5], v[4:5], v[146:147] op_sel:[0,1]
	v_cvt_pk_bf16_f32 v6, v6, v7
	v_cvt_pk_bf16_f32 v7, v8, v9
	v_cvt_pk_bf16_f32 v8, v2, v3
	v_cvt_pk_bf16_f32 v9, v4, v5
	v_pk_mul_f32 v[14:15], v[14:15], v[146:147] op_sel:[0,1]
	v_pk_mul_f32 v[16:17], v[16:17], v[146:147] op_sel:[0,1]
	v_pk_mul_f32 v[10:11], v[10:11], v[146:147] op_sel:[0,1]
	v_pk_mul_f32 v[12:13], v[12:13], v[146:147] op_sel:[0,1]
	s_waitcnt lgkmcnt(0)
	v_cvt_pk_bf16_f32 v14, v14, v15
	v_cvt_pk_bf16_f32 v15, v16, v17
	v_cvt_pk_bf16_f32 v16, v10, v11
	v_cvt_pk_bf16_f32 v17, v12, v13
	s_mul_i32 s44, s66, 160
	s_add_u32 s100, s98, s44
	s_addc_u32 s101, s99, 0
	global_store_dwordx4 v200, v[26:29], s[100:101] nt
	s_add_u32 s100, s100, s67
	s_addc_u32 s101, s101, 0
	global_store_dwordx4 v200, v[18:21], s[100:101] nt
	ds_write_b128 v178, v[14:17]
	ds_write_b128 v178, v[6:9] offset:64
	ds_read_b128 v[10:13], v180
	ds_read_b128 v[2:5], v180 offset:1152
	s_waitcnt lgkmcnt(0)
	s_mul_i32 s44, s66, 176
	s_add_u32 s100, s98, s44
	s_addc_u32 s101, s99, 0
	global_store_dwordx4 v200, v[10:13], s[100:101] nt
	s_add_u32 s100, s100, s67
	s_addc_u32 s101, s101, 0
	global_store_dwordx4 v200, v[2:5], s[100:101] nt

; #define PG8_STAGE(bufoff, gbase, voff) do { _Pragma("unroll") for (int _i = 0; _i < 2; ++_i) \
;         __builtin_amdgcn_global_load_lds((const unsigned*)((const char*)(gbase) + (voff)[_i]), (PG8_LAS unsigned*)(lds + (bufoff) + ldsw + _i * 8192), 16, 0, 0); } while (0)
; #define PG8_LDA(dst, b, h) do { _Pragma("unroll") for (int m = 0; m < 4; ++m) _Pragma("unroll") for (int k = 0; k < 2; ++k) dst[m][k] = *(const PG8_LAS bf16x8*)(lds + PG8_SA(b, h) + aoff + m * 2048 + k * 1024); } while (0)
; #define PG8_LDB(dst, b, h) do { _Pragma("unroll") for (int n = 0; n < 2; ++n) _Pragma("unroll") for (int k = 0; k < 2; ++k) dst[n][k] = *(const PG8_LAS bf16x8*)(lds + PG8_SB(b, h) + boff + n * 2048 + k * 1024); } while (0)
; #define PG8_WAIT_V(n) asm volatile("s_waitcnt vmcnt(" #n ")" ::: "memory")
; #define PG8_WAIT_L(n) asm volatile("s_waitcnt lgkmcnt(" #n ")" ::: "memory")
; #define PG8_BAR __builtin_amdgcn_s_barrier()
; #define PG8_SCHED __builtin_amdgcn_sched_barrier(0)
; template <class Epi, class Sched, bool ALIGN_EPI = false, bool SP2 = false>
; __device__ __forceinline__ void gemm_phase(PG8_LAS unsigned char* lds, const Gemm g, const Sched& S, const Epi& E, const int wave_s) {
;     ...
;         const char* nA = has_next ? (const char*)g.A + (size_t)nxt.pm * tstep : cA; const char* nB = has_next ? (const char*)g.Bt + (size_t)nxt.pn * tstep : cB;
;         for (int t = 0; t < nt; t += 2) {
;             const bool last = (t == nt - 2);
;             const char* a1 = cA + (size_t)(t + 1) * kstep;
;             const char* a2 = last ? nA : cA + (size_t)(t + 2) * kstep; const char* b2 = last ? nB : cB + (size_t)(t + 2) * kstep;
;             const char* a3 = a2 + kstep; const char* b3 = b2 + kstep;
;             if (last && has_next) S.a_ready(nxt);
;             if constexpr (SP2) {
;             PG8_LDB(B0, 0, 0); PG8_LDB(B1, 0, 1); PG8_SCHED; PG8_LDA(At, 0, 0); PG8_STAGE(PG8_SA(1, 1), a1 + hstep, voffA);
;             PG8_WAIT_V(8); PG8_WAIT_L(0); PG8_BAR; PG8_MMA(0, 0, At, B0); PG8_MMA(0, 1, At, B1); PG8_BAR; PG8_SCHED;
;             PG8_LDA(At, 0, 1); PG8_STAGE(PG8_SB(0, 0), b2, voffB); PG8_STAGE(PG8_SB(0, 1), b2 + bhstep, voffB); PG8_STAGE(PG8_SA(0, 0), a2, voffA);
;             PG8_WAIT_V(8); PG8_WAIT_L(0); PG8_BAR; PG8_MMA(1, 0, At, B0); PG8_MMA(1, 1, At, B1); PG8_BAR; PG8_SCHED;
.LBB0_753:
	s_add_i32 s54, s48, 2
	s_add_u32 s55, s44, 0x80
	s_addc_u32 s49, s45, 0
	s_add_i32 s60, 0, 0x10000
	s_cmp_eq_u32 s16, s48
	s_cselect_b32 s49, s39, s49
	s_cselect_b32 s48, s47, s55
	s_cselect_b32 s57, s29, s53
	s_cselect_b32 s56, s51, s52
	s_add_i32 s55, 0, 0x14000
	v_add_u32_e32 v142, s60, v205
	v_add_u32_e32 v160, s55, v205
	ds_read_b128 v[130:133], v142
	ds_read_b128 v[134:137], v142 offset:1024
	ds_read_b128 v[138:141], v142 offset:2048
	ds_read_b128 v[142:145], v142 offset:3072
	ds_read_b128 v[146:149], v160
	ds_read_b128 v[150:153], v160 offset:1024
	ds_read_b128 v[154:157], v160 offset:2048
	ds_read_b128 v[160:163], v160 offset:3072
	v_lshl_add_u64 v[220:221], s[44:45], 0, v[178:179]
	s_add_i32 m0, s7, 0xc000
	ds_read_b128 v[164:167], v208
	ds_read_b128 v[182:185], v208 offset:1024
	ds_read_b128 v[186:189], v208 offset:2048
	ds_read_b128 v[190:193], v208 offset:3072
	ds_read_b128 v[194:197], v208 offset:4096
	ds_read_b128 v[198:201], v208 offset:5120
	ds_read_b128 v[212:215], v208 offset:6144
	ds_read_b128 v[216:219], v208 offset:7168
	global_load_lds_dwordx4 v[220:221], off
	v_lshl_add_u64 v[220:221], s[44:45], 0, v[180:181]
	s_add_i32 m0, s7, 0xe000
	s_nop 0
	global_load_lds_dwordx4 v[220:221], off
	s_waitcnt vmcnt(8)
	s_waitcnt lgkmcnt(0)
	s_barrier
	s_setprio 1
	s_waitcnt lgkmcnt(0)
	v_mfma_f32_16x16x32_bf16 v[126:129], v[130:133], v[164:167], v[126:129]
	v_mfma_f32_16x16x32_bf16 v[126:129], v[134:137], v[182:185], v[126:129]
	v_mfma_f32_16x16x32_bf16 v[122:125], v[138:141], v[164:167], v[122:125]
	v_mfma_f32_16x16x32_bf16 v[122:125], v[142:145], v[182:185], v[122:125]
	v_mfma_f32_16x16x32_bf16 v[110:113], v[130:133], v[186:189], v[110:113]
	v_mfma_f32_16x16x32_bf16 v[110:113], v[134:137], v[190:193], v[110:113]
	v_mfma_f32_16x16x32_bf16 v[106:109], v[138:141], v[186:189], v[106:109]
	v_mfma_f32_16x16x32_bf16 v[106:109], v[142:145], v[190:193], v[106:109]
	v_mfma_f32_16x16x32_bf16 v[94:97], v[130:133], v[194:197], v[94:97]
	v_mfma_f32_16x16x32_bf16 v[94:97], v[134:137], v[198:201], v[94:97]
	v_mfma_f32_16x16x32_bf16 v[90:93], v[138:141], v[194:197], v[90:93]
	v_mfma_f32_16x16x32_bf16 v[90:93], v[142:145], v[198:201], v[90:93]
	v_mfma_f32_16x16x32_bf16 v[78:81], v[130:133], v[212:215], v[78:81]
	v_mfma_f32_16x16x32_bf16 v[78:81], v[134:137], v[216:219], v[78:81]
	v_mfma_f32_16x16x32_bf16 v[74:77], v[138:141], v[212:215], v[74:77]
	v_mfma_f32_16x16x32_bf16 v[74:77], v[142:145], v[216:219], v[74:77]
	s_setprio 0
	s_setprio 1
	v_mfma_f32_16x16x32_bf16 v[118:121], v[146:149], v[164:167], v[118:121]
	v_mfma_f32_16x16x32_bf16 v[118:121], v[150:153], v[182:185], v[118:121]
	v_mfma_f32_16x16x32_bf16 v[114:117], v[154:157], v[164:167], v[114:117]
	v_mfma_f32_16x16x32_bf16 v[114:117], v[160:163], v[182:185], v[114:117]
	v_mfma_f32_16x16x32_bf16 v[102:105], v[146:149], v[186:189], v[102:105]
	v_mfma_f32_16x16x32_bf16 v[102:105], v[150:153], v[190:193], v[102:105]
	v_mfma_f32_16x16x32_bf16 v[98:101], v[154:157], v[186:189], v[98:101]
	v_mfma_f32_16x16x32_bf16 v[98:101], v[160:163], v[190:193], v[98:101]
	v_mfma_f32_16x16x32_bf16 v[86:89], v[146:149], v[194:197], v[86:89]
	v_mfma_f32_16x16x32_bf16 v[86:89], v[150:153], v[198:201], v[86:89]
	v_mfma_f32_16x16x32_bf16 v[82:85], v[154:157], v[194:197], v[82:85]
	v_mfma_f32_16x16x32_bf16 v[82:85], v[160:163], v[198:201], v[82:85]
	v_mfma_f32_16x16x32_bf16 v[70:73], v[146:149], v[212:215], v[70:73]
	v_mfma_f32_16x16x32_bf16 v[70:73], v[150:153], v[216:219], v[70:73]
	v_mfma_f32_16x16x32_bf16 v[66:69], v[154:157], v[212:215], v[66:69]
	v_mfma_f32_16x16x32_bf16 v[66:69], v[160:163], v[216:219], v[66:69]
	s_setprio 0
	s_barrier
	s_add_i32 s60, s60, s5
	v_lshl_add_u64 v[220:221], s[56:57], 0, v[170:171]
	s_mov_b32 m0, s60
	ds_read_b128 v[164:167], v208 offset:16384
	ds_read_b128 v[182:185], v208 offset:17408
	ds_read_b128 v[186:189], v208 offset:18432
	ds_read_b128 v[190:193], v208 offset:19456
	ds_read_b128 v[194:197], v208 offset:20480
	ds_read_b128 v[198:201], v208 offset:21504
	ds_read_b128 v[212:215], v208 offset:22528
	ds_read_b128 v[216:219], v208 offset:23552
	global_load_lds_dwordx4 v[220:221], off
	s_add_i32 m0, s60, 0x2000
	v_lshl_add_u64 v[222:223], s[56:57], 0, v[158:159]
	s_add_u32 s56, s56, s4
	s_addc_u32 s57, s57, 0
	s_add_i32 s55, s55, s5
	global_load_lds_dwordx4 v[222:223], off
	v_lshl_add_u64 v[224:225], s[56:57], 0, v[170:171]
	s_mov_b32 m0, s55
	v_lshl_add_u64 v[226:227], s[56:57], 0, v[158:159]
	global_load_lds_dwordx4 v[224:225], off
	s_add_i32 m0, s55, 0x2000
	v_lshl_add_u64 v[228:229], s[48:49], 0, v[172:173]
	global_load_lds_dwordx4 v[226:227], off
	s_mov_b32 m0, s7
	v_lshl_add_u64 v[230:231], s[48:49], 0, v[168:169]
	global_load_lds_dwordx4 v[228:229], off
	s_mov_b32 m0, s8
	s_nop 0
	global_load_lds_dwordx4 v[230:231], off
	s_waitcnt vmcnt(8)
	s_waitcnt lgkmcnt(0)
	s_barrier
; #define PG8_STAGE(bufoff, gbase, voff) do { _Pragma("unroll") for (int _i = 0; _i < 2; ++_i) \
;         __builtin_amdgcn_global_load_lds((const unsigned*)((const char*)(gbase) + (voff)[_i]), (PG8_LAS unsigned*)(lds + (bufoff) + ldsw + _i * 8192), 16, 0, 0); } while (0)
; #define PG8_LDA(dst, b, h) do { _Pragma("unroll") for (int m = 0; m < 4; ++m) _Pragma("unroll") for (int k = 0; k < 2; ++k) dst[m][k] = *(const PG8_LAS bf16x8*)(lds + PG8_SA(b, h) + aoff + m * 2048 + k * 1024); } while (0)
; #define PG8_LDB(dst, b, h) do { _Pragma("unroll") for (int n = 0; n < 2; ++n) _Pragma("unroll") for (int k = 0; k < 2; ++k) dst[n][k] = *(const PG8_LAS bf16x8*)(lds + PG8_SB(b, h) + boff + n * 2048 + k * 1024); } while (0)
; #define PG8_MMA(ai, bj, At, Bt) do { __builtin_amdgcn_s_setprio(1); _Pragma("unroll") for (int m = 0; m < 4; ++m) _Pragma("unroll") for (int n = 0; n < 2; ++n) _Pragma("unroll") for (int k = 0; k < 2; ++k) \
;         acc[ai][bj][m][n] = __builtin_amdgcn_mfma_f32_16x16x32_bf16(Bt[n][k], At[m][k], acc[ai][bj][m][n], 0, 0, 0); __builtin_amdgcn_s_setprio(0); } while (0)
; #define PG8_WAIT_V(n) asm volatile("s_waitcnt vmcnt(" #n ")" ::: "memory")
; #define PG8_WAIT_L(n) asm volatile("s_waitcnt lgkmcnt(" #n ")" ::: "memory")
; #define PG8_BAR __builtin_amdgcn_s_barrier()
; #define PG8_SCHED __builtin_amdgcn_sched_barrier(0)
; template <class Epi, class Sched, bool ALIGN_EPI = false, bool SP2 = false>
; __device__ __forceinline__ void gemm_phase(PG8_LAS unsigned char* lds, const Gemm g, const Sched& S, const Epi& E, const int wave_s) {
;     ...
;             PG8_WAIT_V(8); PG8_WAIT_L(0); PG8_BAR; PG8_MMA(1, 0, At, B0); PG8_MMA(1, 1, At, B1); PG8_BAR; PG8_SCHED;
;             PG8_LDB(B0, 1, 0); PG8_LDB(B1, 1, 1); PG8_SCHED; PG8_LDA(At, 1, 0); PG8_STAGE(PG8_SA(0, 1), a2 + hstep, voffA);
;             PG8_WAIT_V(8); PG8_WAIT_L(0); PG8_BAR; PG8_MMA(0, 0, At, B0); PG8_MMA(0, 1, At, B1); PG8_BAR; PG8_SCHED;
	s_setprio 1
	s_waitcnt lgkmcnt(0)
	v_mfma_f32_16x16x32_bf16 v[62:65], v[130:133], v[164:167], v[62:65]
	v_mfma_f32_16x16x32_bf16 v[62:65], v[134:137], v[182:185], v[62:65]
	v_mfma_f32_16x16x32_bf16 v[58:61], v[138:141], v[164:167], v[58:61]
	v_mfma_f32_16x16x32_bf16 v[58:61], v[142:145], v[182:185], v[58:61]
	v_mfma_f32_16x16x32_bf16 v[46:49], v[130:133], v[186:189], v[46:49]
	v_mfma_f32_16x16x32_bf16 v[46:49], v[134:137], v[190:193], v[46:49]
	v_mfma_f32_16x16x32_bf16 v[42:45], v[138:141], v[186:189], v[42:45]
	v_mfma_f32_16x16x32_bf16 v[42:45], v[142:145], v[190:193], v[42:45]
	v_mfma_f32_16x16x32_bf16 v[30:33], v[130:133], v[194:197], v[30:33]
	v_mfma_f32_16x16x32_bf16 v[30:33], v[134:137], v[198:201], v[30:33]
	v_mfma_f32_16x16x32_bf16 v[26:29], v[138:141], v[194:197], v[26:29]
	v_mfma_f32_16x16x32_bf16 v[26:29], v[142:145], v[198:201], v[26:29]
	v_mfma_f32_16x16x32_bf16 v[14:17], v[130:133], v[212:215], v[14:17]
	v_mfma_f32_16x16x32_bf16 v[14:17], v[134:137], v[216:219], v[14:17]
	v_mfma_f32_16x16x32_bf16 v[10:13], v[138:141], v[212:215], v[10:13]
	v_mfma_f32_16x16x32_bf16 v[10:13], v[142:145], v[216:219], v[10:13]
	s_setprio 0
	s_setprio 1
	v_mfma_f32_16x16x32_bf16 v[54:57], v[146:149], v[164:167], v[54:57]
	v_mfma_f32_16x16x32_bf16 v[54:57], v[150:153], v[182:185], v[54:57]
	v_mfma_f32_16x16x32_bf16 v[50:53], v[154:157], v[164:167], v[50:53]
	v_mfma_f32_16x16x32_bf16 v[50:53], v[160:163], v[182:185], v[50:53]
	v_mfma_f32_16x16x32_bf16 v[38:41], v[146:149], v[186:189], v[38:41]
	v_mfma_f32_16x16x32_bf16 v[38:41], v[150:153], v[190:193], v[38:41]
	v_mfma_f32_16x16x32_bf16 v[34:37], v[154:157], v[186:189], v[34:37]
	v_mfma_f32_16x16x32_bf16 v[34:37], v[160:163], v[190:193], v[34:37]
	v_mfma_f32_16x16x32_bf16 v[22:25], v[146:149], v[194:197], v[22:25]
	v_mfma_f32_16x16x32_bf16 v[22:25], v[150:153], v[198:201], v[22:25]
	v_mfma_f32_16x16x32_bf16 v[18:21], v[154:157], v[194:197], v[18:21]
	v_mfma_f32_16x16x32_bf16 v[18:21], v[160:163], v[198:201], v[18:21]
	v_mfma_f32_16x16x32_bf16 v[6:9], v[146:149], v[212:215], v[6:9]
	v_mfma_f32_16x16x32_bf16 v[6:9], v[150:153], v[216:219], v[6:9]
	v_mfma_f32_16x16x32_bf16 v[2:5], v[154:157], v[212:215], v[2:5]
	v_mfma_f32_16x16x32_bf16 v[2:5], v[160:163], v[216:219], v[2:5]
	s_setprio 0
	s_barrier
	s_add_i32 s55, 0, 0x18000
	s_add_i32 s56, 0, 0x1c000
	v_add_u32_e32 v142, s55, v205
	v_add_u32_e32 v160, s56, v205
	ds_read_b128 v[130:133], v142
	ds_read_b128 v[134:137], v142 offset:1024
	ds_read_b128 v[138:141], v142 offset:2048
	ds_read_b128 v[142:145], v142 offset:3072
	ds_read_b128 v[146:149], v160
	ds_read_b128 v[150:153], v160 offset:1024
	ds_read_b128 v[154:157], v160 offset:2048
	ds_read_b128 v[160:163], v160 offset:3072
	s_add_u32 s48, s48, s74
	s_addc_u32 s49, s49, 0
	s_mov_b32 m0, s9
	v_lshl_add_u64 v[232:233], s[48:49], 0, v[172:173]
	ds_read_b128 v[164:167], v208 offset:32768
	ds_read_b128 v[182:185], v208 offset:33792
	ds_read_b128 v[186:189], v208 offset:34816
	ds_read_b128 v[190:193], v208 offset:35840
	ds_read_b128 v[194:197], v208 offset:36864
	ds_read_b128 v[198:201], v208 offset:37888
	ds_read_b128 v[212:215], v208 offset:38912
	ds_read_b128 v[216:219], v208 offset:39936
	global_load_lds_dwordx4 v[232:233], off
	v_lshl_add_u64 v[232:233], s[48:49], 0, v[168:169]
	s_mov_b32 m0, s10
	s_nop 0
	global_load_lds_dwordx4 v[232:233], off
	s_waitcnt vmcnt(8)
	s_waitcnt lgkmcnt(0)
	s_barrier
	s_setprio 1
	s_waitcnt lgkmcnt(0)
	v_mfma_f32_16x16x32_bf16 v[126:129], v[130:133], v[164:167], v[126:129]
	v_mfma_f32_16x16x32_bf16 v[126:129], v[134:137], v[182:185], v[126:129]
	v_mfma_f32_16x16x32_bf16 v[122:125], v[138:141], v[164:167], v[122:125]
	v_mfma_f32_16x16x32_bf16 v[122:125], v[142:145], v[182:185], v[122:125]
	v_mfma_f32_16x16x32_bf16 v[110:113], v[130:133], v[186:189], v[110:113]
	v_mfma_f32_16x16x32_bf16 v[110:113], v[134:137], v[190:193], v[110:113]
	v_mfma_f32_16x16x32_bf16 v[106:109], v[138:141], v[186:189], v[106:109]
	v_mfma_f32_16x16x32_bf16 v[106:109], v[142:145], v[190:193], v[106:109]
	v_mfma_f32_16x16x32_bf16 v[94:97], v[130:133], v[194:197], v[94:97]
	v_mfma_f32_16x16x32_bf16 v[94:97], v[134:137], v[198:201], v[94:97]
	v_mfma_f32_16x16x32_bf16 v[90:93], v[138:141], v[194:197], v[90:93]
	v_mfma_f32_16x16x32_bf16 v[90:93], v[142:145], v[198:201], v[90:93]
	v_mfma_f32_16x16x32_bf16 v[78:81], v[130:133], v[212:215], v[78:81]
	v_mfma_f32_16x16x32_bf16 v[78:81], v[134:137], v[216:219], v[78:81]
	v_mfma_f32_16x16x32_bf16 v[74:77], v[138:141], v[212:215], v[74:77]
	v_mfma_f32_16x16x32_bf16 v[74:77], v[142:145], v[216:219], v[74:77]
	s_setprio 0
	s_setprio 1
	v_mfma_f32_16x16x32_bf16 v[118:121], v[146:149], v[164:167], v[118:121]
	v_mfma_f32_16x16x32_bf16 v[118:121], v[150:153], v[182:185], v[118:121]
	v_mfma_f32_16x16x32_bf16 v[114:117], v[154:157], v[164:167], v[114:117]
	v_mfma_f32_16x16x32_bf16 v[114:117], v[160:163], v[182:185], v[114:117]
	v_mfma_f32_16x16x32_bf16 v[102:105], v[146:149], v[186:189], v[102:105]
	v_mfma_f32_16x16x32_bf16 v[102:105], v[150:153], v[190:193], v[102:105]
	v_mfma_f32_16x16x32_bf16 v[98:101], v[154:157], v[186:189], v[98:101]
	v_mfma_f32_16x16x32_bf16 v[98:101], v[160:163], v[190:193], v[98:101]
	v_mfma_f32_16x16x32_bf16 v[86:89], v[146:149], v[194:197], v[86:89]
	v_mfma_f32_16x16x32_bf16 v[86:89], v[150:153], v[198:201], v[86:89]
	v_mfma_f32_16x16x32_bf16 v[82:85], v[154:157], v[194:197], v[82:85]
	v_mfma_f32_16x16x32_bf16 v[82:85], v[160:163], v[198:201], v[82:85]
	v_mfma_f32_16x16x32_bf16 v[70:73], v[146:149], v[212:215], v[70:73]
	v_mfma_f32_16x16x32_bf16 v[70:73], v[150:153], v[216:219], v[70:73]
	v_mfma_f32_16x16x32_bf16 v[66:69], v[154:157], v[212:215], v[66:69]
	v_mfma_f32_16x16x32_bf16 v[66:69], v[160:163], v[216:219], v[66:69]
	s_setprio 0
	s_barrier
; #define PG8_STAGE(bufoff, gbase, voff) do { _Pragma("unroll") for (int _i = 0; _i < 2; ++_i) \
;         __builtin_amdgcn_global_load_lds((const unsigned*)((const char*)(gbase) + (voff)[_i]), (PG8_LAS unsigned*)(lds + (bufoff) + ldsw + _i * 8192), 16, 0, 0); } while (0)
; #define PG8_LDA(dst, b, h) do { _Pragma("unroll") for (int m = 0; m < 4; ++m) _Pragma("unroll") for (int k = 0; k < 2; ++k) dst[m][k] = *(const PG8_LAS bf16x8*)(lds + PG8_SA(b, h) + aoff + m * 2048 + k * 1024); } while (0)
; #define PG8_WAIT_V(n) asm volatile("s_waitcnt vmcnt(" #n ")" ::: "memory")
; #define PG8_BAR __builtin_amdgcn_s_barrier()
; template <class Epi, class Sched, bool ALIGN_EPI = false, bool SP2 = false>
; __device__ __forceinline__ void gemm_phase(PG8_LAS unsigned char* lds, const Gemm g, const Sched& S, const Epi& E, const int wave_s) {
;     ...
;             PG8_LDA(At, 1, 1); PG8_STAGE(PG8_SB(1, 0), b3, voffB); PG8_STAGE(PG8_SB(1, 1), b3 + bhstep, voffB); PG8_STAGE(PG8_SA(1, 0), a3, voffA);
;             PG8_WAIT_V(8); PG8_WAIT_L(0); PG8_BAR; PG8_MMA(1, 0, At, B0); PG8_MMA(1, 1, At, B1); PG8_BAR; PG8_SCHED;
;             } else {
;             PG8_LDB(B0, 0, 0); PG8_SCHED; PG8_LDA(At, 0, 0); PG8_STAGE(PG8_SA(1, 1), a1 + hstep, voffA);
;             PG8_WAIT_L(8); PG8_BAR; PG8_WAIT_L(0); PG8_MMA(0, 0, At, B0); PG8_BAR; PG8_SCHED;
;             PG8_LDB(B1, 0, 1); PG8_STAGE(PG8_SB(0, 0), b2, voffB);
;             PG8_BAR; PG8_WAIT_L(0); PG8_MMA(0, 1, At, B1); PG8_BAR;
;             PG8_LDA(At, 0, 1); PG8_STAGE(PG8_SA(0, 0), a2, voffA);
;             PG8_BAR; PG8_WAIT_L(0); PG8_MMA(1, 0, At, B0); PG8_BAR; PG8_SCHED;
;             PG8_STAGE(PG8_SB(0, 1), b2 + bhstep, voffB);
;             PG8_WAIT_V(6); PG8_BAR; PG8_MMA(1, 1, At, B1); PG8_BAR;
;             PG8_LDB(B0, 1, 0); PG8_SCHED; PG8_LDA(At, 1, 0); PG8_STAGE(PG8_SA(0, 1), a2 + hstep, voffA);
;             PG8_WAIT_L(8); PG8_BAR; PG8_WAIT_L(0); PG8_MMA(0, 0, At, B0); PG8_BAR; PG8_SCHED;
;             PG8_LDB(B1, 1, 1); PG8_STAGE(PG8_SB(1, 0), b3, voffB);
;             PG8_BAR; PG8_WAIT_L(0); PG8_MMA(0, 1, At, B1); PG8_BAR;
;             PG8_LDA(At, 1, 1); PG8_STAGE(PG8_SA(1, 0), a3, voffA);
;             PG8_BAR; PG8_WAIT_L(0); PG8_MMA(1, 0, At, B0); PG8_BAR; PG8_SCHED;
;             PG8_STAGE(PG8_SB(1, 1), b3 + bhstep, voffB);
;             PG8_WAIT_V(6); PG8_BAR; PG8_MMA(1, 1, At, B1); PG8_BAR;
;             }
;         }
	s_add_i32 s48, s55, s5
	v_lshl_add_u64 v[220:221], v[220:221], 0, s[24:25]
	s_mov_b32 m0, s48
	ds_read_b128 v[164:167], v208 offset:49152
	ds_read_b128 v[182:185], v208 offset:50176
	ds_read_b128 v[186:189], v208 offset:51200
	ds_read_b128 v[190:193], v208 offset:52224
	ds_read_b128 v[194:197], v208 offset:53248
	ds_read_b128 v[198:201], v208 offset:54272
	ds_read_b128 v[212:215], v208 offset:55296
	ds_read_b128 v[216:219], v208 offset:56320
	global_load_lds_dwordx4 v[220:221], off
	v_lshl_add_u64 v[220:221], v[222:223], 0, s[24:25]
	s_add_i32 m0, s48, 0x2000
	s_add_i32 s48, s56, s5
	global_load_lds_dwordx4 v[220:221], off
	v_lshl_add_u64 v[220:221], v[224:225], 0, s[24:25]
	s_mov_b32 m0, s48
	s_nop 0
	global_load_lds_dwordx4 v[220:221], off
	v_lshl_add_u64 v[220:221], v[226:227], 0, s[24:25]
	s_add_i32 m0, s48, 0x2000
	s_nop 0
	global_load_lds_dwordx4 v[220:221], off
	v_lshl_add_u64 v[220:221], v[228:229], 0, s[24:25]
	s_mov_b32 m0, s11
	s_nop 0
	global_load_lds_dwordx4 v[220:221], off
	v_lshl_add_u64 v[220:221], v[230:231], 0, s[24:25]
	s_mov_b32 m0, s12
	s_nop 0
	global_load_lds_dwordx4 v[220:221], off
	s_waitcnt vmcnt(8)
	s_waitcnt lgkmcnt(0)
	s_barrier
	s_setprio 1
	s_waitcnt lgkmcnt(0)
	v_mfma_f32_16x16x32_bf16 v[62:65], v[130:133], v[164:167], v[62:65]
	v_mfma_f32_16x16x32_bf16 v[62:65], v[134:137], v[182:185], v[62:65]
	v_mfma_f32_16x16x32_bf16 v[58:61], v[138:141], v[164:167], v[58:61]
	v_mfma_f32_16x16x32_bf16 v[58:61], v[142:145], v[182:185], v[58:61]
	v_mfma_f32_16x16x32_bf16 v[46:49], v[130:133], v[186:189], v[46:49]
	v_mfma_f32_16x16x32_bf16 v[46:49], v[134:137], v[190:193], v[46:49]
	v_mfma_f32_16x16x32_bf16 v[42:45], v[138:141], v[186:189], v[42:45]
	v_mfma_f32_16x16x32_bf16 v[42:45], v[142:145], v[190:193], v[42:45]
	v_mfma_f32_16x16x32_bf16 v[30:33], v[130:133], v[194:197], v[30:33]
	v_mfma_f32_16x16x32_bf16 v[30:33], v[134:137], v[198:201], v[30:33]
	v_mfma_f32_16x16x32_bf16 v[26:29], v[138:141], v[194:197], v[26:29]
	v_mfma_f32_16x16x32_bf16 v[26:29], v[142:145], v[198:201], v[26:29]
	v_mfma_f32_16x16x32_bf16 v[14:17], v[130:133], v[212:215], v[14:17]
	v_mfma_f32_16x16x32_bf16 v[14:17], v[134:137], v[216:219], v[14:17]
	v_mfma_f32_16x16x32_bf16 v[10:13], v[138:141], v[212:215], v[10:13]
	v_mfma_f32_16x16x32_bf16 v[10:13], v[142:145], v[216:219], v[10:13]
	s_setprio 0
	s_setprio 1
	v_mfma_f32_16x16x32_bf16 v[54:57], v[146:149], v[164:167], v[54:57]
	v_mfma_f32_16x16x32_bf16 v[54:57], v[150:153], v[182:185], v[54:57]
	v_mfma_f32_16x16x32_bf16 v[50:53], v[154:157], v[164:167], v[50:53]
	v_mfma_f32_16x16x32_bf16 v[50:53], v[160:163], v[182:185], v[50:53]
	v_mfma_f32_16x16x32_bf16 v[38:41], v[146:149], v[186:189], v[38:41]
	v_mfma_f32_16x16x32_bf16 v[38:41], v[150:153], v[190:193], v[38:41]
	v_mfma_f32_16x16x32_bf16 v[34:37], v[154:157], v[186:189], v[34:37]
	v_mfma_f32_16x16x32_bf16 v[34:37], v[160:163], v[190:193], v[34:37]
	v_mfma_f32_16x16x32_bf16 v[22:25], v[146:149], v[194:197], v[22:25]
	v_mfma_f32_16x16x32_bf16 v[22:25], v[150:153], v[198:201], v[22:25]
	v_mfma_f32_16x16x32_bf16 v[18:21], v[154:157], v[194:197], v[18:21]
	v_mfma_f32_16x16x32_bf16 v[18:21], v[160:163], v[198:201], v[18:21]
	v_mfma_f32_16x16x32_bf16 v[6:9], v[146:149], v[212:215], v[6:9]
	v_mfma_f32_16x16x32_bf16 v[6:9], v[150:153], v[216:219], v[6:9]
	v_mfma_f32_16x16x32_bf16 v[2:5], v[154:157], v[212:215], v[2:5]
	v_mfma_f32_16x16x32_bf16 v[2:5], v[160:163], v[216:219], v[2:5]
	s_setprio 0
	s_barrier
	s_add_u32 s44, s44, 0x100
	s_addc_u32 s45, s45, 0
	s_add_u32 s52, s52, 0x100
	s_addc_u32 s53, s53, 0
	s_cmp_ge_u32 s54, s14
	s_mov_b32 s48, s54
	s_cbranch_scc0 .LBB0_753
; #define PG8_LAS __attribute__((address_space(3)))
;     __device__ __forceinline__ void operator()(const f32x4 (&acc)[2][2][4][2], const Unit& u, int wr, int wc, int fr, int fq, PG8_LAS unsigned char* stg) const {
;         const int lane = fq * 16 + fr;
;         const size_t colw = (size_t)u.pn * BM + wc * 64;
;         const int rowb = u.pm * BM + wr * 64;
;         PG8_LAS unsigned char* st = stg + fr * 144 + fq * 16;
; #pragma unroll
;         for (int ai = 0; ai < 2; ++ai) {
;         asm volatile("" ::: "memory");
;         u32x4 xin[4][2];
; #pragma unroll
;         for (int m = 0; m < 4; ++m)
; #pragma unroll
;             for (int i = 0; i < 2; ++i) { const int c = lane + 64 * i; xin[m][i] = *(const u32x4*)(xb + (size_t)(rowb + ai * HALF + m * 16 + (c >> 3)) * 1024 + colw + (c & 7) * 8); }
; #pragma unroll
;         for (int m = 0; m < 4; ++m) {
;             const int row = rowb + ai * HALF + m * 16 + fr;
; #pragma unroll
;             for (int i = 0; i < 2; ++i) { const int c = lane + 64 * i; *(PG8_LAS u32x4*)(stg + (c >> 3) * 144 + (c & 7) * 16) = xin[m][i]; }
;             float ss = 0.f;
; #pragma unroll
;             for (int bj = 0; bj < 2; ++bj) {
;                 const u32x4 xo = *(const PG8_LAS u32x4*)(st + bj * 64);
;                 float v[8];
; #pragma unroll
;                 for (int i = 0; i < 4; ++i) { v[2 * i] = __uint_as_float(xo[i] << 16) + acc[ai][bj][m][i >> 1][(2 * i) & 3]; v[2 * i + 1] = __uint_as_float(xo[i] & 0xffff0000u) + acc[ai][bj][m][i >> 1][(2 * i + 1) & 3]; }
;                 u32x4 w; w.x = cvt_pk_bf16(v[0], v[1]); w.y = cvt_pk_bf16(v[2], v[3]); w.z = cvt_pk_bf16(v[4], v[5]); w.w = cvt_pk_bf16(v[6], v[7]);
;                 *(PG8_LAS u32x4*)(st + bj * 64) = w;
;                 ss += ((v[0] * v[0] + v[1] * v[1]) + (v[2] * v[2] + v[3] * v[3])) + ((v[4] * v[4] + v[5] * v[5]) + (v[6] * v[6] + v[7] * v[7]));
;             }
; #pragma unroll
;             for (int i = 0; i < 2; ++i) { const int c = lane + 64 * i; const u32x4 w = *(const PG8_LAS u32x4*)(stg + (c >> 3) * 144 + (c & 7) * 16);
;                 *(u32x4*)(xo_ + (size_t)(row - fr + (c >> 3)) * 1024 + colw + (c & 7) * 8) = w; }
;             ss = sum_x16(ss); ss = sum_x32(ss);
;             if (fq == 0) po_[(size_t)(u.pn * 4 + wc) * 65536 + row] = ss;
.LBB0_756:
	s_ashr_i32 s47, s46, 31
	s_lshl_b64 s[44:45], s[46:47], 8
	s_lshl_b32 s29, s50, 8
	s_or_b64 s[48:49], s[44:45], s[22:23]
	s_add_i32 s44, s29, s15
	v_or_b32_e32 v130, s44, v206
	s_lshl_b64 s[48:49], s[48:49], 1
	v_ashrrev_i32_e32 v131, 31, v130
	v_lshl_add_u64 v[182:183], v[176:177], 0, s[48:49]
	v_lshlrev_b64 v[198:199], 11, v[130:131]
	v_lshl_add_u64 v[130:131], v[182:183], 0, v[198:199]
	global_load_dwordx4 v[154:157], v[130:131], off
	v_or_b32_e32 v130, s44, v207
	v_ashrrev_i32_e32 v131, 31, v130
	v_lshlrev_b64 v[196:197], 11, v[130:131]
	v_lshl_add_u64 v[130:131], v[182:183], 0, v[196:197]
	global_load_dwordx4 v[160:163], v[130:131], off
	s_lshl_b32 s29, s46, 2
	s_or_b32 s46, s29, s13
	s_or_b32 s29, s44, 16
	v_or_b32_e32 v130, s29, v206
	v_ashrrev_i32_e32 v131, 31, v130
	v_lshlrev_b64 v[194:195], 11, v[130:131]
	v_lshl_add_u64 v[130:131], v[182:183], 0, v[194:195]
	global_load_dwordx4 v[146:149], v[130:131], off
	v_or_b32_e32 v130, s29, v207
	v_ashrrev_i32_e32 v131, 31, v130
	v_lshlrev_b64 v[192:193], 11, v[130:131]
	v_lshl_add_u64 v[130:131], v[182:183], 0, v[192:193]
	s_or_b32 s29, s44, 32
	global_load_dwordx4 v[150:153], v[130:131], off
	v_or_b32_e32 v130, s29, v206
	v_ashrrev_i32_e32 v131, 31, v130
	v_lshlrev_b64 v[188:189], 11, v[130:131]
	v_lshl_add_u64 v[130:131], v[182:183], 0, v[188:189]
	global_load_dwordx4 v[134:137], v[130:131], off
	v_or_b32_e32 v130, s29, v207
	v_ashrrev_i32_e32 v131, 31, v130
	v_lshlrev_b64 v[186:187], 11, v[130:131]
	v_lshl_add_u64 v[130:131], v[182:183], 0, v[186:187]
	s_or_b32 s29, s44, 48
	global_load_dwordx4 v[138:141], v[130:131], off
	v_or_b32_e32 v130, s29, v206
	v_or_b32_e32 v142, s29, v207
	v_ashrrev_i32_e32 v131, 31, v130
	v_ashrrev_i32_e32 v143, 31, v142
	v_lshlrev_b64 v[184:185], 11, v[130:131]
	v_lshlrev_b64 v[190:191], 11, v[142:143]
	v_lshl_add_u64 v[130:131], v[182:183], 0, v[184:185]
	v_lshl_add_u64 v[142:143], v[182:183], 0, v[190:191]
	global_load_dwordx4 v[130:133], v[130:131], off
	s_ashr_i32 s47, s46, 31
	global_load_dwordx4 v[142:145], v[142:143], off
	s_lshl_b64 s[46:47], s[46:47], 18
	s_and_b64 vcc, exec, s[20:21]
	s_cbranch_vccz .Lalign_outproj
	s_barrier
.Lalign_outproj:
	s_waitcnt vmcnt(0)
	ds_write_b128 v209, v[154:157]
	ds_write_b128 v209, v[160:163] offset:1152
	ds_read_b128 v[154:157], v210
	s_waitcnt lgkmcnt(0)
	v_lshlrev_b32_e32 v160, 16, v154
	v_and_b32_e32 v154, 0xffff0000, v154
	v_add_f32_e32 v127, v127, v154
	v_lshlrev_b32_e32 v154, 16, v155
	v_add_f32_e32 v128, v128, v154
	v_and_b32_e32 v154, 0xffff0000, v155
	v_add_f32_e32 v129, v129, v154
	v_lshlrev_b32_e32 v154, 16, v156
	v_add_f32_e32 v154, v122, v154
	v_and_b32_e32 v122, 0xffff0000, v156
	v_add_f32_e32 v155, v123, v122
	v_lshlrev_b32_e32 v122, 16, v157
	v_add_f32_e32 v156, v124, v122
	v_and_b32_e32 v122, 0xffff0000, v157
	v_add_f32_e32 v126, v126, v160
	v_add_f32_e32 v157, v125, v122
	v_cvt_pk_bf16_f32 v122, v126, v127
	v_cvt_pk_bf16_f32 v123, v128, v129
	v_cvt_pk_bf16_f32 v124, v154, v155
	v_cvt_pk_bf16_f32 v125, v156, v157
	ds_write_b128 v210, v[122:125]
	v_mul_f32_e32 v122, v127, v127
	v_mul_f32_e32 v123, v129, v129
	v_fmac_f32_e32 v122, v126, v126
	v_fmac_f32_e32 v123, v128, v128
	v_add_f32_e32 v122, v122, v123
	v_mul_f32_e32 v123, v155, v155
	v_mul_f32_e32 v124, v157, v157
	v_fmac_f32_e32 v123, v154, v154
	v_fmac_f32_e32 v124, v156, v156
	v_add_f32_e32 v123, v123, v124
	v_add_f32_e32 v126, v122, v123
	ds_read_b128 v[122:125], v210 offset:64
	s_waitcnt lgkmcnt(0)
	v_lshlrev_b32_e32 v127, 16, v122
	v_and_b32_e32 v122, 0xffff0000, v122
	v_add_f32_e32 v119, v119, v122
	v_lshlrev_b32_e32 v122, 16, v123
	v_add_f32_e32 v120, v120, v122
	v_and_b32_e32 v122, 0xffff0000, v123
	v_add_f32_e32 v121, v121, v122
	v_lshlrev_b32_e32 v122, 16, v124
	v_add_f32_e32 v122, v114, v122
	v_and_b32_e32 v114, 0xffff0000, v124
	v_add_f32_e32 v123, v115, v114
	v_lshlrev_b32_e32 v114, 16, v125
	v_add_f32_e32 v124, v116, v114
	v_and_b32_e32 v114, 0xffff0000, v125
	v_add_f32_e32 v118, v118, v127
	v_add_f32_e32 v125, v117, v114
	v_cvt_pk_bf16_f32 v114, v118, v119
	v_cvt_pk_bf16_f32 v115, v120, v121
	v_cvt_pk_bf16_f32 v116, v122, v123
	v_cvt_pk_bf16_f32 v117, v124, v125
	ds_write_b128 v210, v[114:117] offset:64
	v_mul_f32_e32 v114, v119, v119
	v_mul_f32_e32 v115, v121, v121
	v_fmac_f32_e32 v114, v118, v118
	v_fmac_f32_e32 v115, v120, v120
	v_add_f32_e32 v114, v114, v115
	v_mul_f32_e32 v115, v123, v123
	v_mul_f32_e32 v116, v125, v125
	v_fmac_f32_e32 v115, v122, v122
	v_fmac_f32_e32 v116, v124, v124
	v_add_f32_e32 v115, v115, v116
	v_add_f32_e32 v114, v114, v115
	v_add_f32_e32 v120, v126, v114
	ds_read_b128 v[114:117], v211
	v_lshl_add_u64 v[118:119], s[76:77], 0, v[198:199]
	v_lshl_add_u64 v[118:119], v[118:119], 0, s[48:49]
	v_lshl_add_u64 v[118:119], v[118:119], 0, v[0:1]
	s_waitcnt lgkmcnt(0)
	global_store_dwordx4 v[118:119], v[114:117], off nt
	ds_read_b128 v[114:117], v211 offset:1152
	v_lshl_add_u64 v[118:119], s[76:77], 0, v[196:197]
	v_lshl_add_u64 v[118:119], v[118:119], 0, s[48:49]
	v_lshl_add_u64 v[118:119], v[118:119], 0, v[0:1]
	s_waitcnt lgkmcnt(0)
	global_store_dwordx4 v[118:119], v[114:117], off nt
	s_nop 1
	v_mov_b32_e32 v114, v120
	s_nop 1
	v_permlane16_swap_b32_e32 v120, v114
	v_add_f32_e32 v114, v120, v114
	v_mov_b32_e32 v115, v114
	s_nop 1
	v_permlane32_swap_b32_e32 v114, v115
	s_and_saveexec_b64 s[52:53], s[34:35]
	s_cbranch_execz .LBB0_758
	s_add_u32 s50, s82, s46
	v_or_b32_e32 v116, s44, v174
	s_addc_u32 s51, s83, s47
	v_ashrrev_i32_e32 v117, 31, v116
	v_lshl_add_u64 v[116:117], v[116:117], 2, s[50:51]
	v_add_f32_e32 v114, v114, v115
	global_store_dword v[116:117], v114, off

; #define PG8_STAGE(bufoff, gbase, voff) do { _Pragma("unroll") for (int _i = 0; _i < 2; ++_i) \
;         __builtin_amdgcn_global_load_lds((const unsigned*)((const char*)(gbase) + (voff)[_i]), (PG8_LAS unsigned*)(lds + (bufoff) + ldsw + _i * 8192), 16, 0, 0); } while (0)
; #define PG8_LDA(dst, b, h) do { _Pragma("unroll") for (int m = 0; m < 4; ++m) _Pragma("unroll") for (int k = 0; k < 2; ++k) dst[m][k] = *(const PG8_LAS bf16x8*)(lds + PG8_SA(b, h) + aoff + m * 2048 + k * 1024); } while (0)
; #define PG8_LDB(dst, b, h) do { _Pragma("unroll") for (int n = 0; n < 2; ++n) _Pragma("unroll") for (int k = 0; k < 2; ++k) dst[n][k] = *(const PG8_LAS bf16x8*)(lds + PG8_SB(b, h) + boff + n * 2048 + k * 1024); } while (0)
; #define PG8_MMA(ai, bj, At, Bt) do { __builtin_amdgcn_s_setprio(1); _Pragma("unroll") for (int m = 0; m < 4; ++m) _Pragma("unroll") for (int n = 0; n < 2; ++n) _Pragma("unroll") for (int k = 0; k < 2; ++k) \
;         acc[ai][bj][m][n] = __builtin_amdgcn_mfma_f32_16x16x32_bf16(Bt[n][k], At[m][k], acc[ai][bj][m][n], 0, 0, 0); __builtin_amdgcn_s_setprio(0); } while (0)
; #define PG8_WAIT_V(n) asm volatile("s_waitcnt vmcnt(" #n ")" ::: "memory")
; #define PG8_WAIT_L(n) asm volatile("s_waitcnt lgkmcnt(" #n ")" ::: "memory")
; #define PG8_BAR __builtin_amdgcn_s_barrier()
; #define PG8_SCHED __builtin_amdgcn_sched_barrier(0)
; template <class Epi, class Sched, bool ALIGN_EPI = false, bool SP2 = false>
; __device__ __forceinline__ void gemm_phase(PG8_LAS unsigned char* lds, const Gemm g, const Sched& S, const Epi& E, const int wave_s) {
;     ...
;             PG8_LDB(B0, 0, 0); PG8_LDB(B1, 0, 1); PG8_SCHED; PG8_LDA(At, 0, 0); PG8_STAGE(PG8_SA(1, 1), a1 + hstep, voffA);
;             PG8_WAIT_V(8); PG8_WAIT_L(0); PG8_BAR; PG8_MMA(0, 0, At, B0); PG8_MMA(0, 1, At, B1); PG8_BAR; PG8_SCHED;
;             PG8_LDA(At, 0, 1); PG8_STAGE(PG8_SB(0, 0), b2, voffB); PG8_STAGE(PG8_SB(0, 1), b2 + bhstep, voffB); PG8_STAGE(PG8_SA(0, 0), a2, voffA);
;             PG8_WAIT_V(8); PG8_WAIT_L(0); PG8_BAR; PG8_MMA(1, 0, At, B0); PG8_MMA(1, 1, At, B1); PG8_BAR; PG8_SCHED;
.LBB0_843:
	s_add_u32 s44, s42, 0xfffc0080
	s_addc_u32 s45, s43, -1
	s_add_i32 s52, 0, 0x10000
	s_cmp_eq_u32 s51, 12
	s_cselect_b32 s47, s17, s45
	s_cselect_b32 s46, s29, s44
	v_add_u32_e32 v148, s52, v151
	s_cselect_b32 s45, s23, s50
	s_cselect_b32 s44, s48, s49
	s_add_i32 s54, 0, 0x14000
	ds_read_b128 v[144:147], v148
	ds_read_b128 v[160:163], v148 offset:1024
	ds_read_b128 v[164:167], v148 offset:2048
	s_nop 0
	ds_read_b128 v[168:171], v148 offset:3072
	v_add_u32_e32 v148, s54, v151
	ds_read_b128 v[172:175], v148
	ds_read_b128 v[176:179], v148 offset:1024
	ds_read_b128 v[180:183], v148 offset:2048
	ds_read_b128 v[184:187], v148 offset:3072
	v_lshl_add_u64 v[148:149], s[42:43], 0, v[140:141]
	s_add_i32 m0, s7, 0xc000
	ds_read_b128 v[188:191], v155
	ds_read_b128 v[192:195], v155 offset:1024
	ds_read_b128 v[196:199], v155 offset:2048
	ds_read_b128 v[204:207], v155 offset:3072
	ds_read_b128 v[208:211], v155 offset:4096
	ds_read_b128 v[212:215], v155 offset:5120
	ds_read_b128 v[216:219], v155 offset:6144
	ds_read_b128 v[220:223], v155 offset:7168
	global_load_lds_dwordx4 v[148:149], off
	v_lshl_add_u64 v[148:149], s[42:43], 0, v[142:143]
	s_add_i32 m0, s7, 0xe000
	s_nop 0
	global_load_lds_dwordx4 v[148:149], off
	s_waitcnt vmcnt(8)
	s_waitcnt lgkmcnt(0)
	s_barrier
	s_setprio 1
	s_waitcnt lgkmcnt(0)
	v_mfma_f32_16x16x32_bf16 v[126:129], v[144:147], v[188:191], v[126:129]
	v_mfma_f32_16x16x32_bf16 v[126:129], v[160:163], v[192:195], v[126:129]
	v_mfma_f32_16x16x32_bf16 v[122:125], v[164:167], v[188:191], v[122:125]
	v_mfma_f32_16x16x32_bf16 v[122:125], v[168:171], v[192:195], v[122:125]
	v_mfma_f32_16x16x32_bf16 v[110:113], v[144:147], v[196:199], v[110:113]
	v_mfma_f32_16x16x32_bf16 v[110:113], v[160:163], v[204:207], v[110:113]
	v_mfma_f32_16x16x32_bf16 v[106:109], v[164:167], v[196:199], v[106:109]
	v_mfma_f32_16x16x32_bf16 v[106:109], v[168:171], v[204:207], v[106:109]
	v_mfma_f32_16x16x32_bf16 v[94:97], v[144:147], v[208:211], v[94:97]
	v_mfma_f32_16x16x32_bf16 v[94:97], v[160:163], v[212:215], v[94:97]
	v_mfma_f32_16x16x32_bf16 v[90:93], v[164:167], v[208:211], v[90:93]
	v_mfma_f32_16x16x32_bf16 v[90:93], v[168:171], v[212:215], v[90:93]
	v_mfma_f32_16x16x32_bf16 v[78:81], v[144:147], v[216:219], v[78:81]
	v_mfma_f32_16x16x32_bf16 v[78:81], v[160:163], v[220:223], v[78:81]
	v_mfma_f32_16x16x32_bf16 v[74:77], v[164:167], v[216:219], v[74:77]
	v_mfma_f32_16x16x32_bf16 v[74:77], v[168:171], v[220:223], v[74:77]
	s_setprio 0
	s_setprio 1
	v_mfma_f32_16x16x32_bf16 v[118:121], v[172:175], v[188:191], v[118:121]
	v_mfma_f32_16x16x32_bf16 v[118:121], v[176:179], v[192:195], v[118:121]
	v_mfma_f32_16x16x32_bf16 v[114:117], v[180:183], v[188:191], v[114:117]
	v_mfma_f32_16x16x32_bf16 v[114:117], v[184:187], v[192:195], v[114:117]
	v_mfma_f32_16x16x32_bf16 v[102:105], v[172:175], v[196:199], v[102:105]
	v_mfma_f32_16x16x32_bf16 v[102:105], v[176:179], v[204:207], v[102:105]
	v_mfma_f32_16x16x32_bf16 v[98:101], v[180:183], v[196:199], v[98:101]
	v_mfma_f32_16x16x32_bf16 v[98:101], v[184:187], v[204:207], v[98:101]
	v_mfma_f32_16x16x32_bf16 v[86:89], v[172:175], v[208:211], v[86:89]
	v_mfma_f32_16x16x32_bf16 v[86:89], v[176:179], v[212:215], v[86:89]
	v_mfma_f32_16x16x32_bf16 v[82:85], v[180:183], v[208:211], v[82:85]
	v_mfma_f32_16x16x32_bf16 v[82:85], v[184:187], v[212:215], v[82:85]
	v_mfma_f32_16x16x32_bf16 v[70:73], v[172:175], v[216:219], v[70:73]
	v_mfma_f32_16x16x32_bf16 v[70:73], v[176:179], v[220:223], v[70:73]
	v_mfma_f32_16x16x32_bf16 v[66:69], v[180:183], v[216:219], v[66:69]
	v_mfma_f32_16x16x32_bf16 v[66:69], v[184:187], v[220:223], v[66:69]
	s_setprio 0
	s_barrier
	s_add_i32 s52, s52, s6
	v_lshl_add_u64 v[148:149], s[44:45], 0, v[134:135]
	s_mov_b32 m0, s52
	ds_read_b128 v[188:191], v155 offset:16384
	ds_read_b128 v[192:195], v155 offset:17408
	ds_read_b128 v[196:199], v155 offset:18432
	ds_read_b128 v[204:207], v155 offset:19456
	ds_read_b128 v[208:211], v155 offset:20480
	ds_read_b128 v[212:215], v155 offset:21504
	ds_read_b128 v[216:219], v155 offset:22528
	ds_read_b128 v[220:223], v155 offset:23552
	global_load_lds_dwordx4 v[148:149], off
	s_add_i32 m0, s52, 0x2000
	s_add_u32 s52, s44, 0x10000
	v_lshl_add_u64 v[200:201], s[44:45], 0, v[138:139]
	s_addc_u32 s53, s45, 0
	s_add_i32 s54, s54, s6
	global_load_lds_dwordx4 v[200:201], off
	v_lshl_add_u64 v[224:225], s[52:53], 0, v[134:135]
	s_mov_b32 m0, s54
	v_lshl_add_u64 v[226:227], s[46:47], 0, v[136:137]
	global_load_lds_dwordx4 v[224:225], off
	v_lshl_add_u64 v[224:225], s[52:53], 0, v[138:139]
	s_add_i32 m0, s54, 0x2000
	s_nop 0
	global_load_lds_dwordx4 v[224:225], off
	v_lshl_add_u64 v[224:225], s[46:47], 0, v[132:133]
	s_mov_b32 m0, s7
	s_nop 0
	global_load_lds_dwordx4 v[224:225], off
	s_mov_b32 m0, s8
	s_nop 0
	global_load_lds_dwordx4 v[226:227], off
	s_waitcnt vmcnt(8)
	s_waitcnt lgkmcnt(0)
	s_barrier
; #define PG8_STAGE(bufoff, gbase, voff) do { _Pragma("unroll") for (int _i = 0; _i < 2; ++_i) \
;         __builtin_amdgcn_global_load_lds((const unsigned*)((const char*)(gbase) + (voff)[_i]), (PG8_LAS unsigned*)(lds + (bufoff) + ldsw + _i * 8192), 16, 0, 0); } while (0)
; #define PG8_LDA(dst, b, h) do { _Pragma("unroll") for (int m = 0; m < 4; ++m) _Pragma("unroll") for (int k = 0; k < 2; ++k) dst[m][k] = *(const PG8_LAS bf16x8*)(lds + PG8_SA(b, h) + aoff + m * 2048 + k * 1024); } while (0)
; #define PG8_LDB(dst, b, h) do { _Pragma("unroll") for (int n = 0; n < 2; ++n) _Pragma("unroll") for (int k = 0; k < 2; ++k) dst[n][k] = *(const PG8_LAS bf16x8*)(lds + PG8_SB(b, h) + boff + n * 2048 + k * 1024); } while (0)
; #define PG8_MMA(ai, bj, At, Bt) do { __builtin_amdgcn_s_setprio(1); _Pragma("unroll") for (int m = 0; m < 4; ++m) _Pragma("unroll") for (int n = 0; n < 2; ++n) _Pragma("unroll") for (int k = 0; k < 2; ++k) \
;         acc[ai][bj][m][n] = __builtin_amdgcn_mfma_f32_16x16x32_bf16(Bt[n][k], At[m][k], acc[ai][bj][m][n], 0, 0, 0); __builtin_amdgcn_s_setprio(0); } while (0)
; #define PG8_WAIT_V(n) asm volatile("s_waitcnt vmcnt(" #n ")" ::: "memory")
; #define PG8_WAIT_L(n) asm volatile("s_waitcnt lgkmcnt(" #n ")" ::: "memory")
; #define PG8_BAR __builtin_amdgcn_s_barrier()
; #define PG8_SCHED __builtin_amdgcn_sched_barrier(0)
; template <class Epi, class Sched, bool ALIGN_EPI = false, bool SP2 = false>
; __device__ __forceinline__ void gemm_phase(PG8_LAS unsigned char* lds, const Gemm g, const Sched& S, const Epi& E, const int wave_s) {
;     ...
;             PG8_WAIT_V(8); PG8_WAIT_L(0); PG8_BAR; PG8_MMA(1, 0, At, B0); PG8_MMA(1, 1, At, B1); PG8_BAR; PG8_SCHED;
;             PG8_LDB(B0, 1, 0); PG8_LDB(B1, 1, 1); PG8_SCHED; PG8_LDA(At, 1, 0); PG8_STAGE(PG8_SA(0, 1), a2 + hstep, voffA);
;             PG8_WAIT_V(8); PG8_WAIT_L(0); PG8_BAR; PG8_MMA(0, 0, At, B0); PG8_MMA(0, 1, At, B1); PG8_BAR; PG8_SCHED;
	s_setprio 1
	s_waitcnt lgkmcnt(0)
	v_mfma_f32_16x16x32_bf16 v[62:65], v[144:147], v[188:191], v[62:65]
	v_mfma_f32_16x16x32_bf16 v[62:65], v[160:163], v[192:195], v[62:65]
	v_mfma_f32_16x16x32_bf16 v[58:61], v[164:167], v[188:191], v[58:61]
	v_mfma_f32_16x16x32_bf16 v[58:61], v[168:171], v[192:195], v[58:61]
	v_mfma_f32_16x16x32_bf16 v[46:49], v[144:147], v[196:199], v[46:49]
	v_mfma_f32_16x16x32_bf16 v[46:49], v[160:163], v[204:207], v[46:49]
	v_mfma_f32_16x16x32_bf16 v[42:45], v[164:167], v[196:199], v[42:45]
	v_mfma_f32_16x16x32_bf16 v[42:45], v[168:171], v[204:207], v[42:45]
	v_mfma_f32_16x16x32_bf16 v[30:33], v[144:147], v[208:211], v[30:33]
	v_mfma_f32_16x16x32_bf16 v[30:33], v[160:163], v[212:215], v[30:33]
	v_mfma_f32_16x16x32_bf16 v[26:29], v[164:167], v[208:211], v[26:29]
	v_mfma_f32_16x16x32_bf16 v[26:29], v[168:171], v[212:215], v[26:29]
	v_mfma_f32_16x16x32_bf16 v[14:17], v[144:147], v[216:219], v[14:17]
	v_mfma_f32_16x16x32_bf16 v[14:17], v[160:163], v[220:223], v[14:17]
	v_mfma_f32_16x16x32_bf16 v[10:13], v[164:167], v[216:219], v[10:13]
	v_mfma_f32_16x16x32_bf16 v[10:13], v[168:171], v[220:223], v[10:13]
	s_setprio 0
	s_setprio 1
	v_mfma_f32_16x16x32_bf16 v[54:57], v[172:175], v[188:191], v[54:57]
	v_mfma_f32_16x16x32_bf16 v[54:57], v[176:179], v[192:195], v[54:57]
	v_mfma_f32_16x16x32_bf16 v[50:53], v[180:183], v[188:191], v[50:53]
	v_mfma_f32_16x16x32_bf16 v[50:53], v[184:187], v[192:195], v[50:53]
	v_mfma_f32_16x16x32_bf16 v[38:41], v[172:175], v[196:199], v[38:41]
	v_mfma_f32_16x16x32_bf16 v[38:41], v[176:179], v[204:207], v[38:41]
	v_mfma_f32_16x16x32_bf16 v[34:37], v[180:183], v[196:199], v[34:37]
	v_mfma_f32_16x16x32_bf16 v[34:37], v[184:187], v[204:207], v[34:37]
	v_mfma_f32_16x16x32_bf16 v[22:25], v[172:175], v[208:211], v[22:25]
	v_mfma_f32_16x16x32_bf16 v[22:25], v[176:179], v[212:215], v[22:25]
	v_mfma_f32_16x16x32_bf16 v[18:21], v[180:183], v[208:211], v[18:21]
	v_mfma_f32_16x16x32_bf16 v[18:21], v[184:187], v[212:215], v[18:21]
	v_mfma_f32_16x16x32_bf16 v[6:9], v[172:175], v[216:219], v[6:9]
	v_mfma_f32_16x16x32_bf16 v[6:9], v[176:179], v[220:223], v[6:9]
	v_mfma_f32_16x16x32_bf16 v[2:5], v[180:183], v[216:219], v[2:5]
	v_mfma_f32_16x16x32_bf16 v[2:5], v[184:187], v[220:223], v[2:5]
	s_setprio 0
	s_barrier
	s_add_i32 s52, 0, 0x18000
	v_add_u32_e32 v159, s52, v151
	s_add_i32 s53, 0, 0x1c000
	ds_read_b128 v[144:147], v159
	ds_read_b128 v[160:163], v159 offset:1024
	ds_read_b128 v[164:167], v159 offset:2048
	ds_read_b128 v[168:171], v159 offset:3072
	v_add_u32_e32 v159, s53, v151
	ds_read_b128 v[172:175], v159
	ds_read_b128 v[176:179], v159 offset:1024
	ds_read_b128 v[180:183], v159 offset:2048
	ds_read_b128 v[184:187], v159 offset:3072
	s_add_u32 s46, s46, 0x40000
	s_addc_u32 s47, s47, 0
	s_mov_b32 m0, s9
	v_lshl_add_u64 v[228:229], s[46:47], 0, v[132:133]
	ds_read_b128 v[188:191], v155 offset:32768
	ds_read_b128 v[192:195], v155 offset:33792
	ds_read_b128 v[196:199], v155 offset:34816
	ds_read_b128 v[204:207], v155 offset:35840
	ds_read_b128 v[208:211], v155 offset:36864
	ds_read_b128 v[212:215], v155 offset:37888
	ds_read_b128 v[216:219], v155 offset:38912
	ds_read_b128 v[220:223], v155 offset:39936
	global_load_lds_dwordx4 v[228:229], off
	v_lshl_add_u64 v[228:229], s[46:47], 0, v[136:137]
	s_mov_b32 m0, s10
	s_nop 0
	global_load_lds_dwordx4 v[228:229], off
	s_waitcnt vmcnt(8)
	s_waitcnt lgkmcnt(0)
	s_barrier
	s_setprio 1
	s_waitcnt lgkmcnt(0)
	v_mfma_f32_16x16x32_bf16 v[126:129], v[144:147], v[188:191], v[126:129]
	v_mfma_f32_16x16x32_bf16 v[126:129], v[160:163], v[192:195], v[126:129]
	v_mfma_f32_16x16x32_bf16 v[122:125], v[164:167], v[188:191], v[122:125]
	v_mfma_f32_16x16x32_bf16 v[122:125], v[168:171], v[192:195], v[122:125]
	v_mfma_f32_16x16x32_bf16 v[110:113], v[144:147], v[196:199], v[110:113]
	v_mfma_f32_16x16x32_bf16 v[110:113], v[160:163], v[204:207], v[110:113]
	v_mfma_f32_16x16x32_bf16 v[106:109], v[164:167], v[196:199], v[106:109]
	v_mfma_f32_16x16x32_bf16 v[106:109], v[168:171], v[204:207], v[106:109]
	v_mfma_f32_16x16x32_bf16 v[94:97], v[144:147], v[208:211], v[94:97]
	v_mfma_f32_16x16x32_bf16 v[94:97], v[160:163], v[212:215], v[94:97]
	v_mfma_f32_16x16x32_bf16 v[90:93], v[164:167], v[208:211], v[90:93]
	v_mfma_f32_16x16x32_bf16 v[90:93], v[168:171], v[212:215], v[90:93]
	v_mfma_f32_16x16x32_bf16 v[78:81], v[144:147], v[216:219], v[78:81]
	v_mfma_f32_16x16x32_bf16 v[78:81], v[160:163], v[220:223], v[78:81]
	v_mfma_f32_16x16x32_bf16 v[74:77], v[164:167], v[216:219], v[74:77]
	v_mfma_f32_16x16x32_bf16 v[74:77], v[168:171], v[220:223], v[74:77]
	s_setprio 0
	s_setprio 1
	v_mfma_f32_16x16x32_bf16 v[118:121], v[172:175], v[188:191], v[118:121]
	v_mfma_f32_16x16x32_bf16 v[118:121], v[176:179], v[192:195], v[118:121]
	v_mfma_f32_16x16x32_bf16 v[114:117], v[180:183], v[188:191], v[114:117]
	v_mfma_f32_16x16x32_bf16 v[114:117], v[184:187], v[192:195], v[114:117]
	v_mfma_f32_16x16x32_bf16 v[102:105], v[172:175], v[196:199], v[102:105]
	v_mfma_f32_16x16x32_bf16 v[102:105], v[176:179], v[204:207], v[102:105]
	v_mfma_f32_16x16x32_bf16 v[98:101], v[180:183], v[196:199], v[98:101]
	v_mfma_f32_16x16x32_bf16 v[98:101], v[184:187], v[204:207], v[98:101]
	v_mfma_f32_16x16x32_bf16 v[86:89], v[172:175], v[208:211], v[86:89]
	v_mfma_f32_16x16x32_bf16 v[86:89], v[176:179], v[212:215], v[86:89]
	v_mfma_f32_16x16x32_bf16 v[82:85], v[180:183], v[208:211], v[82:85]
	v_mfma_f32_16x16x32_bf16 v[82:85], v[184:187], v[212:215], v[82:85]
	v_mfma_f32_16x16x32_bf16 v[70:73], v[172:175], v[216:219], v[70:73]
	v_mfma_f32_16x16x32_bf16 v[70:73], v[176:179], v[220:223], v[70:73]
	v_mfma_f32_16x16x32_bf16 v[66:69], v[180:183], v[216:219], v[66:69]
	v_mfma_f32_16x16x32_bf16 v[66:69], v[184:187], v[220:223], v[66:69]
	s_setprio 0
	s_barrier
; #define PG8_STAGE(bufoff, gbase, voff) do { _Pragma("unroll") for (int _i = 0; _i < 2; ++_i) \
;         __builtin_amdgcn_global_load_lds((const unsigned*)((const char*)(gbase) + (voff)[_i]), (PG8_LAS unsigned*)(lds + (bufoff) + ldsw + _i * 8192), 16, 0, 0); } while (0)
; #define PG8_LDA(dst, b, h) do { _Pragma("unroll") for (int m = 0; m < 4; ++m) _Pragma("unroll") for (int k = 0; k < 2; ++k) dst[m][k] = *(const PG8_LAS bf16x8*)(lds + PG8_SA(b, h) + aoff + m * 2048 + k * 1024); } while (0)
; #define PG8_MMA(ai, bj, At, Bt) do { __builtin_amdgcn_s_setprio(1); _Pragma("unroll") for (int m = 0; m < 4; ++m) _Pragma("unroll") for (int n = 0; n < 2; ++n) _Pragma("unroll") for (int k = 0; k < 2; ++k) \
;         acc[ai][bj][m][n] = __builtin_amdgcn_mfma_f32_16x16x32_bf16(Bt[n][k], At[m][k], acc[ai][bj][m][n], 0, 0, 0); __builtin_amdgcn_s_setprio(0); } while (0)
; #define PG8_WAIT_V(n) asm volatile("s_waitcnt vmcnt(" #n ")" ::: "memory")
; #define PG8_WAIT_L(n) asm volatile("s_waitcnt lgkmcnt(" #n ")" ::: "memory")
; #define PG8_BAR __builtin_amdgcn_s_barrier()
; #define PG8_SCHED __builtin_amdgcn_sched_barrier(0)
; template <class Epi, class Sched, bool ALIGN_EPI = false, bool SP2 = false>
; __device__ __forceinline__ void gemm_phase(PG8_LAS unsigned char* lds, const Gemm g, const Sched& S, const Epi& E, const int wave_s) {
;     ...
;             PG8_LDA(At, 1, 1); PG8_STAGE(PG8_SB(1, 0), b3, voffB); PG8_STAGE(PG8_SB(1, 1), b3 + bhstep, voffB); PG8_STAGE(PG8_SA(1, 0), a3, voffA);
;             PG8_WAIT_V(8); PG8_WAIT_L(0); PG8_BAR; PG8_MMA(1, 0, At, B0); PG8_MMA(1, 1, At, B1); PG8_BAR; PG8_SCHED;
;     ...
;         if constexpr (ALIGN_EPI) { if (wr == 0) PG8_BAR; }
	s_add_i32 s46, s52, s6
	v_lshl_add_u64 v[148:149], v[148:149], 0, s[24:25]
	s_mov_b32 m0, s46
	ds_read_b128 v[188:191], v155 offset:49152
	ds_read_b128 v[192:195], v155 offset:50176
	ds_read_b128 v[196:199], v155 offset:51200
	ds_read_b128 v[204:207], v155 offset:52224
	ds_read_b128 v[208:211], v155 offset:53248
	ds_read_b128 v[212:215], v155 offset:54272
	ds_read_b128 v[216:219], v155 offset:55296
	ds_read_b128 v[220:223], v155 offset:56320
	global_load_lds_dwordx4 v[148:149], off
	s_add_i32 m0, s46, 0x2000
	s_add_u32 s44, s44, 0x10080
	v_lshl_add_u64 v[148:149], v[200:201], 0, s[24:25]
	s_addc_u32 s45, s45, 0
	s_add_i32 s46, s53, s6
	global_load_lds_dwordx4 v[148:149], off
	v_lshl_add_u64 v[148:149], s[44:45], 0, v[134:135]
	s_mov_b32 m0, s46
	s_nop 0
	global_load_lds_dwordx4 v[148:149], off
	v_lshl_add_u64 v[148:149], s[44:45], 0, v[138:139]
	s_add_i32 m0, s46, 0x2000
	s_nop 0
	global_load_lds_dwordx4 v[148:149], off
	v_lshl_add_u64 v[148:149], v[224:225], 0, s[24:25]
	s_mov_b32 m0, s11
	s_nop 0
	global_load_lds_dwordx4 v[148:149], off
	v_lshl_add_u64 v[148:149], v[226:227], 0, s[24:25]
	s_mov_b32 m0, s12
	s_nop 0
	global_load_lds_dwordx4 v[148:149], off
	s_waitcnt vmcnt(8)
	s_waitcnt lgkmcnt(0)
	s_barrier
	s_setprio 1
	s_waitcnt lgkmcnt(0)
	v_mfma_f32_16x16x32_bf16 v[62:65], v[144:147], v[188:191], v[62:65]
	v_mfma_f32_16x16x32_bf16 v[62:65], v[160:163], v[192:195], v[62:65]
	v_mfma_f32_16x16x32_bf16 v[58:61], v[164:167], v[188:191], v[58:61]
	v_mfma_f32_16x16x32_bf16 v[58:61], v[168:171], v[192:195], v[58:61]
	v_mfma_f32_16x16x32_bf16 v[46:49], v[144:147], v[196:199], v[46:49]
	v_mfma_f32_16x16x32_bf16 v[46:49], v[160:163], v[204:207], v[46:49]
	v_mfma_f32_16x16x32_bf16 v[42:45], v[164:167], v[196:199], v[42:45]
	v_mfma_f32_16x16x32_bf16 v[42:45], v[168:171], v[204:207], v[42:45]
	v_mfma_f32_16x16x32_bf16 v[30:33], v[144:147], v[208:211], v[30:33]
	v_mfma_f32_16x16x32_bf16 v[30:33], v[160:163], v[212:215], v[30:33]
	v_mfma_f32_16x16x32_bf16 v[26:29], v[164:167], v[208:211], v[26:29]
	v_mfma_f32_16x16x32_bf16 v[26:29], v[168:171], v[212:215], v[26:29]
	v_mfma_f32_16x16x32_bf16 v[14:17], v[144:147], v[216:219], v[14:17]
	v_mfma_f32_16x16x32_bf16 v[14:17], v[160:163], v[220:223], v[14:17]
	v_mfma_f32_16x16x32_bf16 v[10:13], v[164:167], v[216:219], v[10:13]
	v_mfma_f32_16x16x32_bf16 v[10:13], v[168:171], v[220:223], v[10:13]
	s_setprio 0
	s_setprio 1
	v_mfma_f32_16x16x32_bf16 v[54:57], v[172:175], v[188:191], v[54:57]
	v_mfma_f32_16x16x32_bf16 v[54:57], v[176:179], v[192:195], v[54:57]
	v_mfma_f32_16x16x32_bf16 v[50:53], v[180:183], v[188:191], v[50:53]
	v_mfma_f32_16x16x32_bf16 v[50:53], v[184:187], v[192:195], v[50:53]
	v_mfma_f32_16x16x32_bf16 v[38:41], v[172:175], v[196:199], v[38:41]
	v_mfma_f32_16x16x32_bf16 v[38:41], v[176:179], v[204:207], v[38:41]
	v_mfma_f32_16x16x32_bf16 v[34:37], v[180:183], v[196:199], v[34:37]
	v_mfma_f32_16x16x32_bf16 v[34:37], v[184:187], v[204:207], v[34:37]
	v_mfma_f32_16x16x32_bf16 v[22:25], v[172:175], v[208:211], v[22:25]
	v_mfma_f32_16x16x32_bf16 v[22:25], v[176:179], v[212:215], v[22:25]
	v_mfma_f32_16x16x32_bf16 v[18:21], v[180:183], v[208:211], v[18:21]
	v_mfma_f32_16x16x32_bf16 v[18:21], v[184:187], v[212:215], v[18:21]
	v_mfma_f32_16x16x32_bf16 v[6:9], v[172:175], v[216:219], v[6:9]
	v_mfma_f32_16x16x32_bf16 v[6:9], v[176:179], v[220:223], v[6:9]
	v_mfma_f32_16x16x32_bf16 v[2:5], v[180:183], v[216:219], v[2:5]
	v_mfma_f32_16x16x32_bf16 v[2:5], v[184:187], v[220:223], v[2:5]
	s_setprio 0
	s_barrier
	s_add_i32 s51, s51, 2
	s_add_u32 s42, s42, 0x100
	s_addc_u32 s43, s43, 0
	s_add_u32 s49, s49, 0x100
	s_addc_u32 s50, s50, 0
	s_cmp_gt_u32 s51, 13
	s_cbranch_scc0 .LBB0_843

; #define PG8_LAS __attribute__((address_space(3)))
; __device__ __forceinline__ unsigned cvt_pk_bf16(float lo, float hi) { unsigned r; asm volatile("v_cvt_pk_bf16_f32 %0, %1, %2" : "=v"(r) : "v"(lo), "v"(hi)); return r; }
; #define PG8_BAR __builtin_amdgcn_s_barrier()
;     __device__ __forceinline__ void operator()(const f32x4 (&acc)[2][2][4][2], const Unit& u, int wr, int wc, int fr, int fq, PG8_LAS float* stash, int par, PG8_LAS unsigned char* stg, const Unit& un) const {
;     ...
;             for (int m = 0; m < 4; ++m) rsa[ai][m] = stash[par * 256 + ai * HALF + wr * 64 + m * 16 + fr];
; #pragma unroll
;         for (int ai = 0; ai < 2; ++ai)
; #pragma unroll
;             for (int m = 0; m < 4; ++m) {
;                 const int row = u.pm * BM + ai * HALF + wr * 64 + m * 16 + fr;
;                 const float rs = rsa[ai][m];
;                 PG8_LAS unsigned char* st = stg + fr * 144 + fq * 16;
; #pragma unroll
;                 for (int bj = 0; bj < 2; ++bj) {
;                     float v[8];
; #pragma unroll
;                     for (int i = 0; i < 4; ++i) { v[i] = acc[ai][bj][m][0][i] * rs; v[4 + i] = acc[ai][bj][m][1][i] * rs; }
; #pragma unroll
;                     for (int i = 0; i < 8; ++i) { const float r = fmaxf(v[i], 0.f); v[i] = r * r; }
;                     u32x4 w; w.x = cvt_pk_bf16(v[0], v[1]); w.y = cvt_pk_bf16(v[2], v[3]); w.z = cvt_pk_bf16(v[4], v[5]); w.w = cvt_pk_bf16(v[6], v[7]);
;                     *(PG8_LAS u32x4*)(st + bj * 64) = w;
;                 }
; #pragma unroll
;                 for (int i = 0; i < 2; ++i) { const int c = fq * 16 + fr + 64 * i, rr = c >> 3, pc = c & 7;
;                     const u32x4 w = *(const PG8_LAS u32x4*)(stg + rr * 144 + pc * 16);
;                     __builtin_nontemporal_store(w, (u32x4*)(uo + (size_t)(row - fr + rr) * 4096 + u.pn * BM + wc * 64 + pc * 8)); }
; template <class Epi, class Sched, bool ALIGN_EPI = false, bool SP2 = false>
; __device__ __forceinline__ void gemm_phase(PG8_LAS unsigned char* lds, const Gemm g, const Sched& S, const Epi& E, const int wave_s) {
;     ...
;         if constexpr (ALIGN_EPI) { if (wr == 0) PG8_BAR; }
.LBB0_848:
	v_lshl_add_u32 v144, v157, 10, v152
	ds_read2_b32 v[160:161], v144 offset1:16
	ds_read2_b32 v[148:149], v144 offset0:32 offset1:48
	ds_read2_b32 v[146:147], v144 offset0:128 offset1:144
	ds_read2_b32 v[144:145], v144 offset0:160 offset1:176
	s_lshl_b32 s16, s14, 8
	s_add_i32 s16, s16, s1
	s_lshl_b32 s100, s16, 13
	s_add_u32 s98, s78, s100
	s_addc_u32 s99, s79, 0
	s_lshl_b32 s100, s15, 9
	s_add_u32 s98, s98, s100
	s_addc_u32 s99, s99, 0
	s_add_u32 s98, s98, s74
	s_addc_u32 s99, s99, s75
	v_lshl_add_u32 v200, v153, 13, v0
	v_add_u32_e32 v201, 0x10000, v200
	s_waitcnt lgkmcnt(0)
	v_pk_mul_f32 v[126:127], v[126:127], v[160:161] op_sel_hi:[1,0]
	v_pk_mul_f32 v[128:129], v[128:129], v[160:161] op_sel_hi:[1,0]
	v_pk_mul_f32 v[122:123], v[122:123], v[160:161] op_sel_hi:[1,0]
	v_pk_mul_f32 v[124:125], v[124:125], v[160:161] op_sel_hi:[1,0]
	v_max_f32_e32 v126, 0, v126
	v_max_f32_e32 v127, 0, v127
	v_max_f32_e32 v128, 0, v128
	v_max_f32_e32 v129, 0, v129
	v_max_f32_e32 v122, 0, v122
	v_max_f32_e32 v123, 0, v123
	v_max_f32_e32 v124, 0, v124
	v_max_f32_e32 v125, 0, v125
	v_pk_mul_f32 v[126:127], v[126:127], v[126:127]
	v_pk_mul_f32 v[128:129], v[128:129], v[128:129]
	v_pk_mul_f32 v[122:123], v[122:123], v[122:123]
	v_pk_mul_f32 v[124:125], v[124:125], v[124:125]
	v_cvt_pk_bf16_f32 v126, v126, v127
	v_cvt_pk_bf16_f32 v127, v128, v129
	v_cvt_pk_bf16_f32 v128, v122, v123
	v_cvt_pk_bf16_f32 v129, v124, v125
	v_pk_mul_f32 v[118:119], v[118:119], v[160:161] op_sel_hi:[1,0]
	v_pk_mul_f32 v[120:121], v[120:121], v[160:161] op_sel_hi:[1,0]
	v_pk_mul_f32 v[114:115], v[114:115], v[160:161] op_sel_hi:[1,0]
	v_pk_mul_f32 v[116:117], v[116:117], v[160:161] op_sel_hi:[1,0]
	v_max_f32_e32 v118, 0, v118
	v_max_f32_e32 v119, 0, v119
	v_max_f32_e32 v120, 0, v120
	v_max_f32_e32 v121, 0, v121
	v_max_f32_e32 v114, 0, v114
	v_max_f32_e32 v115, 0, v115
	v_max_f32_e32 v116, 0, v116
	v_max_f32_e32 v117, 0, v117
	v_pk_mul_f32 v[118:119], v[118:119], v[118:119]
	v_pk_mul_f32 v[120:121], v[120:121], v[120:121]
	v_pk_mul_f32 v[114:115], v[114:115], v[114:115]
	v_pk_mul_f32 v[116:117], v[116:117], v[116:117]
	v_cvt_pk_bf16_f32 v118, v118, v119
	v_cvt_pk_bf16_f32 v119, v120, v121
	v_cvt_pk_bf16_f32 v120, v114, v115
	v_cvt_pk_bf16_f32 v121, v116, v117
	ds_write_b128 v156, v[126:129]
	ds_write_b128 v156, v[118:121] offset:64
	ds_read_b128 v[204:207], v158
	ds_read_b128 v[208:211], v158 offset:1152
	v_pk_mul_f32 v[110:111], v[110:111], v[160:161] op_sel:[0,1]
	v_pk_mul_f32 v[112:113], v[112:113], v[160:161] op_sel:[0,1]
	v_pk_mul_f32 v[106:107], v[106:107], v[160:161] op_sel:[0,1]
	v_pk_mul_f32 v[108:109], v[108:109], v[160:161] op_sel:[0,1]
	v_max_f32_e32 v110, 0, v110
	v_max_f32_e32 v111, 0, v111
	v_max_f32_e32 v112, 0, v112
	v_max_f32_e32 v113, 0, v113
	v_max_f32_e32 v106, 0, v106
	v_max_f32_e32 v107, 0, v107
	v_max_f32_e32 v108, 0, v108
	v_max_f32_e32 v109, 0, v109
	v_pk_mul_f32 v[110:111], v[110:111], v[110:111]
	v_pk_mul_f32 v[112:113], v[112:113], v[112:113]
	v_pk_mul_f32 v[106:107], v[106:107], v[106:107]
	v_pk_mul_f32 v[108:109], v[108:109], v[108:109]
	v_cvt_pk_bf16_f32 v110, v110, v111
	v_cvt_pk_bf16_f32 v111, v112, v113
	v_cvt_pk_bf16_f32 v112, v106, v107
	v_cvt_pk_bf16_f32 v113, v108, v109
	v_pk_mul_f32 v[102:103], v[102:103], v[160:161] op_sel:[0,1]
	v_pk_mul_f32 v[104:105], v[104:105], v[160:161] op_sel:[0,1]
	v_pk_mul_f32 v[98:99], v[98:99], v[160:161] op_sel:[0,1]
	v_pk_mul_f32 v[100:101], v[100:101], v[160:161] op_sel:[0,1]
	v_max_f32_e32 v102, 0, v102
	v_max_f32_e32 v103, 0, v103
	v_max_f32_e32 v104, 0, v104
	v_max_f32_e32 v105, 0, v105
	v_max_f32_e32 v98, 0, v98
	v_max_f32_e32 v99, 0, v99
	v_max_f32_e32 v100, 0, v100
	v_max_f32_e32 v101, 0, v101
	v_pk_mul_f32 v[102:103], v[102:103], v[102:103]
	v_pk_mul_f32 v[104:105], v[104:105], v[104:105]
	v_pk_mul_f32 v[98:99], v[98:99], v[98:99]
	v_pk_mul_f32 v[100:101], v[100:101], v[100:101]
	v_cvt_pk_bf16_f32 v102, v102, v103
	v_cvt_pk_bf16_f32 v103, v104, v105
	v_cvt_pk_bf16_f32 v104, v98, v99
	v_cvt_pk_bf16_f32 v105, v100, v101
	s_waitcnt lgkmcnt(0)
	global_store_dwordx4 v200, v[204:207], s[98:99] nt
	global_store_dwordx4 v201, v[208:211], s[98:99] nt
	ds_write_b128 v156, v[110:113]
	ds_write_b128 v156, v[102:105] offset:64
	ds_read_b128 v[212:215], v158
	ds_read_b128 v[216:219], v158 offset:1152
	s_and_b64 vcc, exec, s[20:21]
	s_cbranch_vccz .Lalign_up
	s_barrier
; #define PG8_LAS __attribute__((address_space(3)))
; __device__ __forceinline__ unsigned cvt_pk_bf16(float lo, float hi) { unsigned r; asm volatile("v_cvt_pk_bf16_f32 %0, %1, %2" : "=v"(r) : "v"(lo), "v"(hi)); return r; }
;     __device__ __forceinline__ void operator()(const f32x4 (&acc)[2][2][4][2], const Unit& u, int wr, int wc, int fr, int fq, PG8_LAS float* stash, int par, PG8_LAS unsigned char* stg, const Unit& un) const {
;     ...
;             for (int m = 0; m < 4; ++m) {
;                 const int row = u.pm * BM + ai * HALF + wr * 64 + m * 16 + fr;
;                 const float rs = rsa[ai][m];
;                 PG8_LAS unsigned char* st = stg + fr * 144 + fq * 16;
; #pragma unroll
;                 for (int bj = 0; bj < 2; ++bj) {
;                     float v[8];
; #pragma unroll
;                     for (int i = 0; i < 4; ++i) { v[i] = acc[ai][bj][m][0][i] * rs; v[4 + i] = acc[ai][bj][m][1][i] * rs; }
; #pragma unroll
;                     for (int i = 0; i < 8; ++i) { const float r = fmaxf(v[i], 0.f); v[i] = r * r; }
;                     u32x4 w; w.x = cvt_pk_bf16(v[0], v[1]); w.y = cvt_pk_bf16(v[2], v[3]); w.z = cvt_pk_bf16(v[4], v[5]); w.w = cvt_pk_bf16(v[6], v[7]);
;                     *(PG8_LAS u32x4*)(st + bj * 64) = w;
;                 }
; #pragma unroll
;                 for (int i = 0; i < 2; ++i) { const int c = fq * 16 + fr + 64 * i, rr = c >> 3, pc = c & 7;
;                     const u32x4 w = *(const PG8_LAS u32x4*)(stg + rr * 144 + pc * 16);
;                     __builtin_nontemporal_store(w, (u32x4*)(uo + (size_t)(row - fr + rr) * 4096 + u.pn * BM + wc * 64 + pc * 8)); }
.Lalign_up:
	v_pk_mul_f32 v[94:95], v[94:95], v[148:149] op_sel_hi:[1,0]
	v_pk_mul_f32 v[96:97], v[96:97], v[148:149] op_sel_hi:[1,0]
	v_pk_mul_f32 v[90:91], v[90:91], v[148:149] op_sel_hi:[1,0]
	v_pk_mul_f32 v[92:93], v[92:93], v[148:149] op_sel_hi:[1,0]
	v_max_f32_e32 v94, 0, v94
	v_max_f32_e32 v95, 0, v95
	v_max_f32_e32 v96, 0, v96
	v_max_f32_e32 v97, 0, v97
	v_max_f32_e32 v90, 0, v90
	v_max_f32_e32 v91, 0, v91
	v_max_f32_e32 v92, 0, v92
	v_max_f32_e32 v93, 0, v93
	v_pk_mul_f32 v[94:95], v[94:95], v[94:95]
	v_pk_mul_f32 v[96:97], v[96:97], v[96:97]
	v_pk_mul_f32 v[90:91], v[90:91], v[90:91]
	v_pk_mul_f32 v[92:93], v[92:93], v[92:93]
	v_cvt_pk_bf16_f32 v94, v94, v95
	v_cvt_pk_bf16_f32 v95, v96, v97
	v_cvt_pk_bf16_f32 v96, v90, v91
	v_cvt_pk_bf16_f32 v97, v92, v93
	v_pk_mul_f32 v[86:87], v[86:87], v[148:149] op_sel_hi:[1,0]
	v_pk_mul_f32 v[88:89], v[88:89], v[148:149] op_sel_hi:[1,0]
	v_pk_mul_f32 v[82:83], v[82:83], v[148:149] op_sel_hi:[1,0]
	v_pk_mul_f32 v[84:85], v[84:85], v[148:149] op_sel_hi:[1,0]
	v_max_f32_e32 v86, 0, v86
	v_max_f32_e32 v87, 0, v87
	v_max_f32_e32 v88, 0, v88
	v_max_f32_e32 v89, 0, v89
	v_max_f32_e32 v82, 0, v82
	v_max_f32_e32 v83, 0, v83
	v_max_f32_e32 v84, 0, v84
	v_max_f32_e32 v85, 0, v85
	v_pk_mul_f32 v[86:87], v[86:87], v[86:87]
	v_pk_mul_f32 v[88:89], v[88:89], v[88:89]
	v_pk_mul_f32 v[82:83], v[82:83], v[82:83]
	v_pk_mul_f32 v[84:85], v[84:85], v[84:85]
	v_cvt_pk_bf16_f32 v86, v86, v87
	v_cvt_pk_bf16_f32 v87, v88, v89
	v_cvt_pk_bf16_f32 v88, v82, v83
	v_cvt_pk_bf16_f32 v89, v84, v85
	s_waitcnt lgkmcnt(0)
	s_add_u32 s100, s98, 0x20000
	s_addc_u32 s101, s99, 0
	global_store_dwordx4 v200, v[212:215], s[100:101] nt
	global_store_dwordx4 v201, v[216:219], s[100:101] nt
	ds_write_b128 v156, v[94:97]
	ds_write_b128 v156, v[86:89] offset:64
	ds_read_b128 v[204:207], v158
	ds_read_b128 v[208:211], v158 offset:1152
	v_pk_mul_f32 v[78:79], v[78:79], v[148:149] op_sel:[0,1]
	v_pk_mul_f32 v[80:81], v[80:81], v[148:149] op_sel:[0,1]
	v_pk_mul_f32 v[74:75], v[74:75], v[148:149] op_sel:[0,1]
	v_pk_mul_f32 v[76:77], v[76:77], v[148:149] op_sel:[0,1]
	v_max_f32_e32 v78, 0, v78
	v_max_f32_e32 v79, 0, v79
	v_max_f32_e32 v80, 0, v80
	v_max_f32_e32 v81, 0, v81
	v_max_f32_e32 v74, 0, v74
	v_max_f32_e32 v75, 0, v75
	v_max_f32_e32 v76, 0, v76
	v_max_f32_e32 v77, 0, v77
	v_pk_mul_f32 v[78:79], v[78:79], v[78:79]
	v_pk_mul_f32 v[80:81], v[80:81], v[80:81]
	v_pk_mul_f32 v[74:75], v[74:75], v[74:75]
	v_pk_mul_f32 v[76:77], v[76:77], v[76:77]
	v_cvt_pk_bf16_f32 v78, v78, v79
	v_cvt_pk_bf16_f32 v79, v80, v81
	v_cvt_pk_bf16_f32 v80, v74, v75
	v_cvt_pk_bf16_f32 v81, v76, v77
	v_pk_mul_f32 v[70:71], v[70:71], v[148:149] op_sel:[0,1]
	v_pk_mul_f32 v[72:73], v[72:73], v[148:149] op_sel:[0,1]
	v_pk_mul_f32 v[66:67], v[66:67], v[148:149] op_sel:[0,1]
	v_pk_mul_f32 v[68:69], v[68:69], v[148:149] op_sel:[0,1]
	v_max_f32_e32 v70, 0, v70
	v_max_f32_e32 v71, 0, v71
	v_max_f32_e32 v72, 0, v72
	v_max_f32_e32 v73, 0, v73
	v_max_f32_e32 v66, 0, v66
	v_max_f32_e32 v67, 0, v67
	v_max_f32_e32 v68, 0, v68
	v_max_f32_e32 v69, 0, v69
	v_pk_mul_f32 v[70:71], v[70:71], v[70:71]
	v_pk_mul_f32 v[72:73], v[72:73], v[72:73]
	v_pk_mul_f32 v[66:67], v[66:67], v[66:67]
	v_pk_mul_f32 v[68:69], v[68:69], v[68:69]
	v_cvt_pk_bf16_f32 v70, v70, v71
	v_cvt_pk_bf16_f32 v71, v72, v73
	v_cvt_pk_bf16_f32 v72, v66, v67
	v_cvt_pk_bf16_f32 v73, v68, v69
	s_waitcnt lgkmcnt(0)
	s_add_u32 s100, s98, 0x40000
	s_addc_u32 s101, s99, 0
	global_store_dwordx4 v200, v[204:207], s[100:101] nt
	global_store_dwordx4 v201, v[208:211], s[100:101] nt
	ds_write_b128 v156, v[78:81]
	ds_write_b128 v156, v[70:73] offset:64
	ds_read_b128 v[212:215], v158
	ds_read_b128 v[216:219], v158 offset:1152
	v_pk_mul_f32 v[62:63], v[62:63], v[146:147] op_sel_hi:[1,0]
	v_pk_mul_f32 v[64:65], v[64:65], v[146:147] op_sel_hi:[1,0]
	v_pk_mul_f32 v[58:59], v[58:59], v[146:147] op_sel_hi:[1,0]
	v_pk_mul_f32 v[60:61], v[60:61], v[146:147] op_sel_hi:[1,0]
	v_max_f32_e32 v62, 0, v62
	v_max_f32_e32 v63, 0, v63
	v_max_f32_e32 v64, 0, v64
	v_max_f32_e32 v65, 0, v65
	v_max_f32_e32 v58, 0, v58
	v_max_f32_e32 v59, 0, v59
	v_max_f32_e32 v60, 0, v60
	v_max_f32_e32 v61, 0, v61
	v_pk_mul_f32 v[62:63], v[62:63], v[62:63]
	v_pk_mul_f32 v[64:65], v[64:65], v[64:65]
	v_pk_mul_f32 v[58:59], v[58:59], v[58:59]
	v_pk_mul_f32 v[60:61], v[60:61], v[60:61]
	v_cvt_pk_bf16_f32 v62, v62, v63
	v_cvt_pk_bf16_f32 v63, v64, v65
	v_cvt_pk_bf16_f32 v64, v58, v59
	v_cvt_pk_bf16_f32 v65, v60, v61
	v_pk_mul_f32 v[54:55], v[54:55], v[146:147] op_sel_hi:[1,0]
	v_pk_mul_f32 v[56:57], v[56:57], v[146:147] op_sel_hi:[1,0]
	v_pk_mul_f32 v[50:51], v[50:51], v[146:147] op_sel_hi:[1,0]
	v_pk_mul_f32 v[52:53], v[52:53], v[146:147] op_sel_hi:[1,0]
	v_max_f32_e32 v54, 0, v54
	v_max_f32_e32 v55, 0, v55
	v_max_f32_e32 v56, 0, v56
	v_max_f32_e32 v57, 0, v57
	v_max_f32_e32 v50, 0, v50
	v_max_f32_e32 v51, 0, v51
	v_max_f32_e32 v52, 0, v52
	v_max_f32_e32 v53, 0, v53
	v_pk_mul_f32 v[54:55], v[54:55], v[54:55]
	v_pk_mul_f32 v[56:57], v[56:57], v[56:57]
	v_pk_mul_f32 v[50:51], v[50:51], v[50:51]
	v_pk_mul_f32 v[52:53], v[52:53], v[52:53]
	v_cvt_pk_bf16_f32 v54, v54, v55
	v_cvt_pk_bf16_f32 v55, v56, v57
	v_cvt_pk_bf16_f32 v56, v50, v51
	v_cvt_pk_bf16_f32 v57, v52, v53
	s_waitcnt lgkmcnt(0)
; #define PG8_LAS __attribute__((address_space(3)))
; __device__ __forceinline__ unsigned cvt_pk_bf16(float lo, float hi) { unsigned r; asm volatile("v_cvt_pk_bf16_f32 %0, %1, %2" : "=v"(r) : "v"(lo), "v"(hi)); return r; }
;     __device__ __forceinline__ void operator()(const f32x4 (&acc)[2][2][4][2], const Unit& u, int wr, int wc, int fr, int fq, PG8_LAS float* stash, int par, PG8_LAS unsigned char* stg, const Unit& un) const {
;     ...
;             for (int m = 0; m < 4; ++m) {
;                 const int row = u.pm * BM + ai * HALF + wr * 64 + m * 16 + fr;
;                 const float rs = rsa[ai][m];
;                 PG8_LAS unsigned char* st = stg + fr * 144 + fq * 16;
; #pragma unroll
;                 for (int bj = 0; bj < 2; ++bj) {
;                     float v[8];
; #pragma unroll
;                     for (int i = 0; i < 4; ++i) { v[i] = acc[ai][bj][m][0][i] * rs; v[4 + i] = acc[ai][bj][m][1][i] * rs; }
; #pragma unroll
;                     for (int i = 0; i < 8; ++i) { const float r = fmaxf(v[i], 0.f); v[i] = r * r; }
;                     u32x4 w; w.x = cvt_pk_bf16(v[0], v[1]); w.y = cvt_pk_bf16(v[2], v[3]); w.z = cvt_pk_bf16(v[4], v[5]); w.w = cvt_pk_bf16(v[6], v[7]);
;                     *(PG8_LAS u32x4*)(st + bj * 64) = w;
;                 }
; #pragma unroll
;                 for (int i = 0; i < 2; ++i) { const int c = fq * 16 + fr + 64 * i, rr = c >> 3, pc = c & 7;
;                     const u32x4 w = *(const PG8_LAS u32x4*)(stg + rr * 144 + pc * 16);
;                     __builtin_nontemporal_store(w, (u32x4*)(uo + (size_t)(row - fr + rr) * 4096 + u.pn * BM + wc * 64 + pc * 8)); }
;             }
;         if (newpm) { float rsn[2][4]; rows_part_reduce(pln, rsn);
	s_add_u32 s100, s98, 0x60000
	s_addc_u32 s101, s99, 0
	global_store_dwordx4 v200, v[212:215], s[100:101] nt
	global_store_dwordx4 v201, v[216:219], s[100:101] nt
	ds_write_b128 v156, v[62:65]
	ds_write_b128 v156, v[54:57] offset:64
	ds_read_b128 v[204:207], v158
	ds_read_b128 v[208:211], v158 offset:1152
	v_pk_mul_f32 v[46:47], v[46:47], v[146:147] op_sel:[0,1]
	v_pk_mul_f32 v[48:49], v[48:49], v[146:147] op_sel:[0,1]
	v_pk_mul_f32 v[42:43], v[42:43], v[146:147] op_sel:[0,1]
	v_pk_mul_f32 v[44:45], v[44:45], v[146:147] op_sel:[0,1]
	v_max_f32_e32 v46, 0, v46
	v_max_f32_e32 v47, 0, v47
	v_max_f32_e32 v48, 0, v48
	v_max_f32_e32 v49, 0, v49
	v_max_f32_e32 v42, 0, v42
	v_max_f32_e32 v43, 0, v43
	v_max_f32_e32 v44, 0, v44
	v_max_f32_e32 v45, 0, v45
	v_pk_mul_f32 v[46:47], v[46:47], v[46:47]
	v_pk_mul_f32 v[48:49], v[48:49], v[48:49]
	v_pk_mul_f32 v[42:43], v[42:43], v[42:43]
	v_pk_mul_f32 v[44:45], v[44:45], v[44:45]
	v_cvt_pk_bf16_f32 v46, v46, v47
	v_cvt_pk_bf16_f32 v47, v48, v49
	v_cvt_pk_bf16_f32 v48, v42, v43
	v_cvt_pk_bf16_f32 v49, v44, v45
	v_pk_mul_f32 v[38:39], v[38:39], v[146:147] op_sel:[0,1]
	v_pk_mul_f32 v[40:41], v[40:41], v[146:147] op_sel:[0,1]
	v_pk_mul_f32 v[34:35], v[34:35], v[146:147] op_sel:[0,1]
	v_pk_mul_f32 v[36:37], v[36:37], v[146:147] op_sel:[0,1]
	v_max_f32_e32 v38, 0, v38
	v_max_f32_e32 v39, 0, v39
	v_max_f32_e32 v40, 0, v40
	v_max_f32_e32 v41, 0, v41
	v_max_f32_e32 v34, 0, v34
	v_max_f32_e32 v35, 0, v35
	v_max_f32_e32 v36, 0, v36
	v_max_f32_e32 v37, 0, v37
	v_pk_mul_f32 v[38:39], v[38:39], v[38:39]
	v_pk_mul_f32 v[40:41], v[40:41], v[40:41]
	v_pk_mul_f32 v[34:35], v[34:35], v[34:35]
	v_pk_mul_f32 v[36:37], v[36:37], v[36:37]
	v_cvt_pk_bf16_f32 v38, v38, v39
	v_cvt_pk_bf16_f32 v39, v40, v41
	v_cvt_pk_bf16_f32 v40, v34, v35
	v_cvt_pk_bf16_f32 v41, v36, v37
	s_waitcnt lgkmcnt(0)
	s_add_u32 s100, s98, 0x100000
	s_addc_u32 s101, s99, 0
	global_store_dwordx4 v200, v[204:207], s[100:101] nt
	global_store_dwordx4 v201, v[208:211], s[100:101] nt
	ds_write_b128 v156, v[46:49]
	ds_write_b128 v156, v[38:41] offset:64
	ds_read_b128 v[212:215], v158
	ds_read_b128 v[216:219], v158 offset:1152
	v_pk_mul_f32 v[30:31], v[30:31], v[144:145] op_sel_hi:[1,0]
	v_pk_mul_f32 v[32:33], v[32:33], v[144:145] op_sel_hi:[1,0]
	v_pk_mul_f32 v[26:27], v[26:27], v[144:145] op_sel_hi:[1,0]
	v_pk_mul_f32 v[28:29], v[28:29], v[144:145] op_sel_hi:[1,0]
	v_max_f32_e32 v30, 0, v30
	v_max_f32_e32 v31, 0, v31
	v_max_f32_e32 v32, 0, v32
	v_max_f32_e32 v33, 0, v33
	v_max_f32_e32 v26, 0, v26
	v_max_f32_e32 v27, 0, v27
	v_max_f32_e32 v28, 0, v28
	v_max_f32_e32 v29, 0, v29
	v_pk_mul_f32 v[30:31], v[30:31], v[30:31]
	v_pk_mul_f32 v[32:33], v[32:33], v[32:33]
	v_pk_mul_f32 v[26:27], v[26:27], v[26:27]
	v_pk_mul_f32 v[28:29], v[28:29], v[28:29]
	v_cvt_pk_bf16_f32 v30, v30, v31
	v_cvt_pk_bf16_f32 v31, v32, v33
	v_cvt_pk_bf16_f32 v32, v26, v27
	v_cvt_pk_bf16_f32 v33, v28, v29
	v_pk_mul_f32 v[22:23], v[22:23], v[144:145] op_sel_hi:[1,0]
	v_pk_mul_f32 v[24:25], v[24:25], v[144:145] op_sel_hi:[1,0]
	v_pk_mul_f32 v[18:19], v[18:19], v[144:145] op_sel_hi:[1,0]
	v_pk_mul_f32 v[20:21], v[20:21], v[144:145] op_sel_hi:[1,0]
	v_max_f32_e32 v22, 0, v22
	v_max_f32_e32 v23, 0, v23
	v_max_f32_e32 v24, 0, v24
	v_max_f32_e32 v25, 0, v25
	v_max_f32_e32 v18, 0, v18
	v_max_f32_e32 v19, 0, v19
	v_max_f32_e32 v20, 0, v20
	v_max_f32_e32 v21, 0, v21
	v_pk_mul_f32 v[22:23], v[22:23], v[22:23]
	v_pk_mul_f32 v[24:25], v[24:25], v[24:25]
	v_pk_mul_f32 v[18:19], v[18:19], v[18:19]
	v_pk_mul_f32 v[20:21], v[20:21], v[20:21]
	v_cvt_pk_bf16_f32 v22, v22, v23
	v_cvt_pk_bf16_f32 v23, v24, v25
	v_cvt_pk_bf16_f32 v24, v18, v19
	v_cvt_pk_bf16_f32 v25, v20, v21
	s_waitcnt lgkmcnt(0)
	s_add_u32 s100, s98, 0x120000
	s_addc_u32 s101, s99, 0
	global_store_dwordx4 v200, v[212:215], s[100:101] nt
	global_store_dwordx4 v201, v[216:219], s[100:101] nt
	ds_write_b128 v156, v[30:33]
	ds_write_b128 v156, v[22:25] offset:64
	ds_read_b128 v[204:207], v158
	ds_read_b128 v[208:211], v158 offset:1152
	v_pk_mul_f32 v[14:15], v[14:15], v[144:145] op_sel:[0,1]
	v_pk_mul_f32 v[16:17], v[16:17], v[144:145] op_sel:[0,1]
	v_pk_mul_f32 v[10:11], v[10:11], v[144:145] op_sel:[0,1]
	v_pk_mul_f32 v[12:13], v[12:13], v[144:145] op_sel:[0,1]
	v_max_f32_e32 v14, 0, v14
	v_max_f32_e32 v15, 0, v15
	v_max_f32_e32 v16, 0, v16
	v_max_f32_e32 v17, 0, v17
	v_max_f32_e32 v10, 0, v10
	v_max_f32_e32 v11, 0, v11
	v_max_f32_e32 v12, 0, v12
	v_max_f32_e32 v13, 0, v13
	v_pk_mul_f32 v[14:15], v[14:15], v[14:15]
	v_pk_mul_f32 v[16:17], v[16:17], v[16:17]
	v_pk_mul_f32 v[10:11], v[10:11], v[10:11]
	v_pk_mul_f32 v[12:13], v[12:13], v[12:13]
	v_cvt_pk_bf16_f32 v14, v14, v15
	v_cvt_pk_bf16_f32 v15, v16, v17
	v_cvt_pk_bf16_f32 v16, v10, v11
	v_cvt_pk_bf16_f32 v17, v12, v13
	v_pk_mul_f32 v[6:7], v[6:7], v[144:145] op_sel:[0,1]
	v_pk_mul_f32 v[8:9], v[8:9], v[144:145] op_sel:[0,1]
	v_pk_mul_f32 v[2:3], v[2:3], v[144:145] op_sel:[0,1]
	v_pk_mul_f32 v[4:5], v[4:5], v[144:145] op_sel:[0,1]
	v_max_f32_e32 v6, 0, v6
	v_max_f32_e32 v7, 0, v7
	v_max_f32_e32 v8, 0, v8
	v_max_f32_e32 v9, 0, v9
	v_max_f32_e32 v2, 0, v2
	v_max_f32_e32 v3, 0, v3
	v_max_f32_e32 v4, 0, v4
	v_max_f32_e32 v5, 0, v5
	v_pk_mul_f32 v[6:7], v[6:7], v[6:7]
	v_pk_mul_f32 v[8:9], v[8:9], v[8:9]
	v_pk_mul_f32 v[2:3], v[2:3], v[2:3]
	v_pk_mul_f32 v[4:5], v[4:5], v[4:5]
	v_cvt_pk_bf16_f32 v6, v6, v7
	v_cvt_pk_bf16_f32 v7, v8, v9
	v_cvt_pk_bf16_f32 v8, v2, v3
	v_cvt_pk_bf16_f32 v9, v4, v5
	s_waitcnt lgkmcnt(0)
	s_add_u32 s100, s98, 0x140000
	s_addc_u32 s101, s99, 0
	global_store_dwordx4 v200, v[204:207], s[100:101] nt
	global_store_dwordx4 v201, v[208:211], s[100:101] nt
	ds_write_b128 v156, v[14:17]
	ds_write_b128 v156, v[6:9] offset:64
	ds_read_b128 v[212:215], v158
	ds_read_b128 v[216:219], v158 offset:1152
	s_waitcnt lgkmcnt(0)
	s_add_u32 s100, s98, 0x160000
	s_addc_u32 s101, s99, 0
	global_store_dwordx4 v200, v[212:215], s[100:101] nt
	global_store_dwordx4 v201, v[216:219], s[100:101] nt
	s_andn2_b64 vcc, exec, s[42:43]
	s_cbranch_vccnz .LBB0_852
; __device__ __forceinline__ float sum_x16(float s) { auto r = __builtin_amdgcn_permlane16_swap(__float_as_uint(s), __float_as_uint(s), false, false); return __uint_as_float(r[0]) + __uint_as_float(r[1]); }
; __device__ __forceinline__ float sum_x32(float s) { auto r = __builtin_amdgcn_permlane32_swap(__float_as_uint(s), __float_as_uint(s), false, false); return __uint_as_float(r[0]) + __uint_as_float(r[1]); }
; __device__ __forceinline__ void rows_part_reduce(const f32x4 (&pl)[2][4], float (&rs)[2][4]) {
; #pragma unroll
;     for (int ai = 0; ai < 2; ++ai)
; #pragma unroll
;         for (int m = 0; m < 4; ++m) { float s = (pl[ai][m][0] + pl[ai][m][1]) + (pl[ai][m][2] + pl[ai][m][3]); s = sum_x16(s); s = sum_x32(s); rs[ai][m] = __builtin_amdgcn_rsqf(s * (1.0f / 1024.0f) + 1e-6f); }
; }
;     __device__ __forceinline__ void operator()(const f32x4 (&acc)[2][2][4][2], const Unit& u, int wr, int wc, int fr, int fq, PG8_LAS float* stash, int par, PG8_LAS unsigned char* stg, const Unit& un) const {
;     ...
;         if (newpm) { float rsn[2][4]; rows_part_reduce(pln, rsn);
;           if (fq == 0) {
; #pragma unroll
;               for (int ai = 0; ai < 2; ++ai)
; #pragma unroll
;                   for (int m = 0; m < 4; ++m) stash[(par ^ 1) * 256 + ai * HALF + wr * 64 + m * 16 + fr] = rsn[ai][m]; } }
	s_waitcnt vmcnt(16)
	v_add_f32_e32 v2, v188, v195
	v_add_f32_e32 v3, v197, v198
	v_add_f32_e32 v4, v184, v192
	v_add_f32_e32 v5, v194, v196
	v_add_f32_e32 v6, v181, v189
	v_add_f32_e32 v7, v191, v193
	v_add_f32_e32 v8, v178, v185
	v_add_f32_e32 v9, v187, v190
	v_add_f32_e32 v10, v175, v180
	v_add_f32_e32 v11, v183, v186
	v_add_f32_e32 v12, v171, v176
	v_add_f32_e32 v13, v179, v182
	v_add_f32_e32 v14, v169, v172
	v_add_f32_e32 v15, v174, v177
	v_add_f32_e32 v16, v159, v168
	v_add_f32_e32 v17, v170, v173
	v_add_f32_e32 v2, v2, v3
	v_add_f32_e32 v4, v4, v5
	v_add_f32_e32 v6, v6, v7
	v_add_f32_e32 v8, v8, v9
	v_add_f32_e32 v10, v10, v11
	v_add_f32_e32 v12, v12, v13
	v_add_f32_e32 v14, v14, v15
	v_add_f32_e32 v16, v16, v17
	v_mov_b32_e32 v3, v2
	v_mov_b32_e32 v5, v4
	v_mov_b32_e32 v7, v6
	v_mov_b32_e32 v9, v8
	v_mov_b32_e32 v11, v10
	v_mov_b32_e32 v13, v12
	v_mov_b32_e32 v15, v14
	v_mov_b32_e32 v17, v16
	v_permlane16_swap_b32_e32 v2, v3
	v_permlane16_swap_b32_e32 v4, v5
	v_permlane16_swap_b32_e32 v6, v7
	v_permlane16_swap_b32_e32 v8, v9
	v_permlane16_swap_b32_e32 v10, v11
	v_permlane16_swap_b32_e32 v12, v13
	v_permlane16_swap_b32_e32 v14, v15
	v_permlane16_swap_b32_e32 v16, v17
	v_add_f32_e32 v2, v2, v3
	v_add_f32_e32 v4, v4, v5
	v_add_f32_e32 v6, v6, v7
	v_add_f32_e32 v8, v8, v9
	v_add_f32_e32 v10, v10, v11
	v_add_f32_e32 v12, v12, v13
	v_add_f32_e32 v14, v14, v15
	v_add_f32_e32 v16, v16, v17
	v_mov_b32_e32 v3, v2
	v_mov_b32_e32 v5, v4
	v_mov_b32_e32 v7, v6
	v_mov_b32_e32 v9, v8
	v_mov_b32_e32 v11, v10
	v_mov_b32_e32 v13, v12
	v_mov_b32_e32 v15, v14
	v_mov_b32_e32 v17, v16
	v_permlane32_swap_b32_e32 v2, v3
	v_permlane32_swap_b32_e32 v4, v5
	v_permlane32_swap_b32_e32 v6, v7
	v_permlane32_swap_b32_e32 v8, v9
	v_permlane32_swap_b32_e32 v10, v11
	v_permlane32_swap_b32_e32 v12, v13
	v_permlane32_swap_b32_e32 v14, v15
	v_permlane32_swap_b32_e32 v16, v17
	s_and_saveexec_b64 s[42:43], s[34:35]
	s_cbranch_execz .LBB0_851
	v_add_f32_e32 v16, v16, v17
	v_mov_b32_e32 v17, 0x358637bd
	v_add_f32_e32 v4, v4, v5
	v_add_f32_e32 v2, v2, v3
	v_add_f32_e32 v8, v8, v9
	v_add_f32_e32 v6, v6, v7
	v_fmamk_f32 v4, v4, 0x3a800000, v17
	v_fmamk_f32 v2, v2, 0x3a800000, v17
	v_add_f32_e32 v12, v12, v13
	v_add_f32_e32 v10, v10, v11
	v_fmamk_f32 v8, v8, 0x3a800000, v17
	v_fmamk_f32 v6, v6, 0x3a800000, v17
	v_rsq_f32_e32 v4, v4
	v_rsq_f32_e32 v2, v2
	v_add_f32_e32 v14, v14, v15
	v_fmamk_f32 v12, v12, 0x3a800000, v17
	v_fmamk_f32 v10, v10, 0x3a800000, v17
	v_rsq_f32_e32 v8, v8
	v_rsq_f32_e32 v6, v6
	v_lshlrev_b32_e32 v3, 10, v157
	v_fmamk_f32 v16, v16, 0x3a800000, v17
	v_fmamk_f32 v14, v14, 0x3a800000, v17
	v_rsq_f32_e32 v12, v12
	v_rsq_f32_e32 v10, v10
	v_xor_b32_e32 v3, 0x400, v3
	v_rsq_f32_e32 v16, v16
	v_rsq_f32_e32 v14, v14
	v_add_u32_e32 v3, v152, v3
	ds_write2_b32 v3, v2, v4 offset1:16
	ds_write2_b32 v3, v6, v8 offset0:32 offset1:48
	ds_write2_b32 v3, v10, v12 offset0:128 offset1:144
	ds_write2_b32 v3, v14, v16 offset0:160 offset1:176

; #define PG8_STAGE(bufoff, gbase, voff) do { _Pragma("unroll") for (int _i = 0; _i < 2; ++_i) \
;         __builtin_amdgcn_global_load_lds((const unsigned*)((const char*)(gbase) + (voff)[_i]), (PG8_LAS unsigned*)(lds + (bufoff) + ldsw + _i * 8192), 16, 0, 0); } while (0)
; #define PG8_LDA(dst, b, h) do { _Pragma("unroll") for (int m = 0; m < 4; ++m) _Pragma("unroll") for (int k = 0; k < 2; ++k) dst[m][k] = *(const PG8_LAS bf16x8*)(lds + PG8_SA(b, h) + aoff + m * 2048 + k * 1024); } while (0)
; #define PG8_LDB(dst, b, h) do { _Pragma("unroll") for (int n = 0; n < 2; ++n) _Pragma("unroll") for (int k = 0; k < 2; ++k) dst[n][k] = *(const PG8_LAS bf16x8*)(lds + PG8_SB(b, h) + boff + n * 2048 + k * 1024); } while (0)
; #define PG8_MMA(ai, bj, At, Bt) do { __builtin_amdgcn_s_setprio(1); _Pragma("unroll") for (int m = 0; m < 4; ++m) _Pragma("unroll") for (int n = 0; n < 2; ++n) _Pragma("unroll") for (int k = 0; k < 2; ++k) \
;         acc[ai][bj][m][n] = __builtin_amdgcn_mfma_f32_16x16x32_bf16(Bt[n][k], At[m][k], acc[ai][bj][m][n], 0, 0, 0); __builtin_amdgcn_s_setprio(0); } while (0)
; #define PG8_WAIT_V(n) asm volatile("s_waitcnt vmcnt(" #n ")" ::: "memory")
; #define PG8_WAIT_L(n) asm volatile("s_waitcnt lgkmcnt(" #n ")" ::: "memory")
; #define PG8_BAR __builtin_amdgcn_s_barrier()
; #define PG8_SCHED __builtin_amdgcn_sched_barrier(0)
; template <class Epi, class Sched, bool ALIGN_EPI = false, bool SP2 = false>
; __device__ __forceinline__ void gemm_phase(PG8_LAS unsigned char* lds, const Gemm g, const Sched& S, const Epi& E, const int wave_s) {
;     ...
;             PG8_LDB(B0, 0, 0); PG8_LDB(B1, 0, 1); PG8_SCHED; PG8_LDA(At, 0, 0); PG8_STAGE(PG8_SA(1, 1), a1 + hstep, voffA);
;             PG8_WAIT_V(8); PG8_WAIT_L(0); PG8_BAR; PG8_MMA(0, 0, At, B0); PG8_MMA(0, 1, At, B1); PG8_BAR; PG8_SCHED;
;             PG8_LDA(At, 0, 1); PG8_STAGE(PG8_SB(0, 0), b2, voffB); PG8_STAGE(PG8_SB(0, 1), b2 + bhstep, voffB); PG8_STAGE(PG8_SA(0, 0), a2, voffA);
;             PG8_WAIT_V(8); PG8_WAIT_L(0); PG8_BAR; PG8_MMA(1, 0, At, B0); PG8_MMA(1, 1, At, B1); PG8_BAR; PG8_SCHED;
.LBB0_923:
	s_add_u32 s46, s42, 0xfff00080
	s_addc_u32 s47, s43, -1
	s_add_i32 s51, 0, 0x10000
	s_cmp_eq_u32 s50, 60
	s_cselect_b32 s49, s15, s47
	s_cselect_b32 s48, s16, s46
	s_cselect_b32 s47, s17, s45
	s_cselect_b32 s46, s23, s29
	s_add_i32 s54, 0, 0x14000
	v_add_u32_e32 v142, s51, v205
	v_add_u32_e32 v160, s54, v205
	ds_read_b128 v[130:133], v142
	ds_read_b128 v[134:137], v142 offset:1024
	ds_read_b128 v[138:141], v142 offset:2048
	ds_read_b128 v[142:145], v142 offset:3072
	ds_read_b128 v[146:149], v160
	ds_read_b128 v[150:153], v160 offset:1024
	ds_read_b128 v[154:157], v160 offset:2048
	ds_read_b128 v[160:163], v160 offset:3072
	v_lshl_add_u64 v[220:221], s[42:43], 0, v[178:179]
	s_add_i32 m0, s5, 0xc000
	ds_read_b128 v[164:167], v208
	ds_read_b128 v[182:185], v208 offset:1024
	ds_read_b128 v[186:189], v208 offset:2048
	ds_read_b128 v[190:193], v208 offset:3072
	ds_read_b128 v[194:197], v208 offset:4096
	ds_read_b128 v[198:201], v208 offset:5120
	ds_read_b128 v[212:215], v208 offset:6144
	ds_read_b128 v[216:219], v208 offset:7168
	global_load_lds_dwordx4 v[220:221], off
	v_lshl_add_u64 v[220:221], s[42:43], 0, v[180:181]
	s_add_i32 m0, s5, 0xe000
	s_nop 0
	global_load_lds_dwordx4 v[220:221], off
	s_waitcnt vmcnt(8)
	s_waitcnt lgkmcnt(0)
	s_barrier
	s_setprio 1
	s_waitcnt lgkmcnt(0)
	v_mfma_f32_16x16x32_bf16 v[126:129], v[130:133], v[164:167], v[126:129]
	v_mfma_f32_16x16x32_bf16 v[126:129], v[134:137], v[182:185], v[126:129]
	v_mfma_f32_16x16x32_bf16 v[122:125], v[138:141], v[164:167], v[122:125]
	v_mfma_f32_16x16x32_bf16 v[122:125], v[142:145], v[182:185], v[122:125]
	v_mfma_f32_16x16x32_bf16 v[110:113], v[130:133], v[186:189], v[110:113]
	v_mfma_f32_16x16x32_bf16 v[110:113], v[134:137], v[190:193], v[110:113]
	v_mfma_f32_16x16x32_bf16 v[106:109], v[138:141], v[186:189], v[106:109]
	v_mfma_f32_16x16x32_bf16 v[106:109], v[142:145], v[190:193], v[106:109]
	v_mfma_f32_16x16x32_bf16 v[94:97], v[130:133], v[194:197], v[94:97]
	v_mfma_f32_16x16x32_bf16 v[94:97], v[134:137], v[198:201], v[94:97]
	v_mfma_f32_16x16x32_bf16 v[90:93], v[138:141], v[194:197], v[90:93]
	v_mfma_f32_16x16x32_bf16 v[90:93], v[142:145], v[198:201], v[90:93]
	v_mfma_f32_16x16x32_bf16 v[78:81], v[130:133], v[212:215], v[78:81]
	v_mfma_f32_16x16x32_bf16 v[78:81], v[134:137], v[216:219], v[78:81]
	v_mfma_f32_16x16x32_bf16 v[74:77], v[138:141], v[212:215], v[74:77]
	v_mfma_f32_16x16x32_bf16 v[74:77], v[142:145], v[216:219], v[74:77]
	s_setprio 0
	s_setprio 1
	v_mfma_f32_16x16x32_bf16 v[118:121], v[146:149], v[164:167], v[118:121]
	v_mfma_f32_16x16x32_bf16 v[118:121], v[150:153], v[182:185], v[118:121]
	v_mfma_f32_16x16x32_bf16 v[114:117], v[154:157], v[164:167], v[114:117]
	v_mfma_f32_16x16x32_bf16 v[114:117], v[160:163], v[182:185], v[114:117]
	v_mfma_f32_16x16x32_bf16 v[102:105], v[146:149], v[186:189], v[102:105]
	v_mfma_f32_16x16x32_bf16 v[102:105], v[150:153], v[190:193], v[102:105]
	v_mfma_f32_16x16x32_bf16 v[98:101], v[154:157], v[186:189], v[98:101]
	v_mfma_f32_16x16x32_bf16 v[98:101], v[160:163], v[190:193], v[98:101]
	v_mfma_f32_16x16x32_bf16 v[86:89], v[146:149], v[194:197], v[86:89]
	v_mfma_f32_16x16x32_bf16 v[86:89], v[150:153], v[198:201], v[86:89]
	v_mfma_f32_16x16x32_bf16 v[82:85], v[154:157], v[194:197], v[82:85]
	v_mfma_f32_16x16x32_bf16 v[82:85], v[160:163], v[198:201], v[82:85]
	v_mfma_f32_16x16x32_bf16 v[70:73], v[146:149], v[212:215], v[70:73]
	v_mfma_f32_16x16x32_bf16 v[70:73], v[150:153], v[216:219], v[70:73]
	v_mfma_f32_16x16x32_bf16 v[66:69], v[154:157], v[212:215], v[66:69]
	v_mfma_f32_16x16x32_bf16 v[66:69], v[160:163], v[216:219], v[66:69]
	s_setprio 0
	s_barrier
	s_add_i32 s51, s51, s4
	v_lshl_add_u64 v[220:221], s[46:47], 0, v[170:171]
	s_mov_b32 m0, s51
	ds_read_b128 v[164:167], v208 offset:16384
	ds_read_b128 v[182:185], v208 offset:17408
	ds_read_b128 v[186:189], v208 offset:18432
	ds_read_b128 v[190:193], v208 offset:19456
	ds_read_b128 v[194:197], v208 offset:20480
	ds_read_b128 v[198:201], v208 offset:21504
	ds_read_b128 v[212:215], v208 offset:22528
	ds_read_b128 v[216:219], v208 offset:23552
	global_load_lds_dwordx4 v[220:221], off
	s_add_i32 m0, s51, 0x2000
	s_add_u32 s52, s46, 0x40000
	v_lshl_add_u64 v[222:223], s[46:47], 0, v[158:159]
	s_addc_u32 s53, s47, 0
	s_add_i32 s51, s54, s4
	global_load_lds_dwordx4 v[222:223], off
	v_lshl_add_u64 v[224:225], s[52:53], 0, v[170:171]
	s_mov_b32 m0, s51
	v_lshl_add_u64 v[226:227], s[48:49], 0, v[168:169]
	global_load_lds_dwordx4 v[224:225], off
	v_lshl_add_u64 v[224:225], s[52:53], 0, v[158:159]
	s_add_i32 m0, s51, 0x2000
	s_nop 0
	global_load_lds_dwordx4 v[224:225], off
	v_lshl_add_u64 v[224:225], s[48:49], 0, v[172:173]
	s_mov_b32 m0, s5
	s_nop 0
	global_load_lds_dwordx4 v[224:225], off
	s_mov_b32 m0, s6
	s_nop 0
	global_load_lds_dwordx4 v[226:227], off
	s_waitcnt vmcnt(8)
	s_waitcnt lgkmcnt(0)
	s_barrier
; #define PG8_STAGE(bufoff, gbase, voff) do { _Pragma("unroll") for (int _i = 0; _i < 2; ++_i) \
;         __builtin_amdgcn_global_load_lds((const unsigned*)((const char*)(gbase) + (voff)[_i]), (PG8_LAS unsigned*)(lds + (bufoff) + ldsw + _i * 8192), 16, 0, 0); } while (0)
; #define PG8_LDA(dst, b, h) do { _Pragma("unroll") for (int m = 0; m < 4; ++m) _Pragma("unroll") for (int k = 0; k < 2; ++k) dst[m][k] = *(const PG8_LAS bf16x8*)(lds + PG8_SA(b, h) + aoff + m * 2048 + k * 1024); } while (0)
; #define PG8_LDB(dst, b, h) do { _Pragma("unroll") for (int n = 0; n < 2; ++n) _Pragma("unroll") for (int k = 0; k < 2; ++k) dst[n][k] = *(const PG8_LAS bf16x8*)(lds + PG8_SB(b, h) + boff + n * 2048 + k * 1024); } while (0)
; #define PG8_MMA(ai, bj, At, Bt) do { __builtin_amdgcn_s_setprio(1); _Pragma("unroll") for (int m = 0; m < 4; ++m) _Pragma("unroll") for (int n = 0; n < 2; ++n) _Pragma("unroll") for (int k = 0; k < 2; ++k) \
;         acc[ai][bj][m][n] = __builtin_amdgcn_mfma_f32_16x16x32_bf16(Bt[n][k], At[m][k], acc[ai][bj][m][n], 0, 0, 0); __builtin_amdgcn_s_setprio(0); } while (0)
; #define PG8_WAIT_V(n) asm volatile("s_waitcnt vmcnt(" #n ")" ::: "memory")
; #define PG8_WAIT_L(n) asm volatile("s_waitcnt lgkmcnt(" #n ")" ::: "memory")
; #define PG8_BAR __builtin_amdgcn_s_barrier()
; #define PG8_SCHED __builtin_amdgcn_sched_barrier(0)
; template <class Epi, class Sched, bool ALIGN_EPI = false, bool SP2 = false>
; __device__ __forceinline__ void gemm_phase(PG8_LAS unsigned char* lds, const Gemm g, const Sched& S, const Epi& E, const int wave_s) {
;     ...
;             PG8_WAIT_V(8); PG8_WAIT_L(0); PG8_BAR; PG8_MMA(1, 0, At, B0); PG8_MMA(1, 1, At, B1); PG8_BAR; PG8_SCHED;
;             PG8_LDB(B0, 1, 0); PG8_LDB(B1, 1, 1); PG8_SCHED; PG8_LDA(At, 1, 0); PG8_STAGE(PG8_SA(0, 1), a2 + hstep, voffA);
;             PG8_WAIT_V(8); PG8_WAIT_L(0); PG8_BAR; PG8_MMA(0, 0, At, B0); PG8_MMA(0, 1, At, B1); PG8_BAR; PG8_SCHED;
	s_setprio 1
	s_waitcnt lgkmcnt(0)
	v_mfma_f32_16x16x32_bf16 v[62:65], v[130:133], v[164:167], v[62:65]
	v_mfma_f32_16x16x32_bf16 v[62:65], v[134:137], v[182:185], v[62:65]
	v_mfma_f32_16x16x32_bf16 v[58:61], v[138:141], v[164:167], v[58:61]
	v_mfma_f32_16x16x32_bf16 v[58:61], v[142:145], v[182:185], v[58:61]
	v_mfma_f32_16x16x32_bf16 v[46:49], v[130:133], v[186:189], v[46:49]
	v_mfma_f32_16x16x32_bf16 v[46:49], v[134:137], v[190:193], v[46:49]
	v_mfma_f32_16x16x32_bf16 v[42:45], v[138:141], v[186:189], v[42:45]
	v_mfma_f32_16x16x32_bf16 v[42:45], v[142:145], v[190:193], v[42:45]
	v_mfma_f32_16x16x32_bf16 v[30:33], v[130:133], v[194:197], v[30:33]
	v_mfma_f32_16x16x32_bf16 v[30:33], v[134:137], v[198:201], v[30:33]
	v_mfma_f32_16x16x32_bf16 v[26:29], v[138:141], v[194:197], v[26:29]
	v_mfma_f32_16x16x32_bf16 v[26:29], v[142:145], v[198:201], v[26:29]
	v_mfma_f32_16x16x32_bf16 v[14:17], v[130:133], v[212:215], v[14:17]
	v_mfma_f32_16x16x32_bf16 v[14:17], v[134:137], v[216:219], v[14:17]
	v_mfma_f32_16x16x32_bf16 v[10:13], v[138:141], v[212:215], v[10:13]
	v_mfma_f32_16x16x32_bf16 v[10:13], v[142:145], v[216:219], v[10:13]
	s_setprio 0
	s_setprio 1
	v_mfma_f32_16x16x32_bf16 v[54:57], v[146:149], v[164:167], v[54:57]
	v_mfma_f32_16x16x32_bf16 v[54:57], v[150:153], v[182:185], v[54:57]
	v_mfma_f32_16x16x32_bf16 v[50:53], v[154:157], v[164:167], v[50:53]
	v_mfma_f32_16x16x32_bf16 v[50:53], v[160:163], v[182:185], v[50:53]
	v_mfma_f32_16x16x32_bf16 v[38:41], v[146:149], v[186:189], v[38:41]
	v_mfma_f32_16x16x32_bf16 v[38:41], v[150:153], v[190:193], v[38:41]
	v_mfma_f32_16x16x32_bf16 v[34:37], v[154:157], v[186:189], v[34:37]
	v_mfma_f32_16x16x32_bf16 v[34:37], v[160:163], v[190:193], v[34:37]
	v_mfma_f32_16x16x32_bf16 v[22:25], v[146:149], v[194:197], v[22:25]
	v_mfma_f32_16x16x32_bf16 v[22:25], v[150:153], v[198:201], v[22:25]
	v_mfma_f32_16x16x32_bf16 v[18:21], v[154:157], v[194:197], v[18:21]
	v_mfma_f32_16x16x32_bf16 v[18:21], v[160:163], v[198:201], v[18:21]
	v_mfma_f32_16x16x32_bf16 v[6:9], v[146:149], v[212:215], v[6:9]
	v_mfma_f32_16x16x32_bf16 v[6:9], v[150:153], v[216:219], v[6:9]
	v_mfma_f32_16x16x32_bf16 v[2:5], v[154:157], v[212:215], v[2:5]
	v_mfma_f32_16x16x32_bf16 v[2:5], v[160:163], v[216:219], v[2:5]
	s_setprio 0
	s_barrier
	s_add_i32 s51, 0, 0x18000
	s_add_i32 s52, 0, 0x1c000
	v_add_u32_e32 v142, s51, v205
	v_add_u32_e32 v160, s52, v205
	ds_read_b128 v[130:133], v142
	ds_read_b128 v[134:137], v142 offset:1024
	ds_read_b128 v[138:141], v142 offset:2048
	ds_read_b128 v[142:145], v142 offset:3072
	ds_read_b128 v[146:149], v160
	ds_read_b128 v[150:153], v160 offset:1024
	ds_read_b128 v[154:157], v160 offset:2048
	ds_read_b128 v[160:163], v160 offset:3072
	s_add_u32 s48, s48, 0x100000
	s_addc_u32 s49, s49, 0
	s_mov_b32 m0, s7
	v_lshl_add_u64 v[228:229], s[48:49], 0, v[172:173]
	ds_read_b128 v[164:167], v208 offset:32768
	ds_read_b128 v[182:185], v208 offset:33792
	ds_read_b128 v[186:189], v208 offset:34816
	ds_read_b128 v[190:193], v208 offset:35840
	ds_read_b128 v[194:197], v208 offset:36864
	ds_read_b128 v[198:201], v208 offset:37888
	ds_read_b128 v[212:215], v208 offset:38912
	ds_read_b128 v[216:219], v208 offset:39936
	global_load_lds_dwordx4 v[228:229], off
	v_lshl_add_u64 v[228:229], s[48:49], 0, v[168:169]
	s_mov_b32 m0, s8
	s_nop 0
	global_load_lds_dwordx4 v[228:229], off
	s_waitcnt vmcnt(8)
	s_waitcnt lgkmcnt(0)
	s_barrier
	s_setprio 1
	s_waitcnt lgkmcnt(0)
	v_mfma_f32_16x16x32_bf16 v[126:129], v[130:133], v[164:167], v[126:129]
	v_mfma_f32_16x16x32_bf16 v[126:129], v[134:137], v[182:185], v[126:129]
	v_mfma_f32_16x16x32_bf16 v[122:125], v[138:141], v[164:167], v[122:125]
	v_mfma_f32_16x16x32_bf16 v[122:125], v[142:145], v[182:185], v[122:125]
	v_mfma_f32_16x16x32_bf16 v[110:113], v[130:133], v[186:189], v[110:113]
	v_mfma_f32_16x16x32_bf16 v[110:113], v[134:137], v[190:193], v[110:113]
	v_mfma_f32_16x16x32_bf16 v[106:109], v[138:141], v[186:189], v[106:109]
	v_mfma_f32_16x16x32_bf16 v[106:109], v[142:145], v[190:193], v[106:109]
	v_mfma_f32_16x16x32_bf16 v[94:97], v[130:133], v[194:197], v[94:97]
	v_mfma_f32_16x16x32_bf16 v[94:97], v[134:137], v[198:201], v[94:97]
	v_mfma_f32_16x16x32_bf16 v[90:93], v[138:141], v[194:197], v[90:93]
	v_mfma_f32_16x16x32_bf16 v[90:93], v[142:145], v[198:201], v[90:93]
	v_mfma_f32_16x16x32_bf16 v[78:81], v[130:133], v[212:215], v[78:81]
	v_mfma_f32_16x16x32_bf16 v[78:81], v[134:137], v[216:219], v[78:81]
	v_mfma_f32_16x16x32_bf16 v[74:77], v[138:141], v[212:215], v[74:77]
	v_mfma_f32_16x16x32_bf16 v[74:77], v[142:145], v[216:219], v[74:77]
	s_setprio 0
	s_setprio 1
	v_mfma_f32_16x16x32_bf16 v[118:121], v[146:149], v[164:167], v[118:121]
	v_mfma_f32_16x16x32_bf16 v[118:121], v[150:153], v[182:185], v[118:121]
	v_mfma_f32_16x16x32_bf16 v[114:117], v[154:157], v[164:167], v[114:117]
	v_mfma_f32_16x16x32_bf16 v[114:117], v[160:163], v[182:185], v[114:117]
	v_mfma_f32_16x16x32_bf16 v[102:105], v[146:149], v[186:189], v[102:105]
	v_mfma_f32_16x16x32_bf16 v[102:105], v[150:153], v[190:193], v[102:105]
	v_mfma_f32_16x16x32_bf16 v[98:101], v[154:157], v[186:189], v[98:101]
	v_mfma_f32_16x16x32_bf16 v[98:101], v[160:163], v[190:193], v[98:101]
	v_mfma_f32_16x16x32_bf16 v[86:89], v[146:149], v[194:197], v[86:89]
	v_mfma_f32_16x16x32_bf16 v[86:89], v[150:153], v[198:201], v[86:89]
	v_mfma_f32_16x16x32_bf16 v[82:85], v[154:157], v[194:197], v[82:85]
	v_mfma_f32_16x16x32_bf16 v[82:85], v[160:163], v[198:201], v[82:85]
	v_mfma_f32_16x16x32_bf16 v[70:73], v[146:149], v[212:215], v[70:73]
	v_mfma_f32_16x16x32_bf16 v[70:73], v[150:153], v[216:219], v[70:73]
	v_mfma_f32_16x16x32_bf16 v[66:69], v[154:157], v[212:215], v[66:69]
	v_mfma_f32_16x16x32_bf16 v[66:69], v[160:163], v[216:219], v[66:69]
	s_setprio 0
	s_barrier
; #define PG8_STAGE(bufoff, gbase, voff) do { _Pragma("unroll") for (int _i = 0; _i < 2; ++_i) \
;         __builtin_amdgcn_global_load_lds((const unsigned*)((const char*)(gbase) + (voff)[_i]), (PG8_LAS unsigned*)(lds + (bufoff) + ldsw + _i * 8192), 16, 0, 0); } while (0)
; #define PG8_LDA(dst, b, h) do { _Pragma("unroll") for (int m = 0; m < 4; ++m) _Pragma("unroll") for (int k = 0; k < 2; ++k) dst[m][k] = *(const PG8_LAS bf16x8*)(lds + PG8_SA(b, h) + aoff + m * 2048 + k * 1024); } while (0)
; #define PG8_MMA(ai, bj, At, Bt) do { __builtin_amdgcn_s_setprio(1); _Pragma("unroll") for (int m = 0; m < 4; ++m) _Pragma("unroll") for (int n = 0; n < 2; ++n) _Pragma("unroll") for (int k = 0; k < 2; ++k) \
;         acc[ai][bj][m][n] = __builtin_amdgcn_mfma_f32_16x16x32_bf16(Bt[n][k], At[m][k], acc[ai][bj][m][n], 0, 0, 0); __builtin_amdgcn_s_setprio(0); } while (0)
; #define PG8_WAIT_V(n) asm volatile("s_waitcnt vmcnt(" #n ")" ::: "memory")
; #define PG8_WAIT_L(n) asm volatile("s_waitcnt lgkmcnt(" #n ")" ::: "memory")
; #define PG8_BAR __builtin_amdgcn_s_barrier()
; #define PG8_SCHED __builtin_amdgcn_sched_barrier(0)
; template <class Epi, class Sched, bool ALIGN_EPI = false, bool SP2 = false>
; __device__ __forceinline__ void gemm_phase(PG8_LAS unsigned char* lds, const Gemm g, const Sched& S, const Epi& E, const int wave_s) {
;     ...
;             PG8_LDA(At, 1, 1); PG8_STAGE(PG8_SB(1, 0), b3, voffB); PG8_STAGE(PG8_SB(1, 1), b3 + bhstep, voffB); PG8_STAGE(PG8_SA(1, 0), a3, voffA);
;             PG8_WAIT_V(8); PG8_WAIT_L(0); PG8_BAR; PG8_MMA(1, 0, At, B0); PG8_MMA(1, 1, At, B1); PG8_BAR; PG8_SCHED;
	s_add_i32 s48, s51, s4
	v_lshl_add_u64 v[220:221], v[220:221], 0, s[24:25]
	s_mov_b32 m0, s48
	ds_read_b128 v[164:167], v208 offset:49152
	ds_read_b128 v[182:185], v208 offset:50176
	ds_read_b128 v[186:189], v208 offset:51200
	ds_read_b128 v[190:193], v208 offset:52224
	ds_read_b128 v[194:197], v208 offset:53248
	ds_read_b128 v[198:201], v208 offset:54272
	ds_read_b128 v[212:215], v208 offset:55296
	ds_read_b128 v[216:219], v208 offset:56320
	global_load_lds_dwordx4 v[220:221], off
	s_add_i32 m0, s48, 0x2000
	s_add_u32 s46, s46, 0x40080
	v_lshl_add_u64 v[220:221], v[222:223], 0, s[24:25]
	s_addc_u32 s47, s47, 0
	s_add_i32 s48, s52, s4
	global_load_lds_dwordx4 v[220:221], off
	v_lshl_add_u64 v[220:221], s[46:47], 0, v[170:171]
	s_mov_b32 m0, s48
	s_nop 0
	global_load_lds_dwordx4 v[220:221], off
	v_lshl_add_u64 v[220:221], s[46:47], 0, v[158:159]
	s_add_i32 m0, s48, 0x2000
	s_nop 0
	global_load_lds_dwordx4 v[220:221], off
	v_lshl_add_u64 v[220:221], v[224:225], 0, s[24:25]
	s_mov_b32 m0, s11
	s_nop 0
	global_load_lds_dwordx4 v[220:221], off
	v_lshl_add_u64 v[220:221], v[226:227], 0, s[24:25]
	s_mov_b32 m0, s12
	s_nop 0
	global_load_lds_dwordx4 v[220:221], off
	s_waitcnt vmcnt(8)
	s_waitcnt lgkmcnt(0)
	s_barrier
	s_setprio 1
	s_waitcnt lgkmcnt(0)
	v_mfma_f32_16x16x32_bf16 v[62:65], v[130:133], v[164:167], v[62:65]
	v_mfma_f32_16x16x32_bf16 v[62:65], v[134:137], v[182:185], v[62:65]
	v_mfma_f32_16x16x32_bf16 v[58:61], v[138:141], v[164:167], v[58:61]
	v_mfma_f32_16x16x32_bf16 v[58:61], v[142:145], v[182:185], v[58:61]
	v_mfma_f32_16x16x32_bf16 v[46:49], v[130:133], v[186:189], v[46:49]
	v_mfma_f32_16x16x32_bf16 v[46:49], v[134:137], v[190:193], v[46:49]
	v_mfma_f32_16x16x32_bf16 v[42:45], v[138:141], v[186:189], v[42:45]
	v_mfma_f32_16x16x32_bf16 v[42:45], v[142:145], v[190:193], v[42:45]
	v_mfma_f32_16x16x32_bf16 v[30:33], v[130:133], v[194:197], v[30:33]
	v_mfma_f32_16x16x32_bf16 v[30:33], v[134:137], v[198:201], v[30:33]
	v_mfma_f32_16x16x32_bf16 v[26:29], v[138:141], v[194:197], v[26:29]
	v_mfma_f32_16x16x32_bf16 v[26:29], v[142:145], v[198:201], v[26:29]
	v_mfma_f32_16x16x32_bf16 v[14:17], v[130:133], v[212:215], v[14:17]
	v_mfma_f32_16x16x32_bf16 v[14:17], v[134:137], v[216:219], v[14:17]
	v_mfma_f32_16x16x32_bf16 v[10:13], v[138:141], v[212:215], v[10:13]
	v_mfma_f32_16x16x32_bf16 v[10:13], v[142:145], v[216:219], v[10:13]
	s_setprio 0
	s_setprio 1
	v_mfma_f32_16x16x32_bf16 v[54:57], v[146:149], v[164:167], v[54:57]
	v_mfma_f32_16x16x32_bf16 v[54:57], v[150:153], v[182:185], v[54:57]
	v_mfma_f32_16x16x32_bf16 v[50:53], v[154:157], v[164:167], v[50:53]
	v_mfma_f32_16x16x32_bf16 v[50:53], v[160:163], v[182:185], v[50:53]
	v_mfma_f32_16x16x32_bf16 v[38:41], v[146:149], v[186:189], v[38:41]
	v_mfma_f32_16x16x32_bf16 v[38:41], v[150:153], v[190:193], v[38:41]
	v_mfma_f32_16x16x32_bf16 v[34:37], v[154:157], v[186:189], v[34:37]
	v_mfma_f32_16x16x32_bf16 v[34:37], v[160:163], v[190:193], v[34:37]
	v_mfma_f32_16x16x32_bf16 v[22:25], v[146:149], v[194:197], v[22:25]
	v_mfma_f32_16x16x32_bf16 v[22:25], v[150:153], v[198:201], v[22:25]
	v_mfma_f32_16x16x32_bf16 v[18:21], v[154:157], v[194:197], v[18:21]
	v_mfma_f32_16x16x32_bf16 v[18:21], v[160:163], v[198:201], v[18:21]
	v_mfma_f32_16x16x32_bf16 v[6:9], v[146:149], v[212:215], v[6:9]
	v_mfma_f32_16x16x32_bf16 v[6:9], v[150:153], v[216:219], v[6:9]
	v_mfma_f32_16x16x32_bf16 v[2:5], v[154:157], v[212:215], v[2:5]
	v_mfma_f32_16x16x32_bf16 v[2:5], v[160:163], v[216:219], v[2:5]
	s_setprio 0
	s_barrier
	s_add_i32 s50, s50, 2
	s_add_u32 s42, s42, 0x100
	s_addc_u32 s43, s43, 0
	s_add_u32 s29, s29, 0x100
	s_addc_u32 s45, s45, 0
	s_cmp_gt_u32 s50, 61
	s_cbranch_scc0 .LBB0_923
; #define PG8_LAS __attribute__((address_space(3)))
;     __device__ __forceinline__ void operator()(const f32x4 (&acc)[2][2][4][2], const Unit& u, int wr, int wc, int fr, int fq, PG8_LAS unsigned char* stg) const {
;         const int lane = fq * 16 + fr;
;         const size_t colw = (size_t)u.pn * BM + wc * 64;
;         const int rowb = u.pm * BM + wr * 64;
;         PG8_LAS unsigned char* st = stg + fr * 144 + fq * 16;
; #pragma unroll
;         for (int ai = 0; ai < 2; ++ai) {
;         asm volatile("" ::: "memory");
;         u32x4 xin[4][2];
; #pragma unroll
;         for (int m = 0; m < 4; ++m)
; #pragma unroll
;             for (int i = 0; i < 2; ++i) { const int c = lane + 64 * i; xin[m][i] = *(const u32x4*)(xb + (size_t)(rowb + ai * HALF + m * 16 + (c >> 3)) * 1024 + colw + (c & 7) * 8); }
; #pragma unroll
;         for (int m = 0; m < 4; ++m) {
;             const int row = rowb + ai * HALF + m * 16 + fr;
; #pragma unroll
;             for (int i = 0; i < 2; ++i) { const int c = lane + 64 * i; *(PG8_LAS u32x4*)(stg + (c >> 3) * 144 + (c & 7) * 16) = xin[m][i]; }
;             float ss = 0.f;
; #pragma unroll
;             for (int bj = 0; bj < 2; ++bj) {
;                 const u32x4 xo = *(const PG8_LAS u32x4*)(st + bj * 64);
;                 float v[8];
; #pragma unroll
;                 for (int i = 0; i < 4; ++i) { v[2 * i] = __uint_as_float(xo[i] << 16) + acc[ai][bj][m][i >> 1][(2 * i) & 3]; v[2 * i + 1] = __uint_as_float(xo[i] & 0xffff0000u) + acc[ai][bj][m][i >> 1][(2 * i + 1) & 3]; }
;                 u32x4 w; w.x = cvt_pk_bf16(v[0], v[1]); w.y = cvt_pk_bf16(v[2], v[3]); w.z = cvt_pk_bf16(v[4], v[5]); w.w = cvt_pk_bf16(v[6], v[7]);
;                 *(PG8_LAS u32x4*)(st + bj * 64) = w;
;                 ss += ((v[0] * v[0] + v[1] * v[1]) + (v[2] * v[2] + v[3] * v[3])) + ((v[4] * v[4] + v[5] * v[5]) + (v[6] * v[6] + v[7] * v[7]));
;             }
; #pragma unroll
;             for (int i = 0; i < 2; ++i) { const int c = lane + 64 * i; const u32x4 w = *(const PG8_LAS u32x4*)(stg + (c >> 3) * 144 + (c & 7) * 16);
;                 *(u32x4*)(xo_ + (size_t)(row - fr + (c >> 3)) * 1024 + colw + (c & 7) * 8) = w; }
;             ss = sum_x16(ss); ss = sum_x32(ss);
;             if (fq == 0) po_[(size_t)(u.pn * 4 + wc) * 65536 + row] = ss;
.LBB0_926:
	s_ashr_i32 s45, s44, 31
	s_lshl_b32 s14, s14, 8
	s_lshl_b64 s[16:17], s[44:45], 8
	s_add_i32 s42, s14, s10
	s_or_b64 s[16:17], s[16:17], s[74:75]
	v_or_b32_e32 v130, s42, v206
	s_lshl_b64 s[46:47], s[16:17], 1
	v_ashrrev_i32_e32 v131, 31, v130
	v_lshl_add_u64 v[182:183], v[176:177], 0, s[46:47]
	v_lshlrev_b64 v[198:199], 11, v[130:131]
	v_lshl_add_u64 v[130:131], v[182:183], 0, v[198:199]
	global_load_dwordx4 v[154:157], v[130:131], off
	v_or_b32_e32 v130, s42, v207
	v_ashrrev_i32_e32 v131, 31, v130
	v_lshlrev_b64 v[196:197], 11, v[130:131]
	v_lshl_add_u64 v[130:131], v[182:183], 0, v[196:197]
	global_load_dwordx4 v[160:163], v[130:131], off
	s_lshl_b32 s14, s44, 2
	s_or_b32 s14, s14, s9
	s_ashr_i32 s15, s14, 31
	s_lshl_b64 s[44:45], s[14:15], 18
	s_or_b32 s14, s42, 16
	v_or_b32_e32 v130, s14, v206
	v_ashrrev_i32_e32 v131, 31, v130
	v_lshlrev_b64 v[194:195], 11, v[130:131]
	v_lshl_add_u64 v[130:131], v[182:183], 0, v[194:195]
	global_load_dwordx4 v[146:149], v[130:131], off
	v_or_b32_e32 v130, s14, v207
	v_ashrrev_i32_e32 v131, 31, v130
	v_lshlrev_b64 v[192:193], 11, v[130:131]
	v_lshl_add_u64 v[130:131], v[182:183], 0, v[192:193]
	s_or_b32 s14, s42, 32
	global_load_dwordx4 v[150:153], v[130:131], off
	v_or_b32_e32 v130, s14, v206
	v_ashrrev_i32_e32 v131, 31, v130
	v_lshlrev_b64 v[188:189], 11, v[130:131]
	v_lshl_add_u64 v[130:131], v[182:183], 0, v[188:189]
	global_load_dwordx4 v[134:137], v[130:131], off
	v_or_b32_e32 v130, s14, v207
	v_ashrrev_i32_e32 v131, 31, v130
	v_lshlrev_b64 v[186:187], 11, v[130:131]
	v_lshl_add_u64 v[130:131], v[182:183], 0, v[186:187]
	s_or_b32 s14, s42, 48
	global_load_dwordx4 v[138:141], v[130:131], off
	v_or_b32_e32 v130, s14, v206
	v_or_b32_e32 v142, s14, v207
	v_ashrrev_i32_e32 v131, 31, v130
	v_ashrrev_i32_e32 v143, 31, v142
	v_lshlrev_b64 v[184:185], 11, v[130:131]
	v_lshlrev_b64 v[190:191], 11, v[142:143]
	v_lshl_add_u64 v[130:131], v[182:183], 0, v[184:185]
	v_lshl_add_u64 v[142:143], v[182:183], 0, v[190:191]
	global_load_dwordx4 v[130:133], v[130:131], off
	s_nop 0
	global_load_dwordx4 v[142:145], v[142:143], off
	s_and_b64 vcc, exec, s[20:21]
	s_cbranch_vccz .Lalign_down
	s_barrier
.Lalign_down:
	s_waitcnt vmcnt(0)
	ds_write_b128 v209, v[154:157]
	ds_write_b128 v209, v[160:163] offset:1152
	ds_read_b128 v[154:157], v210
	s_waitcnt lgkmcnt(0)
	v_lshlrev_b32_e32 v160, 16, v154
	v_and_b32_e32 v154, 0xffff0000, v154
	v_add_f32_e32 v127, v127, v154
	v_lshlrev_b32_e32 v154, 16, v155
	v_add_f32_e32 v128, v128, v154
	v_and_b32_e32 v154, 0xffff0000, v155
	v_add_f32_e32 v129, v129, v154
	v_lshlrev_b32_e32 v154, 16, v156
	v_add_f32_e32 v154, v122, v154
	v_and_b32_e32 v122, 0xffff0000, v156
	v_add_f32_e32 v155, v123, v122
	v_lshlrev_b32_e32 v122, 16, v157
	v_add_f32_e32 v156, v124, v122
	v_and_b32_e32 v122, 0xffff0000, v157
	v_add_f32_e32 v126, v126, v160
	v_add_f32_e32 v157, v125, v122
	v_cvt_pk_bf16_f32 v122, v126, v127
	v_cvt_pk_bf16_f32 v123, v128, v129
	v_cvt_pk_bf16_f32 v124, v154, v155
	v_cvt_pk_bf16_f32 v125, v156, v157
	ds_write_b128 v210, v[122:125]
	v_mul_f32_e32 v122, v127, v127
	v_mul_f32_e32 v123, v129, v129
	v_fmac_f32_e32 v122, v126, v126
	v_fmac_f32_e32 v123, v128, v128
	v_add_f32_e32 v122, v122, v123
	v_mul_f32_e32 v123, v155, v155
	v_mul_f32_e32 v124, v157, v157
	v_fmac_f32_e32 v123, v154, v154
	v_fmac_f32_e32 v124, v156, v156
	v_add_f32_e32 v123, v123, v124
	v_add_f32_e32 v126, v122, v123
	ds_read_b128 v[122:125], v210 offset:64
	s_waitcnt lgkmcnt(0)
	v_lshlrev_b32_e32 v127, 16, v122
	v_and_b32_e32 v122, 0xffff0000, v122
	v_add_f32_e32 v119, v119, v122
	v_lshlrev_b32_e32 v122, 16, v123
	v_add_f32_e32 v120, v120, v122
	v_and_b32_e32 v122, 0xffff0000, v123
	v_add_f32_e32 v121, v121, v122
	v_lshlrev_b32_e32 v122, 16, v124
	v_add_f32_e32 v122, v114, v122
	v_and_b32_e32 v114, 0xffff0000, v124
	v_add_f32_e32 v123, v115, v114
	v_lshlrev_b32_e32 v114, 16, v125
	v_add_f32_e32 v124, v116, v114
	v_and_b32_e32 v114, 0xffff0000, v125
	v_add_f32_e32 v118, v118, v127
	v_add_f32_e32 v125, v117, v114
	v_cvt_pk_bf16_f32 v114, v118, v119
	v_cvt_pk_bf16_f32 v115, v120, v121
	v_cvt_pk_bf16_f32 v116, v122, v123
	v_cvt_pk_bf16_f32 v117, v124, v125
	ds_write_b128 v210, v[114:117] offset:64
	v_mul_f32_e32 v114, v119, v119
	v_mul_f32_e32 v115, v121, v121
	v_fmac_f32_e32 v114, v118, v118
	v_fmac_f32_e32 v115, v120, v120
	v_add_f32_e32 v114, v114, v115
	v_mul_f32_e32 v115, v123, v123
	v_mul_f32_e32 v116, v125, v125
	v_fmac_f32_e32 v115, v122, v122
	v_fmac_f32_e32 v116, v124, v124
	v_add_f32_e32 v115, v115, v116
	v_add_f32_e32 v114, v114, v115
	v_add_f32_e32 v120, v126, v114
	ds_read_b128 v[114:117], v211
	v_lshl_add_u64 v[118:119], s[76:77], 0, v[198:199]
	v_lshl_add_u64 v[118:119], v[118:119], 0, s[46:47]
	v_lshl_add_u64 v[118:119], v[118:119], 0, v[0:1]
	s_waitcnt lgkmcnt(0)
	global_store_dwordx4 v[118:119], v[114:117], off nt
	ds_read_b128 v[114:117], v211 offset:1152
	v_lshl_add_u64 v[118:119], s[76:77], 0, v[196:197]
	v_lshl_add_u64 v[118:119], v[118:119], 0, s[46:47]
	v_lshl_add_u64 v[118:119], v[118:119], 0, v[0:1]
	s_waitcnt lgkmcnt(0)
	global_store_dwordx4 v[118:119], v[114:117], off nt
	s_nop 1
	v_mov_b32_e32 v114, v120
	s_nop 1
	v_permlane16_swap_b32_e32 v120, v114
	v_add_f32_e32 v114, v120, v114
	v_mov_b32_e32 v115, v114
	s_nop 1
	v_permlane32_swap_b32_e32 v114, v115
	s_and_saveexec_b64 s[48:49], s[34:35]
	s_cbranch_execz .LBB0_928
	s_add_u32 s14, s82, s44
	v_or_b32_e32 v116, s42, v174
	s_addc_u32 s15, s83, s45
	v_ashrrev_i32_e32 v117, 31, v116
	v_lshl_add_u64 v[116:117], v[116:117], 2, s[14:15]
	v_add_f32_e32 v114, v114, v115
	global_store_dword v[116:117], v114, off
